# v26: v15 (original per-segment s_setprio flips kept) + K-loop LDS-DMA scalar-base conversion + merged waits (lever 4 A/B against the static raise of v23)
# baseline (speedup 1.0000x reference)
; #define PG8_STAGE(bufoff, gbase, voff) do { _Pragma("unroll") for (int _i = 0; _i < 2; ++_i) \
;         __builtin_amdgcn_global_load_lds((const unsigned*)((const char*)(gbase) + (voff)[_i]), (PG8_LAS unsigned*)(lds + (bufoff) + ldsw + _i * 8192), 16, 0, 0); } while (0)
; #define PG8_LDA(dst, b, h) do { _Pragma("unroll") for (int m = 0; m < 4; ++m) _Pragma("unroll") for (int k = 0; k < 2; ++k) dst[m][k] = *(const PG8_LAS bf16x8*)(lds + PG8_SA(b, h) + aoff + m * 2048 + k * 1024); } while (0)
; #define PG8_LDB(dst, b, h) do { _Pragma("unroll") for (int n = 0; n < 2; ++n) _Pragma("unroll") for (int k = 0; k < 2; ++k) dst[n][k] = *(const PG8_LAS bf16x8*)(lds + PG8_SB(b, h) + boff + n * 2048 + k * 1024); } while (0)
; #define PG8_MMA(ai, bj, At, Bt) do { __builtin_amdgcn_s_setprio(1); _Pragma("unroll") for (int m = 0; m < 4; ++m) _Pragma("unroll") for (int n = 0; n < 2; ++n) _Pragma("unroll") for (int k = 0; k < 2; ++k) \
;         acc[ai][bj][m][n] = mma_<I8>(Bt[n][k], At[m][k], acc[ai][bj][m][n]); __builtin_amdgcn_s_setprio(0); } while (0)
; #define PG8_WAIT_V(n) asm volatile("s_waitcnt vmcnt(" #n ")" ::: "memory")
; #define PG8_WAIT_L(n) asm volatile("s_waitcnt lgkmcnt(" #n ")" ::: "memory")
; #define PG8_BAR __builtin_amdgcn_s_barrier()
; #define PG8_SCHED __builtin_amdgcn_sched_barrier(0)
; template <class Epi, class Sched, bool ALIGN_EPI = false, bool SP2 = false, bool I8 = false>
; __device__ __forceinline__ void gemm_phase(PG8_LAS unsigned char* lds, const Gemm g, const Sched& S, const Epi& E) {
;     ...
;             PG8_LDB(B0, 0, 0); PG8_LDB(B1, 0, 1); PG8_SCHED; PG8_LDA(At, 0, 0); PG8_STAGE(PG8_SA(1, 1), a1 + hstepA, voffA);
;             PG8_WAIT_V(8); PG8_WAIT_L(0); PG8_BAR; PG8_MMA(0, 0, At, B0); PG8_MMA(0, 1, At, B1); PG8_BAR; PG8_SCHED;
;             PG8_LDA(At, 0, 1); PG8_STAGE(PG8_SB(0, 0), b2, voffB); PG8_STAGE(PG8_SB(0, 1), b2 + hstepB, voffB); PG8_STAGE(PG8_SA(0, 0), a2, voffA);
;             PG8_WAIT_V(8); PG8_WAIT_L(0); PG8_BAR; PG8_MMA(1, 0, At, B0); PG8_MMA(1, 1, At, B1); PG8_BAR; PG8_SCHED;
.LBB0_483:
	ds_read_b128 v[58:61], v187
	ds_read_b128 v[62:65], v187 offset:1024
	ds_read_b128 v[74:77], v187 offset:2048
	ds_read_b128 v[78:81], v187 offset:3072
	ds_read_b128 v[162:165], v188
	ds_read_b128 v[166:169], v188 offset:1024
	ds_read_b128 v[170:173], v188 offset:2048
	ds_read_b128 v[190:193], v188 offset:3072
	s_add_u32 s34, s2, 0xfff80080
	s_addc_u32 s35, s3, -1
	s_cmp_eq_u32 s40, 28
	s_cselect_b32 s37, s7, s35
	s_cselect_b32 s36, s25, s34
	s_cselect_b32 s35, s23, s39
	s_cselect_b32 s34, s33, s38
	s_add_i32 m0, s31, 0xc000
	ds_read_b128 v[194:197], v189
	ds_read_b128 v[198:201], v189 offset:1024
	ds_read_b128 v[202:205], v189 offset:2048
	ds_read_b128 v[206:209], v189 offset:3072
	ds_read_b128 v[210:213], v189 offset:4096
	ds_read_b128 v[214:217], v189 offset:5120
	ds_read_b128 v[218:221], v189 offset:6144
	ds_read_b128 v[222:225], v189 offset:7168
	global_load_lds_dwordx4 v154, s[2:3]
	s_add_i32 m0, s31, 0xe000
	s_nop 0
	global_load_lds_dwordx4 v156, s[2:3]
	s_waitcnt vmcnt(8) lgkmcnt(0)
	s_barrier
	s_setprio 1
	s_waitcnt lgkmcnt(0)
	v_mfma_i32_16x16x64_i8 v[142:145], v[58:61], v[194:197], v[142:145]
	v_mfma_i32_16x16x64_i8 v[138:141], v[74:77], v[194:197], v[138:141]
	v_mfma_i32_16x16x64_i8 v[126:129], v[58:61], v[202:205], v[126:129]
	v_mfma_i32_16x16x64_i8 v[122:125], v[74:77], v[202:205], v[122:125]
	v_mfma_i32_16x16x64_i8 v[110:113], v[58:61], v[210:213], v[110:113]
	v_mfma_i32_16x16x64_i8 v[106:109], v[74:77], v[210:213], v[106:109]
	v_mfma_i32_16x16x64_i8 v[94:97], v[58:61], v[218:221], v[94:97]
	v_mfma_i32_16x16x64_i8 v[90:93], v[74:77], v[218:221], v[90:93]
	v_mfma_i32_16x16x64_i8 v[142:145], v[62:65], v[198:201], v[142:145]
	v_mfma_i32_16x16x64_i8 v[138:141], v[78:81], v[198:201], v[138:141]
	v_mfma_i32_16x16x64_i8 v[126:129], v[62:65], v[206:209], v[126:129]
	v_mfma_i32_16x16x64_i8 v[122:125], v[78:81], v[206:209], v[122:125]
	v_mfma_i32_16x16x64_i8 v[110:113], v[62:65], v[214:217], v[110:113]
	v_mfma_i32_16x16x64_i8 v[106:109], v[78:81], v[214:217], v[106:109]
	v_mfma_i32_16x16x64_i8 v[94:97], v[62:65], v[222:225], v[94:97]
	v_mfma_i32_16x16x64_i8 v[90:93], v[78:81], v[222:225], v[90:93]
	s_setprio 0
	s_setprio 1
	v_mfma_i32_16x16x64_i8 v[134:137], v[162:165], v[194:197], v[134:137]
	v_mfma_i32_16x16x64_i8 v[130:133], v[170:173], v[194:197], v[130:133]
	v_mfma_i32_16x16x64_i8 v[118:121], v[162:165], v[202:205], v[118:121]
	v_mfma_i32_16x16x64_i8 v[114:117], v[170:173], v[202:205], v[114:117]
	v_mfma_i32_16x16x64_i8 v[102:105], v[162:165], v[210:213], v[102:105]
	v_mfma_i32_16x16x64_i8 v[98:101], v[170:173], v[210:213], v[98:101]
	v_mfma_i32_16x16x64_i8 v[86:89], v[162:165], v[218:221], v[86:89]
	v_mfma_i32_16x16x64_i8 v[82:85], v[170:173], v[218:221], v[82:85]
	v_mfma_i32_16x16x64_i8 v[134:137], v[166:169], v[198:201], v[134:137]
	v_mfma_i32_16x16x64_i8 v[130:133], v[190:193], v[198:201], v[130:133]
	v_mfma_i32_16x16x64_i8 v[118:121], v[166:169], v[206:209], v[118:121]
	v_mfma_i32_16x16x64_i8 v[114:117], v[190:193], v[206:209], v[114:117]
	v_mfma_i32_16x16x64_i8 v[102:105], v[166:169], v[214:217], v[102:105]
	v_mfma_i32_16x16x64_i8 v[98:101], v[190:193], v[214:217], v[98:101]
	v_mfma_i32_16x16x64_i8 v[86:89], v[166:169], v[222:225], v[86:89]
	v_mfma_i32_16x16x64_i8 v[82:85], v[190:193], v[222:225], v[82:85]
	s_setprio 0
	s_barrier
	s_add_i32 s41, s8, s68
	s_mov_b64 s[98:99], s[34:35]
	s_mov_b32 m0, s41
	ds_read_b128 v[194:197], v189 offset:16384
	ds_read_b128 v[198:201], v189 offset:17408
	ds_read_b128 v[202:205], v189 offset:18432
	ds_read_b128 v[206:209], v189 offset:19456
	ds_read_b128 v[210:213], v189 offset:20480
	ds_read_b128 v[214:217], v189 offset:21504
	ds_read_b128 v[218:221], v189 offset:22528
	ds_read_b128 v[222:225], v189 offset:23552
	global_load_lds_dwordx4 v148, s[34:35]
	s_add_i32 m0, s41, 0x2000
	s_add_u32 vcc_lo, s34, 0x80000
	s_mov_b64 s[98:99], s[34:35]
	s_addc_u32 vcc_hi, s35, 0
	s_add_i32 s41, s9, s68
	global_load_lds_dwordx4 v152, s[34:35]
	s_mov_b32 m0, s41
	s_mov_b64 s[100:101], s[36:37]
	global_load_lds_dwordx4 v148, vcc
	s_add_i32 m0, s41, 0x2000
	s_nop 0
	global_load_lds_dwordx4 v152, vcc
	s_mov_b64 s[100:101], s[36:37]
	s_mov_b32 m0, s31
	s_nop 0
	global_load_lds_dwordx4 v146, s[36:37]
	s_mov_b32 m0, s69
	s_nop 0
	global_load_lds_dwordx4 v150, s[36:37]
	s_waitcnt vmcnt(8) lgkmcnt(0)
	s_barrier
	s_setprio 1
	s_waitcnt lgkmcnt(0)
	v_mfma_i32_16x16x64_i8 v[70:73], v[58:61], v[194:197], v[70:73]
	v_mfma_i32_16x16x64_i8 v[66:69], v[74:77], v[194:197], v[66:69]
	v_mfma_i32_16x16x64_i8 v[46:49], v[58:61], v[202:205], v[46:49]
	v_mfma_i32_16x16x64_i8 v[42:45], v[74:77], v[202:205], v[42:45]
	v_mfma_i32_16x16x64_i8 v[30:33], v[58:61], v[210:213], v[30:33]
	v_mfma_i32_16x16x64_i8 v[26:29], v[74:77], v[210:213], v[26:29]
	v_mfma_i32_16x16x64_i8 v[14:17], v[58:61], v[218:221], v[14:17]
	v_mfma_i32_16x16x64_i8 v[10:13], v[74:77], v[218:221], v[10:13]
	v_mfma_i32_16x16x64_i8 v[70:73], v[62:65], v[198:201], v[70:73]
	v_mfma_i32_16x16x64_i8 v[66:69], v[78:81], v[198:201], v[66:69]
	v_mfma_i32_16x16x64_i8 v[46:49], v[62:65], v[206:209], v[46:49]
	v_mfma_i32_16x16x64_i8 v[42:45], v[78:81], v[206:209], v[42:45]
	v_mfma_i32_16x16x64_i8 v[30:33], v[62:65], v[214:217], v[30:33]
	v_mfma_i32_16x16x64_i8 v[26:29], v[78:81], v[214:217], v[26:29]
	v_mfma_i32_16x16x64_i8 v[14:17], v[62:65], v[222:225], v[14:17]
	v_mfma_i32_16x16x64_i8 v[10:13], v[78:81], v[222:225], v[10:13]
	s_setprio 0
	s_setprio 1
	v_mfma_i32_16x16x64_i8 v[54:57], v[162:165], v[194:197], v[54:57]
	v_mfma_i32_16x16x64_i8 v[50:53], v[170:173], v[194:197], v[50:53]
	v_mfma_i32_16x16x64_i8 v[38:41], v[162:165], v[202:205], v[38:41]
	v_mfma_i32_16x16x64_i8 v[34:37], v[170:173], v[202:205], v[34:37]
	v_mfma_i32_16x16x64_i8 v[22:25], v[162:165], v[210:213], v[22:25]
	v_mfma_i32_16x16x64_i8 v[18:21], v[170:173], v[210:213], v[18:21]
	v_mfma_i32_16x16x64_i8 v[6:9], v[162:165], v[218:221], v[6:9]
	v_mfma_i32_16x16x64_i8 v[2:5], v[170:173], v[218:221], v[2:5]
	v_mfma_i32_16x16x64_i8 v[54:57], v[166:169], v[198:201], v[54:57]
	v_mfma_i32_16x16x64_i8 v[50:53], v[190:193], v[198:201], v[50:53]
	v_mfma_i32_16x16x64_i8 v[38:41], v[166:169], v[206:209], v[38:41]
	v_mfma_i32_16x16x64_i8 v[34:37], v[190:193], v[206:209], v[34:37]
	v_mfma_i32_16x16x64_i8 v[22:25], v[166:169], v[214:217], v[22:25]
	v_mfma_i32_16x16x64_i8 v[18:21], v[190:193], v[214:217], v[18:21]
	v_mfma_i32_16x16x64_i8 v[6:9], v[166:169], v[222:225], v[6:9]
	v_mfma_i32_16x16x64_i8 v[2:5], v[190:193], v[222:225], v[2:5]
	s_setprio 0
	s_barrier
; #define PG8_STAGE(bufoff, gbase, voff) do { _Pragma("unroll") for (int _i = 0; _i < 2; ++_i) \
;         __builtin_amdgcn_global_load_lds((const unsigned*)((const char*)(gbase) + (voff)[_i]), (PG8_LAS unsigned*)(lds + (bufoff) + ldsw + _i * 8192), 16, 0, 0); } while (0)
; #define PG8_LDA(dst, b, h) do { _Pragma("unroll") for (int m = 0; m < 4; ++m) _Pragma("unroll") for (int k = 0; k < 2; ++k) dst[m][k] = *(const PG8_LAS bf16x8*)(lds + PG8_SA(b, h) + aoff + m * 2048 + k * 1024); } while (0)
; #define PG8_LDB(dst, b, h) do { _Pragma("unroll") for (int n = 0; n < 2; ++n) _Pragma("unroll") for (int k = 0; k < 2; ++k) dst[n][k] = *(const PG8_LAS bf16x8*)(lds + PG8_SB(b, h) + boff + n * 2048 + k * 1024); } while (0)
; #define PG8_MMA(ai, bj, At, Bt) do { __builtin_amdgcn_s_setprio(1); _Pragma("unroll") for (int m = 0; m < 4; ++m) _Pragma("unroll") for (int n = 0; n < 2; ++n) _Pragma("unroll") for (int k = 0; k < 2; ++k) \
;         acc[ai][bj][m][n] = mma_<I8>(Bt[n][k], At[m][k], acc[ai][bj][m][n]); __builtin_amdgcn_s_setprio(0); } while (0)
; #define PG8_WAIT_V(n) asm volatile("s_waitcnt vmcnt(" #n ")" ::: "memory")
; #define PG8_WAIT_L(n) asm volatile("s_waitcnt lgkmcnt(" #n ")" ::: "memory")
; #define PG8_BAR __builtin_amdgcn_s_barrier()
; #define PG8_SCHED __builtin_amdgcn_sched_barrier(0)
; template <class Epi, class Sched, bool ALIGN_EPI = false, bool SP2 = false, bool I8 = false>
; __device__ __forceinline__ void gemm_phase(PG8_LAS unsigned char* lds, const Gemm g, const Sched& S, const Epi& E) {
;     ...
;         for (int t = 0; t < nt; t += 2) {
;             const bool last = (t == nt - 2);
;             const char* a1 = cA + (size_t)(t + 1) * kstep;
;             const char* a2 = last ? nA : cA + (size_t)(t + 2) * kstep; const char* b2 = last ? nB : cB + (size_t)(t + 2) * kstep;
;             const char* a3 = a2 + kstep; const char* b3 = b2 + kstep;
;     ...
;             PG8_LDB(B0, 1, 0); PG8_LDB(B1, 1, 1); PG8_SCHED; PG8_LDA(At, 1, 0); PG8_STAGE(PG8_SA(0, 1), a2 + hstepA, voffA);
;             PG8_WAIT_V(8); PG8_WAIT_L(0); PG8_BAR; PG8_MMA(0, 0, At, B0); PG8_MMA(0, 1, At, B1); PG8_BAR; PG8_SCHED;
;             PG8_LDA(At, 1, 1); PG8_STAGE(PG8_SB(1, 0), b3, voffB); PG8_STAGE(PG8_SB(1, 1), b3 + hstepB, voffB); PG8_STAGE(PG8_SA(1, 0), a3, voffA);
;             PG8_WAIT_V(8); PG8_WAIT_L(0); PG8_BAR; PG8_MMA(1, 0, At, B0); PG8_MMA(1, 1, At, B1); PG8_BAR; PG8_SCHED;
	s_add_i32 s41, 0, 0x18000
	s_add_i32 s95, 0, 0x1c000
	v_add_u32_e32 v78, s41, v181
	v_add_u32_e32 v190, s95, v181
	ds_read_b128 v[58:61], v78
	ds_read_b128 v[62:65], v78 offset:1024
	ds_read_b128 v[74:77], v78 offset:2048
	ds_read_b128 v[78:81], v78 offset:3072
	ds_read_b128 v[162:165], v190
	ds_read_b128 v[166:169], v190 offset:1024
	ds_read_b128 v[170:173], v190 offset:2048
	ds_read_b128 v[190:193], v190 offset:3072
	s_add_u32 s36, s36, 0x80000
	s_addc_u32 s37, s37, 0
	s_mov_b32 m0, s70
	ds_read_b128 v[194:197], v189 offset:32768
	ds_read_b128 v[198:201], v189 offset:33792
	ds_read_b128 v[202:205], v189 offset:34816
	ds_read_b128 v[206:209], v189 offset:35840
	ds_read_b128 v[210:213], v189 offset:36864
	ds_read_b128 v[214:217], v189 offset:37888
	ds_read_b128 v[218:221], v189 offset:38912
	ds_read_b128 v[222:225], v189 offset:39936
	global_load_lds_dwordx4 v146, s[36:37]
	s_mov_b32 m0, s71
	s_nop 0
	global_load_lds_dwordx4 v150, s[36:37]
	s_waitcnt vmcnt(8) lgkmcnt(0)
	s_barrier
	s_setprio 1
	s_waitcnt lgkmcnt(0)
	v_mfma_i32_16x16x64_i8 v[142:145], v[58:61], v[194:197], v[142:145]
	v_mfma_i32_16x16x64_i8 v[138:141], v[74:77], v[194:197], v[138:141]
	v_mfma_i32_16x16x64_i8 v[126:129], v[58:61], v[202:205], v[126:129]
	v_mfma_i32_16x16x64_i8 v[122:125], v[74:77], v[202:205], v[122:125]
	v_mfma_i32_16x16x64_i8 v[110:113], v[58:61], v[210:213], v[110:113]
	v_mfma_i32_16x16x64_i8 v[106:109], v[74:77], v[210:213], v[106:109]
	v_mfma_i32_16x16x64_i8 v[94:97], v[58:61], v[218:221], v[94:97]
	v_mfma_i32_16x16x64_i8 v[90:93], v[74:77], v[218:221], v[90:93]
	v_mfma_i32_16x16x64_i8 v[142:145], v[62:65], v[198:201], v[142:145]
	v_mfma_i32_16x16x64_i8 v[138:141], v[78:81], v[198:201], v[138:141]
	v_mfma_i32_16x16x64_i8 v[126:129], v[62:65], v[206:209], v[126:129]
	v_mfma_i32_16x16x64_i8 v[122:125], v[78:81], v[206:209], v[122:125]
	v_mfma_i32_16x16x64_i8 v[110:113], v[62:65], v[214:217], v[110:113]
	v_mfma_i32_16x16x64_i8 v[106:109], v[78:81], v[214:217], v[106:109]
	v_mfma_i32_16x16x64_i8 v[94:97], v[62:65], v[222:225], v[94:97]
	v_mfma_i32_16x16x64_i8 v[90:93], v[78:81], v[222:225], v[90:93]
	s_setprio 0
	s_setprio 1
	v_mfma_i32_16x16x64_i8 v[134:137], v[162:165], v[194:197], v[134:137]
	v_mfma_i32_16x16x64_i8 v[130:133], v[170:173], v[194:197], v[130:133]
	v_mfma_i32_16x16x64_i8 v[118:121], v[162:165], v[202:205], v[118:121]
	v_mfma_i32_16x16x64_i8 v[114:117], v[170:173], v[202:205], v[114:117]
	v_mfma_i32_16x16x64_i8 v[102:105], v[162:165], v[210:213], v[102:105]
	v_mfma_i32_16x16x64_i8 v[98:101], v[170:173], v[210:213], v[98:101]
	v_mfma_i32_16x16x64_i8 v[86:89], v[162:165], v[218:221], v[86:89]
	v_mfma_i32_16x16x64_i8 v[82:85], v[170:173], v[218:221], v[82:85]
	v_mfma_i32_16x16x64_i8 v[134:137], v[166:169], v[198:201], v[134:137]
	v_mfma_i32_16x16x64_i8 v[130:133], v[190:193], v[198:201], v[130:133]
	v_mfma_i32_16x16x64_i8 v[118:121], v[166:169], v[206:209], v[118:121]
	v_mfma_i32_16x16x64_i8 v[114:117], v[190:193], v[206:209], v[114:117]
	v_mfma_i32_16x16x64_i8 v[102:105], v[166:169], v[214:217], v[102:105]
	v_mfma_i32_16x16x64_i8 v[98:101], v[190:193], v[214:217], v[98:101]
	v_mfma_i32_16x16x64_i8 v[86:89], v[166:169], v[222:225], v[86:89]
	v_mfma_i32_16x16x64_i8 v[82:85], v[190:193], v[222:225], v[82:85]
	s_setprio 0
	s_barrier
	s_add_i32 s36, s41, s68
	s_add_i32 m0, s36, 0xffffff80
	ds_read_b128 v[194:197], v189 offset:49152
	ds_read_b128 v[198:201], v189 offset:50176
	ds_read_b128 v[202:205], v189 offset:51200
	ds_read_b128 v[206:209], v189 offset:52224
	ds_read_b128 v[210:213], v189 offset:53248
	ds_read_b128 v[214:217], v189 offset:54272
	ds_read_b128 v[218:221], v189 offset:55296
	ds_read_b128 v[222:225], v189 offset:56320
	global_load_lds_dwordx4 v148, s[98:99] offset:128
	s_add_i32 m0, s36, 0x1f80
	s_add_u32 s34, s34, 0x80080
	s_addc_u32 s35, s35, 0
	s_add_i32 s36, s95, s68
	global_load_lds_dwordx4 v152, s[98:99] offset:128
	s_mov_b32 m0, s36
	s_nop 0
	global_load_lds_dwordx4 v148, s[34:35]
	s_add_i32 m0, s36, 0x2000
	s_nop 0
	global_load_lds_dwordx4 v152, s[34:35]
	s_add_i32 m0, s89, 0xffffff80
	s_nop 0
	global_load_lds_dwordx4 v146, s[100:101] offset:128
	s_add_i32 m0, s92, 0xffffff80
	s_nop 0
	global_load_lds_dwordx4 v150, s[100:101] offset:128
	s_waitcnt vmcnt(8) lgkmcnt(0)
	s_barrier
	s_setprio 1
	s_waitcnt lgkmcnt(0)
	v_mfma_i32_16x16x64_i8 v[70:73], v[58:61], v[194:197], v[70:73]
	v_mfma_i32_16x16x64_i8 v[66:69], v[74:77], v[194:197], v[66:69]
	v_mfma_i32_16x16x64_i8 v[46:49], v[58:61], v[202:205], v[46:49]
	v_mfma_i32_16x16x64_i8 v[42:45], v[74:77], v[202:205], v[42:45]
	v_mfma_i32_16x16x64_i8 v[30:33], v[58:61], v[210:213], v[30:33]
	v_mfma_i32_16x16x64_i8 v[26:29], v[74:77], v[210:213], v[26:29]
	v_mfma_i32_16x16x64_i8 v[14:17], v[58:61], v[218:221], v[14:17]
	v_mfma_i32_16x16x64_i8 v[10:13], v[74:77], v[218:221], v[10:13]
	v_mfma_i32_16x16x64_i8 v[70:73], v[62:65], v[198:201], v[70:73]
	v_mfma_i32_16x16x64_i8 v[66:69], v[78:81], v[198:201], v[66:69]
	v_mfma_i32_16x16x64_i8 v[46:49], v[62:65], v[206:209], v[46:49]
	v_mfma_i32_16x16x64_i8 v[42:45], v[78:81], v[206:209], v[42:45]
	v_mfma_i32_16x16x64_i8 v[30:33], v[62:65], v[214:217], v[30:33]
	v_mfma_i32_16x16x64_i8 v[26:29], v[78:81], v[214:217], v[26:29]
	v_mfma_i32_16x16x64_i8 v[14:17], v[62:65], v[222:225], v[14:17]
	v_mfma_i32_16x16x64_i8 v[10:13], v[78:81], v[222:225], v[10:13]
	s_setprio 0
	s_setprio 1
	v_mfma_i32_16x16x64_i8 v[54:57], v[162:165], v[194:197], v[54:57]
	v_mfma_i32_16x16x64_i8 v[50:53], v[170:173], v[194:197], v[50:53]
	v_mfma_i32_16x16x64_i8 v[38:41], v[162:165], v[202:205], v[38:41]
	v_mfma_i32_16x16x64_i8 v[34:37], v[170:173], v[202:205], v[34:37]
	v_mfma_i32_16x16x64_i8 v[22:25], v[162:165], v[210:213], v[22:25]
	v_mfma_i32_16x16x64_i8 v[18:21], v[170:173], v[210:213], v[18:21]
	v_mfma_i32_16x16x64_i8 v[6:9], v[162:165], v[218:221], v[6:9]
	v_mfma_i32_16x16x64_i8 v[2:5], v[170:173], v[218:221], v[2:5]
	v_mfma_i32_16x16x64_i8 v[54:57], v[166:169], v[198:201], v[54:57]
	v_mfma_i32_16x16x64_i8 v[50:53], v[190:193], v[198:201], v[50:53]
	v_mfma_i32_16x16x64_i8 v[38:41], v[166:169], v[206:209], v[38:41]
	v_mfma_i32_16x16x64_i8 v[34:37], v[190:193], v[206:209], v[34:37]
	v_mfma_i32_16x16x64_i8 v[22:25], v[166:169], v[214:217], v[22:25]
	v_mfma_i32_16x16x64_i8 v[18:21], v[190:193], v[214:217], v[18:21]
	v_mfma_i32_16x16x64_i8 v[6:9], v[166:169], v[222:225], v[6:9]
	v_mfma_i32_16x16x64_i8 v[2:5], v[190:193], v[222:225], v[2:5]
	s_setprio 0
	s_barrier
	s_add_i32 s40, s40, 2
	s_add_u32 s2, s2, 0x100
	s_addc_u32 s3, s3, 0
	s_add_u32 s38, s38, 0x100
	s_addc_u32 s39, s39, 0
	s_cmp_gt_u32 s40, 29
	s_cbranch_scc0 .LBB0_483
	s_and_b64 vcc, exec, s[20:21]
	s_cbranch_vccz .LBB0_486
	s_barrier

; #define PG8_STAGE(bufoff, gbase, voff) do { _Pragma("unroll") for (int _i = 0; _i < 2; ++_i) \
;         __builtin_amdgcn_global_load_lds((const unsigned*)((const char*)(gbase) + (voff)[_i]), (PG8_LAS unsigned*)(lds + (bufoff) + ldsw + _i * 8192), 16, 0, 0); } while (0)
; #define PG8_LDA(dst, b, h) do { _Pragma("unroll") for (int m = 0; m < 4; ++m) _Pragma("unroll") for (int k = 0; k < 2; ++k) dst[m][k] = *(const PG8_LAS bf16x8*)(lds + PG8_SA(b, h) + aoff + m * 2048 + k * 1024); } while (0)
; #define PG8_LDB(dst, b, h) do { _Pragma("unroll") for (int n = 0; n < 2; ++n) _Pragma("unroll") for (int k = 0; k < 2; ++k) dst[n][k] = *(const PG8_LAS bf16x8*)(lds + PG8_SB(b, h) + boff + n * 2048 + k * 1024); } while (0)
; #define PG8_MMA(ai, bj, At, Bt) do { __builtin_amdgcn_s_setprio(1); _Pragma("unroll") for (int m = 0; m < 4; ++m) _Pragma("unroll") for (int n = 0; n < 2; ++n) _Pragma("unroll") for (int k = 0; k < 2; ++k) \
;         acc[ai][bj][m][n] = mma_<I8>(Bt[n][k], At[m][k], acc[ai][bj][m][n]); __builtin_amdgcn_s_setprio(0); } while (0)
; #define PG8_WAIT_V(n) asm volatile("s_waitcnt vmcnt(" #n ")" ::: "memory")
; #define PG8_WAIT_L(n) asm volatile("s_waitcnt lgkmcnt(" #n ")" ::: "memory")
; #define PG8_BAR __builtin_amdgcn_s_barrier()
; #define PG8_SCHED __builtin_amdgcn_sched_barrier(0)
; template <class Epi, class Sched, bool ALIGN_EPI = false, bool SP2 = false, bool I8 = false>
; __device__ __forceinline__ void gemm_phase(PG8_LAS unsigned char* lds, const Gemm g, const Sched& S, const Epi& E) {
;     ...
;             PG8_LDB(B0, 0, 0); PG8_LDB(B1, 0, 1); PG8_SCHED; PG8_LDA(At, 0, 0); PG8_STAGE(PG8_SA(1, 1), a1 + hstepA, voffA);
;             PG8_WAIT_V(8); PG8_WAIT_L(0); PG8_BAR; PG8_MMA(0, 0, At, B0); PG8_MMA(0, 1, At, B1); PG8_BAR; PG8_SCHED;
;             PG8_LDA(At, 0, 1); PG8_STAGE(PG8_SB(0, 0), b2, voffB); PG8_STAGE(PG8_SB(0, 1), b2 + hstepB, voffB); PG8_STAGE(PG8_SA(0, 0), a2, voffA);
;             PG8_WAIT_V(8); PG8_WAIT_L(0); PG8_BAR; PG8_MMA(1, 0, At, B0); PG8_MMA(1, 1, At, B1); PG8_BAR; PG8_SCHED;
.LBB0_541:
	ds_read_b128 v[154:157], v149
	ds_read_b128 v[158:161], v149 offset:1024
	ds_read_b128 v[162:165], v149 offset:2048
	ds_read_b128 v[166:169], v149 offset:3072
	ds_read_b128 v[170:173], v151
	ds_read_b128 v[174:177], v151 offset:1024
	ds_read_b128 v[178:181], v151 offset:2048
	ds_read_b128 v[188:191], v151 offset:3072
	s_add_u32 s34, s30, 0xfff00080
	s_addc_u32 s35, s31, -1
	s_cmp_eq_u32 s94, 60
	s_cselect_b32 s37, s7, s35
	s_cselect_b32 s36, s25, s34
	s_cselect_b32 s35, s23, s93
	s_cselect_b32 s34, s29, s92
	s_add_i32 m0, s39, 0xc000
	ds_read_b128 v[192:195], v153
	ds_read_b128 v[196:199], v153 offset:1024
	ds_read_b128 v[200:203], v153 offset:2048
	ds_read_b128 v[204:207], v153 offset:3072
	ds_read_b128 v[208:211], v153 offset:4096
	ds_read_b128 v[212:215], v153 offset:5120
	ds_read_b128 v[216:219], v153 offset:6144
	ds_read_b128 v[220:223], v153 offset:7168
	global_load_lds_dwordx4 v138, s[30:31]
	s_add_i32 m0, s39, 0xe000
	s_nop 0
	global_load_lds_dwordx4 v140, s[30:31]
	s_waitcnt vmcnt(8) lgkmcnt(0)
	s_barrier
	s_setprio 1
	s_waitcnt lgkmcnt(0)
	v_mfma_f32_16x16x32_bf16 v[126:129], v[154:157], v[192:195], v[126:129]
	v_mfma_f32_16x16x32_bf16 v[122:125], v[162:165], v[192:195], v[122:125]
	v_mfma_f32_16x16x32_bf16 v[110:113], v[154:157], v[200:203], v[110:113]
	v_mfma_f32_16x16x32_bf16 v[106:109], v[162:165], v[200:203], v[106:109]
	v_mfma_f32_16x16x32_bf16 v[94:97], v[154:157], v[208:211], v[94:97]
	v_mfma_f32_16x16x32_bf16 v[90:93], v[162:165], v[208:211], v[90:93]
	v_mfma_f32_16x16x32_bf16 v[78:81], v[154:157], v[216:219], v[78:81]
	v_mfma_f32_16x16x32_bf16 v[74:77], v[162:165], v[216:219], v[74:77]
	v_mfma_f32_16x16x32_bf16 v[126:129], v[158:161], v[196:199], v[126:129]
	v_mfma_f32_16x16x32_bf16 v[122:125], v[166:169], v[196:199], v[122:125]
	v_mfma_f32_16x16x32_bf16 v[110:113], v[158:161], v[204:207], v[110:113]
	v_mfma_f32_16x16x32_bf16 v[106:109], v[166:169], v[204:207], v[106:109]
	v_mfma_f32_16x16x32_bf16 v[94:97], v[158:161], v[212:215], v[94:97]
	v_mfma_f32_16x16x32_bf16 v[90:93], v[166:169], v[212:215], v[90:93]
	v_mfma_f32_16x16x32_bf16 v[78:81], v[158:161], v[220:223], v[78:81]
	v_mfma_f32_16x16x32_bf16 v[74:77], v[166:169], v[220:223], v[74:77]
	s_setprio 0
	s_setprio 1
	v_mfma_f32_16x16x32_bf16 v[118:121], v[170:173], v[192:195], v[118:121]
	v_mfma_f32_16x16x32_bf16 v[114:117], v[178:181], v[192:195], v[114:117]
	v_mfma_f32_16x16x32_bf16 v[102:105], v[170:173], v[200:203], v[102:105]
	v_mfma_f32_16x16x32_bf16 v[98:101], v[178:181], v[200:203], v[98:101]
	v_mfma_f32_16x16x32_bf16 v[86:89], v[170:173], v[208:211], v[86:89]
	v_mfma_f32_16x16x32_bf16 v[82:85], v[178:181], v[208:211], v[82:85]
	v_mfma_f32_16x16x32_bf16 v[70:73], v[170:173], v[216:219], v[70:73]
	v_mfma_f32_16x16x32_bf16 v[66:69], v[178:181], v[216:219], v[66:69]
	v_mfma_f32_16x16x32_bf16 v[118:121], v[174:177], v[196:199], v[118:121]
	v_mfma_f32_16x16x32_bf16 v[114:117], v[188:191], v[196:199], v[114:117]
	v_mfma_f32_16x16x32_bf16 v[102:105], v[174:177], v[204:207], v[102:105]
	v_mfma_f32_16x16x32_bf16 v[98:101], v[188:191], v[204:207], v[98:101]
	v_mfma_f32_16x16x32_bf16 v[86:89], v[174:177], v[212:215], v[86:89]
	v_mfma_f32_16x16x32_bf16 v[82:85], v[188:191], v[212:215], v[82:85]
	v_mfma_f32_16x16x32_bf16 v[70:73], v[174:177], v[220:223], v[70:73]
	v_mfma_f32_16x16x32_bf16 v[66:69], v[188:191], v[220:223], v[66:69]
	s_setprio 0
	s_barrier
	s_add_i32 s95, s88, s38
	s_mov_b64 s[98:99], s[34:35]
	s_mov_b32 m0, s95
	ds_read_b128 v[192:195], v153 offset:16384
	ds_read_b128 v[196:199], v153 offset:17408
	ds_read_b128 v[200:203], v153 offset:18432
	ds_read_b128 v[204:207], v153 offset:19456
	ds_read_b128 v[208:211], v153 offset:20480
	ds_read_b128 v[212:215], v153 offset:21504
	ds_read_b128 v[216:219], v153 offset:22528
	ds_read_b128 v[220:223], v153 offset:23552
	global_load_lds_dwordx4 v132, s[34:35]
	s_add_i32 m0, s95, 0x2000
	s_add_u32 vcc_lo, s34, 0x100000
	s_mov_b64 s[98:99], s[34:35]
	s_addc_u32 vcc_hi, s35, 0
	s_add_i32 s95, s89, s38
	global_load_lds_dwordx4 v136, s[34:35]
	s_mov_b32 m0, s95
	s_mov_b64 s[100:101], s[36:37]
	global_load_lds_dwordx4 v132, vcc
	s_add_i32 m0, s95, 0x2000
	s_nop 0
	global_load_lds_dwordx4 v136, vcc
	s_mov_b64 s[100:101], s[36:37]
	s_mov_b32 m0, s39
	s_nop 0
	global_load_lds_dwordx4 v130, s[36:37]
	s_mov_b32 m0, s40
	s_nop 0
	global_load_lds_dwordx4 v134, s[36:37]
	s_waitcnt vmcnt(8) lgkmcnt(0)
	s_barrier
	s_setprio 1
	s_waitcnt lgkmcnt(0)
	v_mfma_f32_16x16x32_bf16 v[62:65], v[154:157], v[192:195], v[62:65]
	v_mfma_f32_16x16x32_bf16 v[58:61], v[162:165], v[192:195], v[58:61]
	v_mfma_f32_16x16x32_bf16 v[46:49], v[154:157], v[200:203], v[46:49]
	v_mfma_f32_16x16x32_bf16 v[42:45], v[162:165], v[200:203], v[42:45]
	v_mfma_f32_16x16x32_bf16 v[30:33], v[154:157], v[208:211], v[30:33]
	v_mfma_f32_16x16x32_bf16 v[26:29], v[162:165], v[208:211], v[26:29]
	v_mfma_f32_16x16x32_bf16 v[14:17], v[154:157], v[216:219], v[14:17]
	v_mfma_f32_16x16x32_bf16 v[10:13], v[162:165], v[216:219], v[10:13]
	v_mfma_f32_16x16x32_bf16 v[62:65], v[158:161], v[196:199], v[62:65]
	v_mfma_f32_16x16x32_bf16 v[58:61], v[166:169], v[196:199], v[58:61]
	v_mfma_f32_16x16x32_bf16 v[46:49], v[158:161], v[204:207], v[46:49]
	v_mfma_f32_16x16x32_bf16 v[42:45], v[166:169], v[204:207], v[42:45]
	v_mfma_f32_16x16x32_bf16 v[30:33], v[158:161], v[212:215], v[30:33]
	v_mfma_f32_16x16x32_bf16 v[26:29], v[166:169], v[212:215], v[26:29]
	v_mfma_f32_16x16x32_bf16 v[14:17], v[158:161], v[220:223], v[14:17]
	v_mfma_f32_16x16x32_bf16 v[10:13], v[166:169], v[220:223], v[10:13]
	s_setprio 0
	s_setprio 1
	v_mfma_f32_16x16x32_bf16 v[54:57], v[170:173], v[192:195], v[54:57]
	v_mfma_f32_16x16x32_bf16 v[50:53], v[178:181], v[192:195], v[50:53]
	v_mfma_f32_16x16x32_bf16 v[38:41], v[170:173], v[200:203], v[38:41]
	v_mfma_f32_16x16x32_bf16 v[34:37], v[178:181], v[200:203], v[34:37]
	v_mfma_f32_16x16x32_bf16 v[22:25], v[170:173], v[208:211], v[22:25]
	v_mfma_f32_16x16x32_bf16 v[18:21], v[178:181], v[208:211], v[18:21]
	v_mfma_f32_16x16x32_bf16 v[6:9], v[170:173], v[216:219], v[6:9]
	v_mfma_f32_16x16x32_bf16 v[2:5], v[178:181], v[216:219], v[2:5]
	v_mfma_f32_16x16x32_bf16 v[54:57], v[174:177], v[196:199], v[54:57]
	v_mfma_f32_16x16x32_bf16 v[50:53], v[188:191], v[196:199], v[50:53]
	v_mfma_f32_16x16x32_bf16 v[38:41], v[174:177], v[204:207], v[38:41]
	v_mfma_f32_16x16x32_bf16 v[34:37], v[188:191], v[204:207], v[34:37]
	v_mfma_f32_16x16x32_bf16 v[22:25], v[174:177], v[212:215], v[22:25]
	v_mfma_f32_16x16x32_bf16 v[18:21], v[188:191], v[212:215], v[18:21]
	v_mfma_f32_16x16x32_bf16 v[6:9], v[174:177], v[220:223], v[6:9]
	v_mfma_f32_16x16x32_bf16 v[2:5], v[188:191], v[220:223], v[2:5]
	s_setprio 0
	s_barrier
; #define PG8_STAGE(bufoff, gbase, voff) do { _Pragma("unroll") for (int _i = 0; _i < 2; ++_i) \
;         __builtin_amdgcn_global_load_lds((const unsigned*)((const char*)(gbase) + (voff)[_i]), (PG8_LAS unsigned*)(lds + (bufoff) + ldsw + _i * 8192), 16, 0, 0); } while (0)
; #define PG8_LDA(dst, b, h) do { _Pragma("unroll") for (int m = 0; m < 4; ++m) _Pragma("unroll") for (int k = 0; k < 2; ++k) dst[m][k] = *(const PG8_LAS bf16x8*)(lds + PG8_SA(b, h) + aoff + m * 2048 + k * 1024); } while (0)
; #define PG8_LDB(dst, b, h) do { _Pragma("unroll") for (int n = 0; n < 2; ++n) _Pragma("unroll") for (int k = 0; k < 2; ++k) dst[n][k] = *(const PG8_LAS bf16x8*)(lds + PG8_SB(b, h) + boff + n * 2048 + k * 1024); } while (0)
; #define PG8_MMA(ai, bj, At, Bt) do { __builtin_amdgcn_s_setprio(1); _Pragma("unroll") for (int m = 0; m < 4; ++m) _Pragma("unroll") for (int n = 0; n < 2; ++n) _Pragma("unroll") for (int k = 0; k < 2; ++k) \
;         acc[ai][bj][m][n] = mma_<I8>(Bt[n][k], At[m][k], acc[ai][bj][m][n]); __builtin_amdgcn_s_setprio(0); } while (0)
; #define PG8_WAIT_V(n) asm volatile("s_waitcnt vmcnt(" #n ")" ::: "memory")
; #define PG8_WAIT_L(n) asm volatile("s_waitcnt lgkmcnt(" #n ")" ::: "memory")
; #define PG8_BAR __builtin_amdgcn_s_barrier()
; #define PG8_SCHED __builtin_amdgcn_sched_barrier(0)
; template <class Epi, class Sched, bool ALIGN_EPI = false, bool SP2 = false, bool I8 = false>
; __device__ __forceinline__ void gemm_phase(PG8_LAS unsigned char* lds, const Gemm g, const Sched& S, const Epi& E) {
;     ...
;         for (int t = 0; t < nt; t += 2) {
;             const bool last = (t == nt - 2);
;             const char* a1 = cA + (size_t)(t + 1) * kstep;
;             const char* a2 = last ? nA : cA + (size_t)(t + 2) * kstep; const char* b2 = last ? nB : cB + (size_t)(t + 2) * kstep;
;             const char* a3 = a2 + kstep; const char* b3 = b2 + kstep;
;     ...
;             PG8_LDB(B0, 1, 0); PG8_LDB(B1, 1, 1); PG8_SCHED; PG8_LDA(At, 1, 0); PG8_STAGE(PG8_SA(0, 1), a2 + hstepA, voffA);
;             PG8_WAIT_V(8); PG8_WAIT_L(0); PG8_BAR; PG8_MMA(0, 0, At, B0); PG8_MMA(0, 1, At, B1); PG8_BAR; PG8_SCHED;
;             PG8_LDA(At, 1, 1); PG8_STAGE(PG8_SB(1, 0), b3, voffB); PG8_STAGE(PG8_SB(1, 1), b3 + hstepB, voffB); PG8_STAGE(PG8_SA(1, 0), a3, voffA);
;             PG8_WAIT_V(8); PG8_WAIT_L(0); PG8_BAR; PG8_MMA(1, 0, At, B0); PG8_MMA(1, 1, At, B1); PG8_BAR; PG8_SCHED;
	s_add_i32 s95, 0, 0x18000
	s_add_i32 vcc_lo, 0, 0x1c000
	v_add_u32_e32 v166, s95, v147
	v_add_u32_e32 v187, vcc_lo, v147
	ds_read_b128 v[154:157], v166
	ds_read_b128 v[158:161], v166 offset:1024
	ds_read_b128 v[162:165], v166 offset:2048
	ds_read_b128 v[166:169], v166 offset:3072
	ds_read_b128 v[170:173], v187
	ds_read_b128 v[174:177], v187 offset:1024
	ds_read_b128 v[178:181], v187 offset:2048
	ds_read_b128 v[188:191], v187 offset:3072
	s_add_u32 s36, s36, 0x100000
	s_addc_u32 s37, s37, 0
	s_mov_b32 m0, s41
	ds_read_b128 v[192:195], v153 offset:32768
	ds_read_b128 v[196:199], v153 offset:33792
	ds_read_b128 v[200:203], v153 offset:34816
	ds_read_b128 v[204:207], v153 offset:35840
	ds_read_b128 v[208:211], v153 offset:36864
	ds_read_b128 v[212:215], v153 offset:37888
	ds_read_b128 v[216:219], v153 offset:38912
	ds_read_b128 v[220:223], v153 offset:39936
	global_load_lds_dwordx4 v130, s[36:37]
	s_mov_b32 m0, s46
	s_nop 0
	global_load_lds_dwordx4 v134, s[36:37]
	s_waitcnt vmcnt(8) lgkmcnt(0)
	s_barrier
	s_setprio 1
	s_waitcnt lgkmcnt(0)
	v_mfma_f32_16x16x32_bf16 v[126:129], v[154:157], v[192:195], v[126:129]
	v_mfma_f32_16x16x32_bf16 v[122:125], v[162:165], v[192:195], v[122:125]
	v_mfma_f32_16x16x32_bf16 v[110:113], v[154:157], v[200:203], v[110:113]
	v_mfma_f32_16x16x32_bf16 v[106:109], v[162:165], v[200:203], v[106:109]
	v_mfma_f32_16x16x32_bf16 v[94:97], v[154:157], v[208:211], v[94:97]
	v_mfma_f32_16x16x32_bf16 v[90:93], v[162:165], v[208:211], v[90:93]
	v_mfma_f32_16x16x32_bf16 v[78:81], v[154:157], v[216:219], v[78:81]
	v_mfma_f32_16x16x32_bf16 v[74:77], v[162:165], v[216:219], v[74:77]
	v_mfma_f32_16x16x32_bf16 v[126:129], v[158:161], v[196:199], v[126:129]
	v_mfma_f32_16x16x32_bf16 v[122:125], v[166:169], v[196:199], v[122:125]
	v_mfma_f32_16x16x32_bf16 v[110:113], v[158:161], v[204:207], v[110:113]
	v_mfma_f32_16x16x32_bf16 v[106:109], v[166:169], v[204:207], v[106:109]
	v_mfma_f32_16x16x32_bf16 v[94:97], v[158:161], v[212:215], v[94:97]
	v_mfma_f32_16x16x32_bf16 v[90:93], v[166:169], v[212:215], v[90:93]
	v_mfma_f32_16x16x32_bf16 v[78:81], v[158:161], v[220:223], v[78:81]
	v_mfma_f32_16x16x32_bf16 v[74:77], v[166:169], v[220:223], v[74:77]
	s_setprio 0
	s_setprio 1
	v_mfma_f32_16x16x32_bf16 v[118:121], v[170:173], v[192:195], v[118:121]
	v_mfma_f32_16x16x32_bf16 v[114:117], v[178:181], v[192:195], v[114:117]
	v_mfma_f32_16x16x32_bf16 v[102:105], v[170:173], v[200:203], v[102:105]
	v_mfma_f32_16x16x32_bf16 v[98:101], v[178:181], v[200:203], v[98:101]
	v_mfma_f32_16x16x32_bf16 v[86:89], v[170:173], v[208:211], v[86:89]
	v_mfma_f32_16x16x32_bf16 v[82:85], v[178:181], v[208:211], v[82:85]
	v_mfma_f32_16x16x32_bf16 v[70:73], v[170:173], v[216:219], v[70:73]
	v_mfma_f32_16x16x32_bf16 v[66:69], v[178:181], v[216:219], v[66:69]
	v_mfma_f32_16x16x32_bf16 v[118:121], v[174:177], v[196:199], v[118:121]
	v_mfma_f32_16x16x32_bf16 v[114:117], v[188:191], v[196:199], v[114:117]
	v_mfma_f32_16x16x32_bf16 v[102:105], v[174:177], v[204:207], v[102:105]
	v_mfma_f32_16x16x32_bf16 v[98:101], v[188:191], v[204:207], v[98:101]
	v_mfma_f32_16x16x32_bf16 v[86:89], v[174:177], v[212:215], v[86:89]
	v_mfma_f32_16x16x32_bf16 v[82:85], v[188:191], v[212:215], v[82:85]
	v_mfma_f32_16x16x32_bf16 v[70:73], v[174:177], v[220:223], v[70:73]
	v_mfma_f32_16x16x32_bf16 v[66:69], v[188:191], v[220:223], v[66:69]
	s_setprio 0
	s_barrier
	s_add_i32 s36, s95, s38
	s_add_i32 m0, s36, 0xffffff80
	ds_read_b128 v[192:195], v153 offset:49152
	ds_read_b128 v[196:199], v153 offset:50176
	ds_read_b128 v[200:203], v153 offset:51200
	ds_read_b128 v[204:207], v153 offset:52224
	ds_read_b128 v[208:211], v153 offset:53248
	ds_read_b128 v[212:215], v153 offset:54272
	ds_read_b128 v[216:219], v153 offset:55296
	ds_read_b128 v[220:223], v153 offset:56320
	global_load_lds_dwordx4 v132, s[98:99] offset:128
	s_add_i32 m0, s36, 0x1f80
	s_add_u32 s34, s34, 0x100080
	s_addc_u32 s35, s35, 0
	s_add_i32 s36, vcc_lo, s38
	global_load_lds_dwordx4 v136, s[98:99] offset:128
	s_mov_b32 m0, s36
	s_nop 0
	global_load_lds_dwordx4 v132, s[34:35]
	s_add_i32 m0, s36, 0x2000
	s_nop 0
	global_load_lds_dwordx4 v136, s[34:35]
	s_add_i32 m0, s68, 0xffffff80
	s_nop 0
	global_load_lds_dwordx4 v130, s[100:101] offset:128
	s_add_i32 m0, s69, 0xffffff80
	s_nop 0
	global_load_lds_dwordx4 v134, s[100:101] offset:128
	s_waitcnt vmcnt(8) lgkmcnt(0)
	s_barrier
	s_setprio 1
	s_waitcnt lgkmcnt(0)
	v_mfma_f32_16x16x32_bf16 v[62:65], v[154:157], v[192:195], v[62:65]
	v_mfma_f32_16x16x32_bf16 v[58:61], v[162:165], v[192:195], v[58:61]
	v_mfma_f32_16x16x32_bf16 v[46:49], v[154:157], v[200:203], v[46:49]
	v_mfma_f32_16x16x32_bf16 v[42:45], v[162:165], v[200:203], v[42:45]
	v_mfma_f32_16x16x32_bf16 v[30:33], v[154:157], v[208:211], v[30:33]
	v_mfma_f32_16x16x32_bf16 v[26:29], v[162:165], v[208:211], v[26:29]
	v_mfma_f32_16x16x32_bf16 v[14:17], v[154:157], v[216:219], v[14:17]
	v_mfma_f32_16x16x32_bf16 v[10:13], v[162:165], v[216:219], v[10:13]
	v_mfma_f32_16x16x32_bf16 v[62:65], v[158:161], v[196:199], v[62:65]
	v_mfma_f32_16x16x32_bf16 v[58:61], v[166:169], v[196:199], v[58:61]
	v_mfma_f32_16x16x32_bf16 v[46:49], v[158:161], v[204:207], v[46:49]
	v_mfma_f32_16x16x32_bf16 v[42:45], v[166:169], v[204:207], v[42:45]
	v_mfma_f32_16x16x32_bf16 v[30:33], v[158:161], v[212:215], v[30:33]
	v_mfma_f32_16x16x32_bf16 v[26:29], v[166:169], v[212:215], v[26:29]
	v_mfma_f32_16x16x32_bf16 v[14:17], v[158:161], v[220:223], v[14:17]
	v_mfma_f32_16x16x32_bf16 v[10:13], v[166:169], v[220:223], v[10:13]
	s_setprio 0
	s_setprio 1
	v_mfma_f32_16x16x32_bf16 v[54:57], v[170:173], v[192:195], v[54:57]
	v_mfma_f32_16x16x32_bf16 v[50:53], v[178:181], v[192:195], v[50:53]
	v_mfma_f32_16x16x32_bf16 v[38:41], v[170:173], v[200:203], v[38:41]
	v_mfma_f32_16x16x32_bf16 v[34:37], v[178:181], v[200:203], v[34:37]
	v_mfma_f32_16x16x32_bf16 v[22:25], v[170:173], v[208:211], v[22:25]
	v_mfma_f32_16x16x32_bf16 v[18:21], v[178:181], v[208:211], v[18:21]
	v_mfma_f32_16x16x32_bf16 v[6:9], v[170:173], v[216:219], v[6:9]
	v_mfma_f32_16x16x32_bf16 v[2:5], v[178:181], v[216:219], v[2:5]
	v_mfma_f32_16x16x32_bf16 v[54:57], v[174:177], v[196:199], v[54:57]
	v_mfma_f32_16x16x32_bf16 v[50:53], v[188:191], v[196:199], v[50:53]
	v_mfma_f32_16x16x32_bf16 v[38:41], v[174:177], v[204:207], v[38:41]
	v_mfma_f32_16x16x32_bf16 v[34:37], v[188:191], v[204:207], v[34:37]
	v_mfma_f32_16x16x32_bf16 v[22:25], v[174:177], v[212:215], v[22:25]
	v_mfma_f32_16x16x32_bf16 v[18:21], v[188:191], v[212:215], v[18:21]
	v_mfma_f32_16x16x32_bf16 v[6:9], v[174:177], v[220:223], v[6:9]
	v_mfma_f32_16x16x32_bf16 v[2:5], v[188:191], v[220:223], v[2:5]
	s_setprio 0
	s_barrier
	s_add_i32 s94, s94, 2
	s_add_u32 s30, s30, 0x100
	s_addc_u32 s31, s31, 0
	s_add_u32 s92, s92, 0x100
	s_addc_u32 s93, s93, 0
	s_cmp_gt_u32 s94, 61
	s_cbranch_scc0 .LBB0_541
	s_and_b64 vcc, exec, s[20:21]
	s_cbranch_vccz .LBB0_544
	s_barrier

; #define PG8_STAGE(bufoff, gbase, voff) do { _Pragma("unroll") for (int _i = 0; _i < 2; ++_i) \
;         __builtin_amdgcn_global_load_lds((const unsigned*)((const char*)(gbase) + (voff)[_i]), (PG8_LAS unsigned*)(lds + (bufoff) + ldsw + _i * 8192), 16, 0, 0); } while (0)
; #define PG8_LDA(dst, b, h) do { _Pragma("unroll") for (int m = 0; m < 4; ++m) _Pragma("unroll") for (int k = 0; k < 2; ++k) dst[m][k] = *(const PG8_LAS bf16x8*)(lds + PG8_SA(b, h) + aoff + m * 2048 + k * 1024); } while (0)
; #define PG8_LDB(dst, b, h) do { _Pragma("unroll") for (int n = 0; n < 2; ++n) _Pragma("unroll") for (int k = 0; k < 2; ++k) dst[n][k] = *(const PG8_LAS bf16x8*)(lds + PG8_SB(b, h) + boff + n * 2048 + k * 1024); } while (0)
; #define PG8_MMA(ai, bj, At, Bt) do { __builtin_amdgcn_s_setprio(1); _Pragma("unroll") for (int m = 0; m < 4; ++m) _Pragma("unroll") for (int n = 0; n < 2; ++n) _Pragma("unroll") for (int k = 0; k < 2; ++k) \
;         acc[ai][bj][m][n] = mma_<I8>(Bt[n][k], At[m][k], acc[ai][bj][m][n]); __builtin_amdgcn_s_setprio(0); } while (0)
; #define PG8_WAIT_V(n) asm volatile("s_waitcnt vmcnt(" #n ")" ::: "memory")
; #define PG8_WAIT_L(n) asm volatile("s_waitcnt lgkmcnt(" #n ")" ::: "memory")
; #define PG8_BAR __builtin_amdgcn_s_barrier()
; #define PG8_SCHED __builtin_amdgcn_sched_barrier(0)
; template <class Epi, class Sched, bool ALIGN_EPI = false, bool SP2 = false, bool I8 = false>
; __device__ __forceinline__ void gemm_phase(PG8_LAS unsigned char* lds, const Gemm g, const Sched& S, const Epi& E) {
;     ...
;             PG8_LDB(B0, 0, 0); PG8_LDB(B1, 0, 1); PG8_SCHED; PG8_LDA(At, 0, 0); PG8_STAGE(PG8_SA(1, 1), a1 + hstepA, voffA);
;             PG8_WAIT_V(8); PG8_WAIT_L(0); PG8_BAR; PG8_MMA(0, 0, At, B0); PG8_MMA(0, 1, At, B1); PG8_BAR; PG8_SCHED;
;             PG8_LDA(At, 0, 1); PG8_STAGE(PG8_SB(0, 0), b2, voffB); PG8_STAGE(PG8_SB(0, 1), b2 + hstepB, voffB); PG8_STAGE(PG8_SA(0, 0), a2, voffA);
;             PG8_WAIT_V(8); PG8_WAIT_L(0); PG8_BAR; PG8_MMA(1, 0, At, B0); PG8_MMA(1, 1, At, B1); PG8_BAR; PG8_SCHED;
.LBB0_607:
	ds_read_b128 v[58:61], v177
	ds_read_b128 v[62:65], v177 offset:1024
	ds_read_b128 v[74:77], v177 offset:2048
	ds_read_b128 v[78:81], v177 offset:3072
	ds_read_b128 v[162:165], v178
	ds_read_b128 v[166:169], v178 offset:1024
	ds_read_b128 v[170:173], v178 offset:2048
	ds_read_b128 v[180:183], v178 offset:3072
	s_add_u32 s34, s2, 0xfff80080
	s_addc_u32 s35, s3, -1
	s_cmp_eq_u32 s39, 28
	s_cselect_b32 s37, s7, s35
	s_cselect_b32 s36, s9, s34
	s_cselect_b32 s35, s23, s38
	s_cselect_b32 s34, s25, s31
	s_add_i32 m0, s69, 0xc000
	ds_read_b128 v[184:187], v179
	ds_read_b128 v[188:191], v179 offset:1024
	ds_read_b128 v[192:195], v179 offset:2048
	ds_read_b128 v[196:199], v179 offset:3072
	ds_read_b128 v[200:203], v179 offset:4096
	ds_read_b128 v[204:207], v179 offset:5120
	ds_read_b128 v[208:211], v179 offset:6144
	ds_read_b128 v[212:215], v179 offset:7168
	global_load_lds_dwordx4 v154, s[2:3]
	s_add_i32 m0, s69, 0xe000
	s_nop 0
	global_load_lds_dwordx4 v156, s[2:3]
	s_waitcnt vmcnt(8) lgkmcnt(0)
	s_barrier
	s_setprio 1
	s_waitcnt lgkmcnt(0)
	v_mfma_i32_16x16x64_i8 v[142:145], v[58:61], v[184:187], v[142:145]
	v_mfma_i32_16x16x64_i8 v[138:141], v[74:77], v[184:187], v[138:141]
	v_mfma_i32_16x16x64_i8 v[126:129], v[58:61], v[192:195], v[126:129]
	v_mfma_i32_16x16x64_i8 v[122:125], v[74:77], v[192:195], v[122:125]
	v_mfma_i32_16x16x64_i8 v[110:113], v[58:61], v[200:203], v[110:113]
	v_mfma_i32_16x16x64_i8 v[106:109], v[74:77], v[200:203], v[106:109]
	v_mfma_i32_16x16x64_i8 v[94:97], v[58:61], v[208:211], v[94:97]
	v_mfma_i32_16x16x64_i8 v[90:93], v[74:77], v[208:211], v[90:93]
	v_mfma_i32_16x16x64_i8 v[142:145], v[62:65], v[188:191], v[142:145]
	v_mfma_i32_16x16x64_i8 v[138:141], v[78:81], v[188:191], v[138:141]
	v_mfma_i32_16x16x64_i8 v[126:129], v[62:65], v[196:199], v[126:129]
	v_mfma_i32_16x16x64_i8 v[122:125], v[78:81], v[196:199], v[122:125]
	v_mfma_i32_16x16x64_i8 v[110:113], v[62:65], v[204:207], v[110:113]
	v_mfma_i32_16x16x64_i8 v[106:109], v[78:81], v[204:207], v[106:109]
	v_mfma_i32_16x16x64_i8 v[94:97], v[62:65], v[212:215], v[94:97]
	v_mfma_i32_16x16x64_i8 v[90:93], v[78:81], v[212:215], v[90:93]
	s_setprio 0
	s_setprio 1
	v_mfma_i32_16x16x64_i8 v[134:137], v[162:165], v[184:187], v[134:137]
	v_mfma_i32_16x16x64_i8 v[130:133], v[170:173], v[184:187], v[130:133]
	v_mfma_i32_16x16x64_i8 v[118:121], v[162:165], v[192:195], v[118:121]
	v_mfma_i32_16x16x64_i8 v[114:117], v[170:173], v[192:195], v[114:117]
	v_mfma_i32_16x16x64_i8 v[102:105], v[162:165], v[200:203], v[102:105]
	v_mfma_i32_16x16x64_i8 v[98:101], v[170:173], v[200:203], v[98:101]
	v_mfma_i32_16x16x64_i8 v[86:89], v[162:165], v[208:211], v[86:89]
	v_mfma_i32_16x16x64_i8 v[82:85], v[170:173], v[208:211], v[82:85]
	v_mfma_i32_16x16x64_i8 v[134:137], v[166:169], v[188:191], v[134:137]
	v_mfma_i32_16x16x64_i8 v[130:133], v[180:183], v[188:191], v[130:133]
	v_mfma_i32_16x16x64_i8 v[118:121], v[166:169], v[196:199], v[118:121]
	v_mfma_i32_16x16x64_i8 v[114:117], v[180:183], v[196:199], v[114:117]
	v_mfma_i32_16x16x64_i8 v[102:105], v[166:169], v[204:207], v[102:105]
	v_mfma_i32_16x16x64_i8 v[98:101], v[180:183], v[204:207], v[98:101]
	v_mfma_i32_16x16x64_i8 v[86:89], v[166:169], v[212:215], v[86:89]
	v_mfma_i32_16x16x64_i8 v[82:85], v[180:183], v[212:215], v[82:85]
	s_setprio 0
	s_barrier
	s_add_i32 s40, s33, s68
	s_mov_b64 s[98:99], s[34:35]
	s_mov_b32 m0, s40
	ds_read_b128 v[184:187], v179 offset:16384
	ds_read_b128 v[188:191], v179 offset:17408
	ds_read_b128 v[192:195], v179 offset:18432
	ds_read_b128 v[196:199], v179 offset:19456
	ds_read_b128 v[200:203], v179 offset:20480
	ds_read_b128 v[204:207], v179 offset:21504
	ds_read_b128 v[208:211], v179 offset:22528
	ds_read_b128 v[212:215], v179 offset:23552
	global_load_lds_dwordx4 v148, s[34:35]
	s_add_i32 m0, s40, 0x2000
	s_add_u32 s40, s34, 0x80000
	s_mov_b64 s[98:99], s[34:35]
	s_addc_u32 s41, s35, 0
	s_add_i32 vcc_lo, s8, s68
	global_load_lds_dwordx4 v152, s[34:35]
	s_mov_b32 m0, vcc_lo
	s_mov_b64 s[100:101], s[36:37]
	global_load_lds_dwordx4 v148, s[40:41]
	s_add_i32 m0, vcc_lo, 0x2000
	s_nop 0
	global_load_lds_dwordx4 v152, s[40:41]
	s_mov_b64 s[100:101], s[36:37]
	s_mov_b32 m0, s69
	s_nop 0
	global_load_lds_dwordx4 v146, s[36:37]
	s_mov_b32 m0, s70
	s_nop 0
	global_load_lds_dwordx4 v150, s[36:37]
	s_waitcnt vmcnt(8) lgkmcnt(0)
	s_barrier
	s_setprio 1
	s_waitcnt lgkmcnt(0)
	v_mfma_i32_16x16x64_i8 v[70:73], v[58:61], v[184:187], v[70:73]
	v_mfma_i32_16x16x64_i8 v[66:69], v[74:77], v[184:187], v[66:69]
	v_mfma_i32_16x16x64_i8 v[46:49], v[58:61], v[192:195], v[46:49]
	v_mfma_i32_16x16x64_i8 v[42:45], v[74:77], v[192:195], v[42:45]
	v_mfma_i32_16x16x64_i8 v[30:33], v[58:61], v[200:203], v[30:33]
	v_mfma_i32_16x16x64_i8 v[26:29], v[74:77], v[200:203], v[26:29]
	v_mfma_i32_16x16x64_i8 v[14:17], v[58:61], v[208:211], v[14:17]
	v_mfma_i32_16x16x64_i8 v[10:13], v[74:77], v[208:211], v[10:13]
	v_mfma_i32_16x16x64_i8 v[70:73], v[62:65], v[188:191], v[70:73]
	v_mfma_i32_16x16x64_i8 v[66:69], v[78:81], v[188:191], v[66:69]
	v_mfma_i32_16x16x64_i8 v[46:49], v[62:65], v[196:199], v[46:49]
	v_mfma_i32_16x16x64_i8 v[42:45], v[78:81], v[196:199], v[42:45]
	v_mfma_i32_16x16x64_i8 v[30:33], v[62:65], v[204:207], v[30:33]
	v_mfma_i32_16x16x64_i8 v[26:29], v[78:81], v[204:207], v[26:29]
	v_mfma_i32_16x16x64_i8 v[14:17], v[62:65], v[212:215], v[14:17]
	v_mfma_i32_16x16x64_i8 v[10:13], v[78:81], v[212:215], v[10:13]
	s_setprio 0
	s_setprio 1
	v_mfma_i32_16x16x64_i8 v[54:57], v[162:165], v[184:187], v[54:57]
	v_mfma_i32_16x16x64_i8 v[50:53], v[170:173], v[184:187], v[50:53]
	v_mfma_i32_16x16x64_i8 v[38:41], v[162:165], v[192:195], v[38:41]
	v_mfma_i32_16x16x64_i8 v[34:37], v[170:173], v[192:195], v[34:37]
	v_mfma_i32_16x16x64_i8 v[22:25], v[162:165], v[200:203], v[22:25]
	v_mfma_i32_16x16x64_i8 v[18:21], v[170:173], v[200:203], v[18:21]
	v_mfma_i32_16x16x64_i8 v[6:9], v[162:165], v[208:211], v[6:9]
	v_mfma_i32_16x16x64_i8 v[2:5], v[170:173], v[208:211], v[2:5]
	v_mfma_i32_16x16x64_i8 v[54:57], v[166:169], v[188:191], v[54:57]
	v_mfma_i32_16x16x64_i8 v[50:53], v[180:183], v[188:191], v[50:53]
	v_mfma_i32_16x16x64_i8 v[38:41], v[166:169], v[196:199], v[38:41]
	v_mfma_i32_16x16x64_i8 v[34:37], v[180:183], v[196:199], v[34:37]
	v_mfma_i32_16x16x64_i8 v[22:25], v[166:169], v[204:207], v[22:25]
	v_mfma_i32_16x16x64_i8 v[18:21], v[180:183], v[204:207], v[18:21]
	v_mfma_i32_16x16x64_i8 v[6:9], v[166:169], v[212:215], v[6:9]
	v_mfma_i32_16x16x64_i8 v[2:5], v[180:183], v[212:215], v[2:5]
	s_setprio 0
	s_barrier
; #define PG8_STAGE(bufoff, gbase, voff) do { _Pragma("unroll") for (int _i = 0; _i < 2; ++_i) \
;         __builtin_amdgcn_global_load_lds((const unsigned*)((const char*)(gbase) + (voff)[_i]), (PG8_LAS unsigned*)(lds + (bufoff) + ldsw + _i * 8192), 16, 0, 0); } while (0)
; #define PG8_LDA(dst, b, h) do { _Pragma("unroll") for (int m = 0; m < 4; ++m) _Pragma("unroll") for (int k = 0; k < 2; ++k) dst[m][k] = *(const PG8_LAS bf16x8*)(lds + PG8_SA(b, h) + aoff + m * 2048 + k * 1024); } while (0)
; #define PG8_LDB(dst, b, h) do { _Pragma("unroll") for (int n = 0; n < 2; ++n) _Pragma("unroll") for (int k = 0; k < 2; ++k) dst[n][k] = *(const PG8_LAS bf16x8*)(lds + PG8_SB(b, h) + boff + n * 2048 + k * 1024); } while (0)
; #define PG8_MMA(ai, bj, At, Bt) do { __builtin_amdgcn_s_setprio(1); _Pragma("unroll") for (int m = 0; m < 4; ++m) _Pragma("unroll") for (int n = 0; n < 2; ++n) _Pragma("unroll") for (int k = 0; k < 2; ++k) \
;         acc[ai][bj][m][n] = mma_<I8>(Bt[n][k], At[m][k], acc[ai][bj][m][n]); __builtin_amdgcn_s_setprio(0); } while (0)
; #define PG8_WAIT_V(n) asm volatile("s_waitcnt vmcnt(" #n ")" ::: "memory")
; #define PG8_WAIT_L(n) asm volatile("s_waitcnt lgkmcnt(" #n ")" ::: "memory")
; #define PG8_BAR __builtin_amdgcn_s_barrier()
; #define PG8_SCHED __builtin_amdgcn_sched_barrier(0)
; template <class Epi, class Sched, bool ALIGN_EPI = false, bool SP2 = false, bool I8 = false>
; __device__ __forceinline__ void gemm_phase(PG8_LAS unsigned char* lds, const Gemm g, const Sched& S, const Epi& E) {
;     ...
;         for (int t = 0; t < nt; t += 2) {
;             const bool last = (t == nt - 2);
;             const char* a1 = cA + (size_t)(t + 1) * kstep;
;             const char* a2 = last ? nA : cA + (size_t)(t + 2) * kstep; const char* b2 = last ? nB : cB + (size_t)(t + 2) * kstep;
;             const char* a3 = a2 + kstep; const char* b3 = b2 + kstep;
;     ...
;             PG8_LDB(B0, 1, 0); PG8_LDB(B1, 1, 1); PG8_SCHED; PG8_LDA(At, 1, 0); PG8_STAGE(PG8_SA(0, 1), a2 + hstepA, voffA);
;             PG8_WAIT_V(8); PG8_WAIT_L(0); PG8_BAR; PG8_MMA(0, 0, At, B0); PG8_MMA(0, 1, At, B1); PG8_BAR; PG8_SCHED;
;             PG8_LDA(At, 1, 1); PG8_STAGE(PG8_SB(1, 0), b3, voffB); PG8_STAGE(PG8_SB(1, 1), b3 + hstepB, voffB); PG8_STAGE(PG8_SA(1, 0), a3, voffA);
;             PG8_WAIT_V(8); PG8_WAIT_L(0); PG8_BAR; PG8_MMA(1, 0, At, B0); PG8_MMA(1, 1, At, B1); PG8_BAR; PG8_SCHED;
	s_add_i32 s40, 0, 0x18000
	s_add_i32 s41, 0, 0x1c000
	v_add_u32_e32 v78, s40, v176
	v_add_u32_e32 v180, s41, v176
	ds_read_b128 v[58:61], v78
	ds_read_b128 v[62:65], v78 offset:1024
	ds_read_b128 v[74:77], v78 offset:2048
	ds_read_b128 v[78:81], v78 offset:3072
	ds_read_b128 v[162:165], v180
	ds_read_b128 v[166:169], v180 offset:1024
	ds_read_b128 v[170:173], v180 offset:2048
	ds_read_b128 v[180:183], v180 offset:3072
	s_add_u32 s36, s36, 0x80000
	s_addc_u32 s37, s37, 0
	s_mov_b32 m0, s71
	ds_read_b128 v[184:187], v179 offset:32768
	ds_read_b128 v[188:191], v179 offset:33792
	ds_read_b128 v[192:195], v179 offset:34816
	ds_read_b128 v[196:199], v179 offset:35840
	ds_read_b128 v[200:203], v179 offset:36864
	ds_read_b128 v[204:207], v179 offset:37888
	ds_read_b128 v[208:211], v179 offset:38912
	ds_read_b128 v[212:215], v179 offset:39936
	global_load_lds_dwordx4 v146, s[36:37]
	s_mov_b32 m0, s88
	s_nop 0
	global_load_lds_dwordx4 v150, s[36:37]
	s_waitcnt vmcnt(8) lgkmcnt(0)
	s_barrier
	s_setprio 1
	s_waitcnt lgkmcnt(0)
	v_mfma_i32_16x16x64_i8 v[142:145], v[58:61], v[184:187], v[142:145]
	v_mfma_i32_16x16x64_i8 v[138:141], v[74:77], v[184:187], v[138:141]
	v_mfma_i32_16x16x64_i8 v[126:129], v[58:61], v[192:195], v[126:129]
	v_mfma_i32_16x16x64_i8 v[122:125], v[74:77], v[192:195], v[122:125]
	v_mfma_i32_16x16x64_i8 v[110:113], v[58:61], v[200:203], v[110:113]
	v_mfma_i32_16x16x64_i8 v[106:109], v[74:77], v[200:203], v[106:109]
	v_mfma_i32_16x16x64_i8 v[94:97], v[58:61], v[208:211], v[94:97]
	v_mfma_i32_16x16x64_i8 v[90:93], v[74:77], v[208:211], v[90:93]
	v_mfma_i32_16x16x64_i8 v[142:145], v[62:65], v[188:191], v[142:145]
	v_mfma_i32_16x16x64_i8 v[138:141], v[78:81], v[188:191], v[138:141]
	v_mfma_i32_16x16x64_i8 v[126:129], v[62:65], v[196:199], v[126:129]
	v_mfma_i32_16x16x64_i8 v[122:125], v[78:81], v[196:199], v[122:125]
	v_mfma_i32_16x16x64_i8 v[110:113], v[62:65], v[204:207], v[110:113]
	v_mfma_i32_16x16x64_i8 v[106:109], v[78:81], v[204:207], v[106:109]
	v_mfma_i32_16x16x64_i8 v[94:97], v[62:65], v[212:215], v[94:97]
	v_mfma_i32_16x16x64_i8 v[90:93], v[78:81], v[212:215], v[90:93]
	s_setprio 0
	s_setprio 1
	v_mfma_i32_16x16x64_i8 v[134:137], v[162:165], v[184:187], v[134:137]
	v_mfma_i32_16x16x64_i8 v[130:133], v[170:173], v[184:187], v[130:133]
	v_mfma_i32_16x16x64_i8 v[118:121], v[162:165], v[192:195], v[118:121]
	v_mfma_i32_16x16x64_i8 v[114:117], v[170:173], v[192:195], v[114:117]
	v_mfma_i32_16x16x64_i8 v[102:105], v[162:165], v[200:203], v[102:105]
	v_mfma_i32_16x16x64_i8 v[98:101], v[170:173], v[200:203], v[98:101]
	v_mfma_i32_16x16x64_i8 v[86:89], v[162:165], v[208:211], v[86:89]
	v_mfma_i32_16x16x64_i8 v[82:85], v[170:173], v[208:211], v[82:85]
	v_mfma_i32_16x16x64_i8 v[134:137], v[166:169], v[188:191], v[134:137]
	v_mfma_i32_16x16x64_i8 v[130:133], v[180:183], v[188:191], v[130:133]
	v_mfma_i32_16x16x64_i8 v[118:121], v[166:169], v[196:199], v[118:121]
	v_mfma_i32_16x16x64_i8 v[114:117], v[180:183], v[196:199], v[114:117]
	v_mfma_i32_16x16x64_i8 v[102:105], v[166:169], v[204:207], v[102:105]
	v_mfma_i32_16x16x64_i8 v[98:101], v[180:183], v[204:207], v[98:101]
	v_mfma_i32_16x16x64_i8 v[86:89], v[166:169], v[212:215], v[86:89]
	v_mfma_i32_16x16x64_i8 v[82:85], v[180:183], v[212:215], v[82:85]
	s_setprio 0
	s_barrier
	s_add_i32 s36, s40, s68
	s_add_i32 m0, s36, 0xffffff80
	ds_read_b128 v[184:187], v179 offset:49152
	ds_read_b128 v[188:191], v179 offset:50176
	ds_read_b128 v[192:195], v179 offset:51200
	ds_read_b128 v[196:199], v179 offset:52224
	ds_read_b128 v[200:203], v179 offset:53248
	ds_read_b128 v[204:207], v179 offset:54272
	ds_read_b128 v[208:211], v179 offset:55296
	ds_read_b128 v[212:215], v179 offset:56320
	global_load_lds_dwordx4 v148, s[98:99] offset:128
	s_add_i32 m0, s36, 0x1f80
	s_add_u32 s34, s34, 0x80080
	s_addc_u32 s35, s35, 0
	s_add_i32 s36, s41, s68
	global_load_lds_dwordx4 v152, s[98:99] offset:128
	s_mov_b32 m0, s36
	s_nop 0
	global_load_lds_dwordx4 v148, s[34:35]
	s_add_i32 m0, s36, 0x2000
	s_nop 0
	global_load_lds_dwordx4 v152, s[34:35]
	s_add_i32 m0, s92, 0xffffff80
	s_nop 0
	global_load_lds_dwordx4 v146, s[100:101] offset:128
	s_add_i32 m0, s93, 0xffffff80
	s_nop 0
	global_load_lds_dwordx4 v150, s[100:101] offset:128
	s_waitcnt vmcnt(8) lgkmcnt(0)
	s_barrier
	s_setprio 1
	s_waitcnt lgkmcnt(0)
	v_mfma_i32_16x16x64_i8 v[70:73], v[58:61], v[184:187], v[70:73]
	v_mfma_i32_16x16x64_i8 v[66:69], v[74:77], v[184:187], v[66:69]
	v_mfma_i32_16x16x64_i8 v[46:49], v[58:61], v[192:195], v[46:49]
	v_mfma_i32_16x16x64_i8 v[42:45], v[74:77], v[192:195], v[42:45]
	v_mfma_i32_16x16x64_i8 v[30:33], v[58:61], v[200:203], v[30:33]
	v_mfma_i32_16x16x64_i8 v[26:29], v[74:77], v[200:203], v[26:29]
	v_mfma_i32_16x16x64_i8 v[14:17], v[58:61], v[208:211], v[14:17]
	v_mfma_i32_16x16x64_i8 v[10:13], v[74:77], v[208:211], v[10:13]
	v_mfma_i32_16x16x64_i8 v[70:73], v[62:65], v[188:191], v[70:73]
	v_mfma_i32_16x16x64_i8 v[66:69], v[78:81], v[188:191], v[66:69]
	v_mfma_i32_16x16x64_i8 v[46:49], v[62:65], v[196:199], v[46:49]
	v_mfma_i32_16x16x64_i8 v[42:45], v[78:81], v[196:199], v[42:45]
	v_mfma_i32_16x16x64_i8 v[30:33], v[62:65], v[204:207], v[30:33]
	v_mfma_i32_16x16x64_i8 v[26:29], v[78:81], v[204:207], v[26:29]
	v_mfma_i32_16x16x64_i8 v[14:17], v[62:65], v[212:215], v[14:17]
	v_mfma_i32_16x16x64_i8 v[10:13], v[78:81], v[212:215], v[10:13]
	s_setprio 0
	s_setprio 1
	v_mfma_i32_16x16x64_i8 v[54:57], v[162:165], v[184:187], v[54:57]
	v_mfma_i32_16x16x64_i8 v[50:53], v[170:173], v[184:187], v[50:53]
	v_mfma_i32_16x16x64_i8 v[38:41], v[162:165], v[192:195], v[38:41]
	v_mfma_i32_16x16x64_i8 v[34:37], v[170:173], v[192:195], v[34:37]
	v_mfma_i32_16x16x64_i8 v[22:25], v[162:165], v[200:203], v[22:25]
	v_mfma_i32_16x16x64_i8 v[18:21], v[170:173], v[200:203], v[18:21]
	v_mfma_i32_16x16x64_i8 v[6:9], v[162:165], v[208:211], v[6:9]
	v_mfma_i32_16x16x64_i8 v[2:5], v[170:173], v[208:211], v[2:5]
	v_mfma_i32_16x16x64_i8 v[54:57], v[166:169], v[188:191], v[54:57]
	v_mfma_i32_16x16x64_i8 v[50:53], v[180:183], v[188:191], v[50:53]
	v_mfma_i32_16x16x64_i8 v[38:41], v[166:169], v[196:199], v[38:41]
	v_mfma_i32_16x16x64_i8 v[34:37], v[180:183], v[196:199], v[34:37]
	v_mfma_i32_16x16x64_i8 v[22:25], v[166:169], v[204:207], v[22:25]
	v_mfma_i32_16x16x64_i8 v[18:21], v[180:183], v[204:207], v[18:21]
	v_mfma_i32_16x16x64_i8 v[6:9], v[166:169], v[212:215], v[6:9]
	v_mfma_i32_16x16x64_i8 v[2:5], v[180:183], v[212:215], v[2:5]
	s_setprio 0
	s_barrier
	s_add_i32 s39, s39, 2
	s_add_u32 s2, s2, 0x100
	s_addc_u32 s3, s3, 0
	s_add_u32 s31, s31, 0x100
	s_addc_u32 s38, s38, 0
	s_cmp_gt_u32 s39, 29
	s_cbranch_scc0 .LBB0_607
	s_and_b64 vcc, exec, s[20:21]
	s_cbranch_vccz .LBB0_610
	s_barrier

; #define PG8_STAGE(bufoff, gbase, voff) do { _Pragma("unroll") for (int _i = 0; _i < 2; ++_i) \
;         __builtin_amdgcn_global_load_lds((const unsigned*)((const char*)(gbase) + (voff)[_i]), (PG8_LAS unsigned*)(lds + (bufoff) + ldsw + _i * 8192), 16, 0, 0); } while (0)
; #define PG8_LDA(dst, b, h) do { _Pragma("unroll") for (int m = 0; m < 4; ++m) _Pragma("unroll") for (int k = 0; k < 2; ++k) dst[m][k] = *(const PG8_LAS bf16x8*)(lds + PG8_SA(b, h) + aoff + m * 2048 + k * 1024); } while (0)
; #define PG8_LDB(dst, b, h) do { _Pragma("unroll") for (int n = 0; n < 2; ++n) _Pragma("unroll") for (int k = 0; k < 2; ++k) dst[n][k] = *(const PG8_LAS bf16x8*)(lds + PG8_SB(b, h) + boff + n * 2048 + k * 1024); } while (0)
; #define PG8_MMA(ai, bj, At, Bt) do { __builtin_amdgcn_s_setprio(1); _Pragma("unroll") for (int m = 0; m < 4; ++m) _Pragma("unroll") for (int n = 0; n < 2; ++n) _Pragma("unroll") for (int k = 0; k < 2; ++k) \
;         acc[ai][bj][m][n] = mma_<I8>(Bt[n][k], At[m][k], acc[ai][bj][m][n]); __builtin_amdgcn_s_setprio(0); } while (0)
; #define PG8_WAIT_V(n) asm volatile("s_waitcnt vmcnt(" #n ")" ::: "memory")
; #define PG8_WAIT_L(n) asm volatile("s_waitcnt lgkmcnt(" #n ")" ::: "memory")
; #define PG8_BAR __builtin_amdgcn_s_barrier()
; #define PG8_SCHED __builtin_amdgcn_sched_barrier(0)
; template <class Epi, class Sched, bool ALIGN_EPI = false, bool SP2 = false, bool I8 = false>
; __device__ __forceinline__ void gemm_phase(PG8_LAS unsigned char* lds, const Gemm g, const Sched& S, const Epi& E) {
;     ...
;             PG8_LDB(B0, 0, 0); PG8_LDB(B1, 0, 1); PG8_SCHED; PG8_LDA(At, 0, 0); PG8_STAGE(PG8_SA(1, 1), a1 + hstepA, voffA);
;             PG8_WAIT_V(8); PG8_WAIT_L(0); PG8_BAR; PG8_MMA(0, 0, At, B0); PG8_MMA(0, 1, At, B1); PG8_BAR; PG8_SCHED;
;             PG8_LDA(At, 0, 1); PG8_STAGE(PG8_SB(0, 0), b2, voffB); PG8_STAGE(PG8_SB(0, 1), b2 + hstepB, voffB); PG8_STAGE(PG8_SA(0, 0), a2, voffA);
;             PG8_WAIT_V(8); PG8_WAIT_L(0); PG8_BAR; PG8_MMA(1, 0, At, B0); PG8_MMA(1, 1, At, B1); PG8_BAR; PG8_SCHED;
.LBB0_1092:
	ds_read_b128 v[58:61], v172
	ds_read_b128 v[62:65], v172 offset:1024
	ds_read_b128 v[74:77], v172 offset:2048
	ds_read_b128 v[78:81], v172 offset:3072
	ds_read_b128 v[164:167], v173
	ds_read_b128 v[168:171], v173 offset:1024
	ds_read_b128 v[176:179], v173 offset:2048
	ds_read_b128 v[180:183], v173 offset:3072
	s_add_i32 s47, s22, 2
	s_add_u32 s23, s8, 0xfffe0080
	s_addc_u32 s24, s9, -1
	s_cmp_eq_u32 s3, s22
	s_cselect_b32 s22, s20, s17
	s_cselect_b32 s25, s1, s24
	s_cselect_b32 s24, s0, s23
	s_cselect_b32 s23, s21, s19
	s_add_i32 m0, s33, 0xc000
	ds_read_b128 v[184:187], v174
	ds_read_b128 v[188:191], v174 offset:1024
	ds_read_b128 v[192:195], v174 offset:2048
	ds_read_b128 v[196:199], v174 offset:3072
	ds_read_b128 v[200:203], v174 offset:4096
	ds_read_b128 v[204:207], v174 offset:5120
	ds_read_b128 v[208:211], v174 offset:6144
	ds_read_b128 v[212:215], v174 offset:7168
	global_load_lds_dwordx4 v156, s[8:9]
	s_add_i32 m0, s33, 0xe000
	s_nop 0
	global_load_lds_dwordx4 v158, s[8:9]
	s_waitcnt vmcnt(8) lgkmcnt(0)
	s_barrier
	s_setprio 1
	s_waitcnt lgkmcnt(0)
	v_mfma_f32_16x16x32_bf16 v[142:145], v[58:61], v[184:187], v[142:145]
	v_mfma_f32_16x16x32_bf16 v[138:141], v[74:77], v[184:187], v[138:141]
	v_mfma_f32_16x16x32_bf16 v[126:129], v[58:61], v[192:195], v[126:129]
	v_mfma_f32_16x16x32_bf16 v[122:125], v[74:77], v[192:195], v[122:125]
	v_mfma_f32_16x16x32_bf16 v[110:113], v[58:61], v[200:203], v[110:113]
	v_mfma_f32_16x16x32_bf16 v[106:109], v[74:77], v[200:203], v[106:109]
	v_mfma_f32_16x16x32_bf16 v[94:97], v[58:61], v[208:211], v[94:97]
	v_mfma_f32_16x16x32_bf16 v[90:93], v[74:77], v[208:211], v[90:93]
	v_mfma_f32_16x16x32_bf16 v[142:145], v[62:65], v[188:191], v[142:145]
	v_mfma_f32_16x16x32_bf16 v[138:141], v[78:81], v[188:191], v[138:141]
	v_mfma_f32_16x16x32_bf16 v[126:129], v[62:65], v[196:199], v[126:129]
	v_mfma_f32_16x16x32_bf16 v[122:125], v[78:81], v[196:199], v[122:125]
	v_mfma_f32_16x16x32_bf16 v[110:113], v[62:65], v[204:207], v[110:113]
	v_mfma_f32_16x16x32_bf16 v[106:109], v[78:81], v[204:207], v[106:109]
	v_mfma_f32_16x16x32_bf16 v[94:97], v[62:65], v[212:215], v[94:97]
	v_mfma_f32_16x16x32_bf16 v[90:93], v[78:81], v[212:215], v[90:93]
	s_setprio 0
	s_setprio 1
	v_mfma_f32_16x16x32_bf16 v[134:137], v[164:167], v[184:187], v[134:137]
	v_mfma_f32_16x16x32_bf16 v[130:133], v[176:179], v[184:187], v[130:133]
	v_mfma_f32_16x16x32_bf16 v[118:121], v[164:167], v[192:195], v[118:121]
	v_mfma_f32_16x16x32_bf16 v[114:117], v[176:179], v[192:195], v[114:117]
	v_mfma_f32_16x16x32_bf16 v[102:105], v[164:167], v[200:203], v[102:105]
	v_mfma_f32_16x16x32_bf16 v[98:101], v[176:179], v[200:203], v[98:101]
	v_mfma_f32_16x16x32_bf16 v[86:89], v[164:167], v[208:211], v[86:89]
	v_mfma_f32_16x16x32_bf16 v[82:85], v[176:179], v[208:211], v[82:85]
	v_mfma_f32_16x16x32_bf16 v[134:137], v[168:171], v[188:191], v[134:137]
	v_mfma_f32_16x16x32_bf16 v[130:133], v[180:183], v[188:191], v[130:133]
	v_mfma_f32_16x16x32_bf16 v[118:121], v[168:171], v[196:199], v[118:121]
	v_mfma_f32_16x16x32_bf16 v[114:117], v[180:183], v[196:199], v[114:117]
	v_mfma_f32_16x16x32_bf16 v[102:105], v[168:171], v[204:207], v[102:105]
	v_mfma_f32_16x16x32_bf16 v[98:101], v[180:183], v[204:207], v[98:101]
	v_mfma_f32_16x16x32_bf16 v[86:89], v[168:171], v[212:215], v[86:89]
	v_mfma_f32_16x16x32_bf16 v[82:85], v[180:183], v[212:215], v[82:85]
	s_setprio 0
	s_barrier
	s_add_i32 s56, s44, s30
	s_mov_b64 s[98:99], s[22:23]
	s_mov_b32 m0, s56
	ds_read_b128 v[184:187], v174 offset:16384
	ds_read_b128 v[188:191], v174 offset:17408
	ds_read_b128 v[192:195], v174 offset:18432
	ds_read_b128 v[196:199], v174 offset:19456
	ds_read_b128 v[200:203], v174 offset:20480
	ds_read_b128 v[204:207], v174 offset:21504
	ds_read_b128 v[208:211], v174 offset:22528
	ds_read_b128 v[212:215], v174 offset:23552
	global_load_lds_dwordx4 v148, s[22:23]
	s_add_i32 m0, s56, 0x2000
	s_add_u32 s56, s22, 0x20000
	s_mov_b64 s[98:99], s[22:23]
	s_addc_u32 s57, s23, 0
	s_add_i32 s58, s45, s30
	global_load_lds_dwordx4 v152, s[22:23]
	s_mov_b32 m0, s58
	s_mov_b64 s[100:101], s[24:25]
	global_load_lds_dwordx4 v148, s[56:57]
	s_add_i32 m0, s58, 0x2000
	s_nop 0
	global_load_lds_dwordx4 v152, s[56:57]
	s_mov_b64 s[100:101], s[24:25]
	s_mov_b32 m0, s33
	s_nop 0
	global_load_lds_dwordx4 v146, s[24:25]
	s_mov_b32 m0, s34
	s_nop 0
	global_load_lds_dwordx4 v150, s[24:25]
	s_waitcnt vmcnt(8) lgkmcnt(0)
	s_barrier
	s_setprio 1
	s_waitcnt lgkmcnt(0)
	v_mfma_f32_16x16x32_bf16 v[70:73], v[58:61], v[184:187], v[70:73]
	v_mfma_f32_16x16x32_bf16 v[66:69], v[74:77], v[184:187], v[66:69]
	v_mfma_f32_16x16x32_bf16 v[46:49], v[58:61], v[192:195], v[46:49]
	v_mfma_f32_16x16x32_bf16 v[42:45], v[74:77], v[192:195], v[42:45]
	v_mfma_f32_16x16x32_bf16 v[30:33], v[58:61], v[200:203], v[30:33]
	v_mfma_f32_16x16x32_bf16 v[26:29], v[74:77], v[200:203], v[26:29]
	v_mfma_f32_16x16x32_bf16 v[14:17], v[58:61], v[208:211], v[14:17]
	v_mfma_f32_16x16x32_bf16 v[10:13], v[74:77], v[208:211], v[10:13]
	v_mfma_f32_16x16x32_bf16 v[70:73], v[62:65], v[188:191], v[70:73]
	v_mfma_f32_16x16x32_bf16 v[66:69], v[78:81], v[188:191], v[66:69]
	v_mfma_f32_16x16x32_bf16 v[46:49], v[62:65], v[196:199], v[46:49]
	v_mfma_f32_16x16x32_bf16 v[42:45], v[78:81], v[196:199], v[42:45]
	v_mfma_f32_16x16x32_bf16 v[30:33], v[62:65], v[204:207], v[30:33]
	v_mfma_f32_16x16x32_bf16 v[26:29], v[78:81], v[204:207], v[26:29]
	v_mfma_f32_16x16x32_bf16 v[14:17], v[62:65], v[212:215], v[14:17]
	v_mfma_f32_16x16x32_bf16 v[10:13], v[78:81], v[212:215], v[10:13]
	s_setprio 0
	s_setprio 1
	v_mfma_f32_16x16x32_bf16 v[54:57], v[164:167], v[184:187], v[54:57]
	v_mfma_f32_16x16x32_bf16 v[50:53], v[176:179], v[184:187], v[50:53]
	v_mfma_f32_16x16x32_bf16 v[38:41], v[164:167], v[192:195], v[38:41]
	v_mfma_f32_16x16x32_bf16 v[34:37], v[176:179], v[192:195], v[34:37]
	v_mfma_f32_16x16x32_bf16 v[22:25], v[164:167], v[200:203], v[22:25]
	v_mfma_f32_16x16x32_bf16 v[18:21], v[176:179], v[200:203], v[18:21]
	v_mfma_f32_16x16x32_bf16 v[6:9], v[164:167], v[208:211], v[6:9]
	v_mfma_f32_16x16x32_bf16 v[2:5], v[176:179], v[208:211], v[2:5]
	v_mfma_f32_16x16x32_bf16 v[54:57], v[168:171], v[188:191], v[54:57]
	v_mfma_f32_16x16x32_bf16 v[50:53], v[180:183], v[188:191], v[50:53]
	v_mfma_f32_16x16x32_bf16 v[38:41], v[168:171], v[196:199], v[38:41]
	v_mfma_f32_16x16x32_bf16 v[34:37], v[180:183], v[196:199], v[34:37]
	v_mfma_f32_16x16x32_bf16 v[22:25], v[168:171], v[204:207], v[22:25]
	v_mfma_f32_16x16x32_bf16 v[18:21], v[180:183], v[204:207], v[18:21]
	v_mfma_f32_16x16x32_bf16 v[6:9], v[168:171], v[212:215], v[6:9]
	v_mfma_f32_16x16x32_bf16 v[2:5], v[180:183], v[212:215], v[2:5]
	s_setprio 0
	s_barrier
; #define PG8_STAGE(bufoff, gbase, voff) do { _Pragma("unroll") for (int _i = 0; _i < 2; ++_i) \
;         __builtin_amdgcn_global_load_lds((const unsigned*)((const char*)(gbase) + (voff)[_i]), (PG8_LAS unsigned*)(lds + (bufoff) + ldsw + _i * 8192), 16, 0, 0); } while (0)
; #define PG8_LDA(dst, b, h) do { _Pragma("unroll") for (int m = 0; m < 4; ++m) _Pragma("unroll") for (int k = 0; k < 2; ++k) dst[m][k] = *(const PG8_LAS bf16x8*)(lds + PG8_SA(b, h) + aoff + m * 2048 + k * 1024); } while (0)
; #define PG8_LDB(dst, b, h) do { _Pragma("unroll") for (int n = 0; n < 2; ++n) _Pragma("unroll") for (int k = 0; k < 2; ++k) dst[n][k] = *(const PG8_LAS bf16x8*)(lds + PG8_SB(b, h) + boff + n * 2048 + k * 1024); } while (0)
; #define PG8_MMA(ai, bj, At, Bt) do { __builtin_amdgcn_s_setprio(1); _Pragma("unroll") for (int m = 0; m < 4; ++m) _Pragma("unroll") for (int n = 0; n < 2; ++n) _Pragma("unroll") for (int k = 0; k < 2; ++k) \
;         acc[ai][bj][m][n] = mma_<I8>(Bt[n][k], At[m][k], acc[ai][bj][m][n]); __builtin_amdgcn_s_setprio(0); } while (0)
; #define PG8_WAIT_V(n) asm volatile("s_waitcnt vmcnt(" #n ")" ::: "memory")
; #define PG8_WAIT_L(n) asm volatile("s_waitcnt lgkmcnt(" #n ")" ::: "memory")
; #define PG8_BAR __builtin_amdgcn_s_barrier()
; #define PG8_SCHED __builtin_amdgcn_sched_barrier(0)
; template <class Epi, class Sched, bool ALIGN_EPI = false, bool SP2 = false, bool I8 = false>
; __device__ __forceinline__ void gemm_phase(PG8_LAS unsigned char* lds, const Gemm g, const Sched& S, const Epi& E) {
;     ...
;         for (int t = 0; t < nt; t += 2) {
;             const bool last = (t == nt - 2);
;             const char* a1 = cA + (size_t)(t + 1) * kstep;
;             const char* a2 = last ? nA : cA + (size_t)(t + 2) * kstep; const char* b2 = last ? nB : cB + (size_t)(t + 2) * kstep;
;             const char* a3 = a2 + kstep; const char* b3 = b2 + kstep;
;     ...
;             PG8_LDB(B0, 1, 0); PG8_LDB(B1, 1, 1); PG8_SCHED; PG8_LDA(At, 1, 0); PG8_STAGE(PG8_SA(0, 1), a2 + hstepA, voffA);
;             PG8_WAIT_V(8); PG8_WAIT_L(0); PG8_BAR; PG8_MMA(0, 0, At, B0); PG8_MMA(0, 1, At, B1); PG8_BAR; PG8_SCHED;
;             PG8_LDA(At, 1, 1); PG8_STAGE(PG8_SB(1, 0), b3, voffB); PG8_STAGE(PG8_SB(1, 1), b3 + hstepB, voffB); PG8_STAGE(PG8_SA(1, 0), a3, voffA);
;             PG8_WAIT_V(8); PG8_WAIT_L(0); PG8_BAR; PG8_MMA(1, 0, At, B0); PG8_MMA(1, 1, At, B1); PG8_BAR; PG8_SCHED;
	s_add_i32 s56, 0, 0x18000
	s_add_i32 s57, 0, 0x1c000
	v_add_u32_e32 v78, s56, v1
	v_add_u32_e32 v154, s57, v1
	ds_read_b128 v[58:61], v78
	ds_read_b128 v[62:65], v78 offset:1024
	ds_read_b128 v[74:77], v78 offset:2048
	ds_read_b128 v[78:81], v78 offset:3072
	ds_read_b128 v[164:167], v154
	ds_read_b128 v[168:171], v154 offset:1024
	ds_read_b128 v[176:179], v154 offset:2048
	ds_read_b128 v[180:183], v154 offset:3072
	s_add_u32 s24, s24, 0x20000
	s_addc_u32 s25, s25, 0
	s_mov_b32 m0, s35
	ds_read_b128 v[184:187], v174 offset:32768
	ds_read_b128 v[188:191], v174 offset:33792
	ds_read_b128 v[192:195], v174 offset:34816
	ds_read_b128 v[196:199], v174 offset:35840
	ds_read_b128 v[200:203], v174 offset:36864
	ds_read_b128 v[204:207], v174 offset:37888
	ds_read_b128 v[208:211], v174 offset:38912
	ds_read_b128 v[212:215], v174 offset:39936
	global_load_lds_dwordx4 v146, s[24:25]
	s_mov_b32 m0, s36
	s_nop 0
	global_load_lds_dwordx4 v150, s[24:25]
	s_waitcnt vmcnt(8) lgkmcnt(0)
	s_barrier
	s_setprio 1
	s_waitcnt lgkmcnt(0)
	v_mfma_f32_16x16x32_bf16 v[142:145], v[58:61], v[184:187], v[142:145]
	v_mfma_f32_16x16x32_bf16 v[138:141], v[74:77], v[184:187], v[138:141]
	v_mfma_f32_16x16x32_bf16 v[126:129], v[58:61], v[192:195], v[126:129]
	v_mfma_f32_16x16x32_bf16 v[122:125], v[74:77], v[192:195], v[122:125]
	v_mfma_f32_16x16x32_bf16 v[110:113], v[58:61], v[200:203], v[110:113]
	v_mfma_f32_16x16x32_bf16 v[106:109], v[74:77], v[200:203], v[106:109]
	v_mfma_f32_16x16x32_bf16 v[94:97], v[58:61], v[208:211], v[94:97]
	v_mfma_f32_16x16x32_bf16 v[90:93], v[74:77], v[208:211], v[90:93]
	v_mfma_f32_16x16x32_bf16 v[142:145], v[62:65], v[188:191], v[142:145]
	v_mfma_f32_16x16x32_bf16 v[138:141], v[78:81], v[188:191], v[138:141]
	v_mfma_f32_16x16x32_bf16 v[126:129], v[62:65], v[196:199], v[126:129]
	v_mfma_f32_16x16x32_bf16 v[122:125], v[78:81], v[196:199], v[122:125]
	v_mfma_f32_16x16x32_bf16 v[110:113], v[62:65], v[204:207], v[110:113]
	v_mfma_f32_16x16x32_bf16 v[106:109], v[78:81], v[204:207], v[106:109]
	v_mfma_f32_16x16x32_bf16 v[94:97], v[62:65], v[212:215], v[94:97]
	v_mfma_f32_16x16x32_bf16 v[90:93], v[78:81], v[212:215], v[90:93]
	s_setprio 0
	s_setprio 1
	v_mfma_f32_16x16x32_bf16 v[134:137], v[164:167], v[184:187], v[134:137]
	v_mfma_f32_16x16x32_bf16 v[130:133], v[176:179], v[184:187], v[130:133]
	v_mfma_f32_16x16x32_bf16 v[118:121], v[164:167], v[192:195], v[118:121]
	v_mfma_f32_16x16x32_bf16 v[114:117], v[176:179], v[192:195], v[114:117]
	v_mfma_f32_16x16x32_bf16 v[102:105], v[164:167], v[200:203], v[102:105]
	v_mfma_f32_16x16x32_bf16 v[98:101], v[176:179], v[200:203], v[98:101]
	v_mfma_f32_16x16x32_bf16 v[86:89], v[164:167], v[208:211], v[86:89]
	v_mfma_f32_16x16x32_bf16 v[82:85], v[176:179], v[208:211], v[82:85]
	v_mfma_f32_16x16x32_bf16 v[134:137], v[168:171], v[188:191], v[134:137]
	v_mfma_f32_16x16x32_bf16 v[130:133], v[180:183], v[188:191], v[130:133]
	v_mfma_f32_16x16x32_bf16 v[118:121], v[168:171], v[196:199], v[118:121]
	v_mfma_f32_16x16x32_bf16 v[114:117], v[180:183], v[196:199], v[114:117]
	v_mfma_f32_16x16x32_bf16 v[102:105], v[168:171], v[204:207], v[102:105]
	v_mfma_f32_16x16x32_bf16 v[98:101], v[180:183], v[204:207], v[98:101]
	v_mfma_f32_16x16x32_bf16 v[86:89], v[168:171], v[212:215], v[86:89]
	v_mfma_f32_16x16x32_bf16 v[82:85], v[180:183], v[212:215], v[82:85]
	s_setprio 0
	s_barrier
	s_add_i32 s24, s56, s30
	s_add_i32 m0, s24, 0xffffff80
	ds_read_b128 v[184:187], v174 offset:49152
	ds_read_b128 v[188:191], v174 offset:50176
	ds_read_b128 v[192:195], v174 offset:51200
	ds_read_b128 v[196:199], v174 offset:52224
	ds_read_b128 v[200:203], v174 offset:53248
	ds_read_b128 v[204:207], v174 offset:54272
	ds_read_b128 v[208:211], v174 offset:55296
	ds_read_b128 v[212:215], v174 offset:56320
	global_load_lds_dwordx4 v148, s[98:99] offset:128
	s_add_i32 m0, s24, 0x1f80
	s_add_u32 s22, s22, 0x20080
	s_addc_u32 s23, s23, 0
	s_add_i32 s24, s57, s30
	global_load_lds_dwordx4 v152, s[98:99] offset:128
	s_mov_b32 m0, s24
	s_nop 0
	global_load_lds_dwordx4 v148, s[22:23]
	s_add_i32 m0, s24, 0x2000
	s_nop 0
	global_load_lds_dwordx4 v152, s[22:23]
	s_add_i32 m0, s40, 0xffffff80
	s_nop 0
	global_load_lds_dwordx4 v146, s[100:101] offset:128
	s_add_i32 m0, s41, 0xffffff80
	s_nop 0
	global_load_lds_dwordx4 v150, s[100:101] offset:128
	s_waitcnt vmcnt(8) lgkmcnt(0)
	s_barrier
	s_setprio 1
	s_waitcnt lgkmcnt(0)
	v_mfma_f32_16x16x32_bf16 v[70:73], v[58:61], v[184:187], v[70:73]
	v_mfma_f32_16x16x32_bf16 v[66:69], v[74:77], v[184:187], v[66:69]
	v_mfma_f32_16x16x32_bf16 v[46:49], v[58:61], v[192:195], v[46:49]
	v_mfma_f32_16x16x32_bf16 v[42:45], v[74:77], v[192:195], v[42:45]
	v_mfma_f32_16x16x32_bf16 v[30:33], v[58:61], v[200:203], v[30:33]
	v_mfma_f32_16x16x32_bf16 v[26:29], v[74:77], v[200:203], v[26:29]
	v_mfma_f32_16x16x32_bf16 v[14:17], v[58:61], v[208:211], v[14:17]
	v_mfma_f32_16x16x32_bf16 v[10:13], v[74:77], v[208:211], v[10:13]
	v_mfma_f32_16x16x32_bf16 v[70:73], v[62:65], v[188:191], v[70:73]
	v_mfma_f32_16x16x32_bf16 v[66:69], v[78:81], v[188:191], v[66:69]
	v_mfma_f32_16x16x32_bf16 v[46:49], v[62:65], v[196:199], v[46:49]
	v_mfma_f32_16x16x32_bf16 v[42:45], v[78:81], v[196:199], v[42:45]
	v_mfma_f32_16x16x32_bf16 v[30:33], v[62:65], v[204:207], v[30:33]
	v_mfma_f32_16x16x32_bf16 v[26:29], v[78:81], v[204:207], v[26:29]
	v_mfma_f32_16x16x32_bf16 v[14:17], v[62:65], v[212:215], v[14:17]
	v_mfma_f32_16x16x32_bf16 v[10:13], v[78:81], v[212:215], v[10:13]
	s_setprio 0
	s_setprio 1
	v_mfma_f32_16x16x32_bf16 v[54:57], v[164:167], v[184:187], v[54:57]
	v_mfma_f32_16x16x32_bf16 v[50:53], v[176:179], v[184:187], v[50:53]
	v_mfma_f32_16x16x32_bf16 v[38:41], v[164:167], v[192:195], v[38:41]
	v_mfma_f32_16x16x32_bf16 v[34:37], v[176:179], v[192:195], v[34:37]
	v_mfma_f32_16x16x32_bf16 v[22:25], v[164:167], v[200:203], v[22:25]
	v_mfma_f32_16x16x32_bf16 v[18:21], v[176:179], v[200:203], v[18:21]
	v_mfma_f32_16x16x32_bf16 v[6:9], v[164:167], v[208:211], v[6:9]
	v_mfma_f32_16x16x32_bf16 v[2:5], v[176:179], v[208:211], v[2:5]
	v_mfma_f32_16x16x32_bf16 v[54:57], v[168:171], v[188:191], v[54:57]
	v_mfma_f32_16x16x32_bf16 v[50:53], v[180:183], v[188:191], v[50:53]
	v_mfma_f32_16x16x32_bf16 v[38:41], v[168:171], v[196:199], v[38:41]
	v_mfma_f32_16x16x32_bf16 v[34:37], v[180:183], v[196:199], v[34:37]
	v_mfma_f32_16x16x32_bf16 v[22:25], v[168:171], v[204:207], v[22:25]
	v_mfma_f32_16x16x32_bf16 v[18:21], v[180:183], v[204:207], v[18:21]
	v_mfma_f32_16x16x32_bf16 v[6:9], v[168:171], v[212:215], v[6:9]
	v_mfma_f32_16x16x32_bf16 v[2:5], v[180:183], v[212:215], v[2:5]
	s_setprio 0
	s_barrier
	s_add_u32 s8, s8, 0x100
	s_addc_u32 s9, s9, 0
	s_add_u32 s17, s17, 0x100
	s_addc_u32 s19, s19, 0
	s_cmp_ge_u32 s47, s7
	s_mov_b32 s22, s47
	s_cbranch_scc0 .LBB0_1092
	s_and_b64 vcc, exec, s[14:15]
	s_cbranch_vccz .LBB0_1095
	s_barrier

; #define PG8_STAGE(bufoff, gbase, voff) do { _Pragma("unroll") for (int _i = 0; _i < 2; ++_i) \
;         __builtin_amdgcn_global_load_lds((const unsigned*)((const char*)(gbase) + (voff)[_i]), (PG8_LAS unsigned*)(lds + (bufoff) + ldsw + _i * 8192), 16, 0, 0); } while (0)
; #define PG8_LDA(dst, b, h) do { _Pragma("unroll") for (int m = 0; m < 4; ++m) _Pragma("unroll") for (int k = 0; k < 2; ++k) dst[m][k] = *(const PG8_LAS bf16x8*)(lds + PG8_SA(b, h) + aoff + m * 2048 + k * 1024); } while (0)
; #define PG8_LDB(dst, b, h) do { _Pragma("unroll") for (int n = 0; n < 2; ++n) _Pragma("unroll") for (int k = 0; k < 2; ++k) dst[n][k] = *(const PG8_LAS bf16x8*)(lds + PG8_SB(b, h) + boff + n * 2048 + k * 1024); } while (0)
; #define PG8_MMA(ai, bj, At, Bt) do { __builtin_amdgcn_s_setprio(1); _Pragma("unroll") for (int m = 0; m < 4; ++m) _Pragma("unroll") for (int n = 0; n < 2; ++n) _Pragma("unroll") for (int k = 0; k < 2; ++k) \
;         acc[ai][bj][m][n] = mma_<I8>(Bt[n][k], At[m][k], acc[ai][bj][m][n]); __builtin_amdgcn_s_setprio(0); } while (0)
; #define PG8_WAIT_V(n) asm volatile("s_waitcnt vmcnt(" #n ")" ::: "memory")
; #define PG8_WAIT_L(n) asm volatile("s_waitcnt lgkmcnt(" #n ")" ::: "memory")
; #define PG8_BAR __builtin_amdgcn_s_barrier()
; #define PG8_SCHED __builtin_amdgcn_sched_barrier(0)
; template <class Epi, class Sched, bool ALIGN_EPI = false, bool SP2 = false, bool I8 = false>
; __device__ __forceinline__ void gemm_phase(PG8_LAS unsigned char* lds, const Gemm g, const Sched& S, const Epi& E) {
;     ...
;             PG8_LDB(B0, 0, 0); PG8_LDB(B1, 0, 1); PG8_SCHED; PG8_LDA(At, 0, 0); PG8_STAGE(PG8_SA(1, 1), a1 + hstepA, voffA);
;             PG8_WAIT_V(8); PG8_WAIT_L(0); PG8_BAR; PG8_MMA(0, 0, At, B0); PG8_MMA(0, 1, At, B1); PG8_BAR; PG8_SCHED;
;             PG8_LDA(At, 0, 1); PG8_STAGE(PG8_SB(0, 0), b2, voffB); PG8_STAGE(PG8_SB(0, 1), b2 + hstepB, voffB); PG8_STAGE(PG8_SA(0, 0), a2, voffA);
;             PG8_WAIT_V(8); PG8_WAIT_L(0); PG8_BAR; PG8_MMA(1, 0, At, B0); PG8_MMA(1, 1, At, B1); PG8_BAR; PG8_SCHED;
.LBB0_1538:
	ds_read_b128 v[146:149], v154
	ds_read_b128 v[150:153], v154 offset:1024
	ds_read_b128 v[158:161], v154 offset:2048
	ds_read_b128 v[162:165], v154 offset:3072
	ds_read_b128 v[166:169], v155
	ds_read_b128 v[170:173], v155 offset:1024
	ds_read_b128 v[174:177], v155 offset:2048
	ds_read_b128 v[178:181], v155 offset:3072
	s_add_u32 s24, s22, 0xfffe0080
	s_addc_u32 s25, s23, -1
	s_cmp_eq_u32 s49, 4
	s_cselect_b32 s27, s15, s25
	s_cselect_b32 s26, s45, s24
	s_cselect_b32 s25, s13, s48
	s_cselect_b32 s24, s46, s47
	s_add_i32 m0, s21, 0xc000
	ds_read_b128 v[182:185], v156
	ds_read_b128 v[186:189], v156 offset:1024
	ds_read_b128 v[190:193], v156 offset:2048
	ds_read_b128 v[194:197], v156 offset:3072
	ds_read_b128 v[198:201], v156 offset:4096
	ds_read_b128 v[202:205], v156 offset:5120
	ds_read_b128 v[206:209], v156 offset:6144
	ds_read_b128 v[210:213], v156 offset:7168
	global_load_lds_dwordx4 v138, s[22:23]
	s_add_i32 m0, s21, 0xe000
	s_nop 0
	global_load_lds_dwordx4 v140, s[22:23]
	s_waitcnt vmcnt(8) lgkmcnt(0)
	s_barrier
	s_setprio 1
	s_waitcnt lgkmcnt(0)
	v_mfma_f32_16x16x32_bf16 v[126:129], v[146:149], v[182:185], v[126:129]
	v_mfma_f32_16x16x32_bf16 v[122:125], v[158:161], v[182:185], v[122:125]
	v_mfma_f32_16x16x32_bf16 v[114:117], v[146:149], v[190:193], v[114:117]
	v_mfma_f32_16x16x32_bf16 v[106:109], v[158:161], v[190:193], v[106:109]
	v_mfma_f32_16x16x32_bf16 v[94:97], v[146:149], v[198:201], v[94:97]
	v_mfma_f32_16x16x32_bf16 v[90:93], v[158:161], v[198:201], v[90:93]
	v_mfma_f32_16x16x32_bf16 v[86:89], v[146:149], v[206:209], v[86:89]
	v_mfma_f32_16x16x32_bf16 v[82:85], v[158:161], v[206:209], v[82:85]
	v_mfma_f32_16x16x32_bf16 v[126:129], v[150:153], v[186:189], v[126:129]
	v_mfma_f32_16x16x32_bf16 v[122:125], v[162:165], v[186:189], v[122:125]
	v_mfma_f32_16x16x32_bf16 v[114:117], v[150:153], v[194:197], v[114:117]
	v_mfma_f32_16x16x32_bf16 v[106:109], v[162:165], v[194:197], v[106:109]
	v_mfma_f32_16x16x32_bf16 v[94:97], v[150:153], v[202:205], v[94:97]
	v_mfma_f32_16x16x32_bf16 v[90:93], v[162:165], v[202:205], v[90:93]
	v_mfma_f32_16x16x32_bf16 v[86:89], v[150:153], v[210:213], v[86:89]
	v_mfma_f32_16x16x32_bf16 v[82:85], v[162:165], v[210:213], v[82:85]
	s_setprio 0
	s_setprio 1
	v_mfma_f32_16x16x32_bf16 v[118:121], v[166:169], v[182:185], v[118:121]
	v_mfma_f32_16x16x32_bf16 v[110:113], v[174:177], v[182:185], v[110:113]
	v_mfma_f32_16x16x32_bf16 v[102:105], v[166:169], v[190:193], v[102:105]
	v_mfma_f32_16x16x32_bf16 v[98:101], v[174:177], v[190:193], v[98:101]
	v_mfma_f32_16x16x32_bf16 v[78:81], v[166:169], v[198:201], v[78:81]
	v_mfma_f32_16x16x32_bf16 v[74:77], v[174:177], v[198:201], v[74:77]
	v_mfma_f32_16x16x32_bf16 v[70:73], v[166:169], v[206:209], v[70:73]
	v_mfma_f32_16x16x32_bf16 v[66:69], v[174:177], v[206:209], v[66:69]
	v_mfma_f32_16x16x32_bf16 v[118:121], v[170:173], v[186:189], v[118:121]
	v_mfma_f32_16x16x32_bf16 v[110:113], v[178:181], v[186:189], v[110:113]
	v_mfma_f32_16x16x32_bf16 v[102:105], v[170:173], v[194:197], v[102:105]
	v_mfma_f32_16x16x32_bf16 v[98:101], v[178:181], v[194:197], v[98:101]
	v_mfma_f32_16x16x32_bf16 v[78:81], v[170:173], v[202:205], v[78:81]
	v_mfma_f32_16x16x32_bf16 v[74:77], v[178:181], v[202:205], v[74:77]
	v_mfma_f32_16x16x32_bf16 v[70:73], v[170:173], v[210:213], v[70:73]
	v_mfma_f32_16x16x32_bf16 v[66:69], v[178:181], v[210:213], v[66:69]
	s_setprio 0
	s_barrier
	s_add_i32 s50, s42, s34
	s_mov_b64 s[98:99], s[24:25]
	s_mov_b32 m0, s50
	ds_read_b128 v[182:185], v156 offset:16384
	ds_read_b128 v[186:189], v156 offset:17408
	ds_read_b128 v[190:193], v156 offset:18432
	ds_read_b128 v[194:197], v156 offset:19456
	ds_read_b128 v[198:201], v156 offset:20480
	ds_read_b128 v[202:205], v156 offset:21504
	ds_read_b128 v[206:209], v156 offset:22528
	ds_read_b128 v[210:213], v156 offset:23552
	global_load_lds_dwordx4 v132, s[24:25]
	s_add_i32 m0, s50, 0x2000
	s_add_u32 s50, s24, 0x20000
	s_mov_b64 s[98:99], s[24:25]
	s_addc_u32 s51, s25, 0
	s_add_i32 s52, s43, s34
	global_load_lds_dwordx4 v136, s[24:25]
	s_mov_b32 m0, s52
	s_mov_b64 s[100:101], s[26:27]
	global_load_lds_dwordx4 v132, s[50:51]
	s_add_i32 m0, s52, 0x2000
	s_nop 0
	global_load_lds_dwordx4 v136, s[50:51]
	s_mov_b64 s[100:101], s[26:27]
	s_mov_b32 m0, s21
	s_nop 0
	global_load_lds_dwordx4 v130, s[26:27]
	s_mov_b32 m0, s35
	s_nop 0
	global_load_lds_dwordx4 v134, s[26:27]
	s_waitcnt vmcnt(8) lgkmcnt(0)
	s_barrier
	s_setprio 1
	s_waitcnt lgkmcnt(0)
	v_mfma_f32_16x16x32_bf16 v[62:65], v[146:149], v[182:185], v[62:65]
	v_mfma_f32_16x16x32_bf16 v[58:61], v[158:161], v[182:185], v[58:61]
	v_mfma_f32_16x16x32_bf16 v[54:57], v[146:149], v[190:193], v[54:57]
	v_mfma_f32_16x16x32_bf16 v[50:53], v[158:161], v[190:193], v[50:53]
	v_mfma_f32_16x16x32_bf16 v[30:33], v[146:149], v[198:201], v[30:33]
	v_mfma_f32_16x16x32_bf16 v[26:29], v[158:161], v[198:201], v[26:29]
	v_mfma_f32_16x16x32_bf16 v[22:25], v[146:149], v[206:209], v[22:25]
	v_mfma_f32_16x16x32_bf16 v[10:13], v[158:161], v[206:209], v[10:13]
	v_mfma_f32_16x16x32_bf16 v[62:65], v[150:153], v[186:189], v[62:65]
	v_mfma_f32_16x16x32_bf16 v[58:61], v[162:165], v[186:189], v[58:61]
	v_mfma_f32_16x16x32_bf16 v[54:57], v[150:153], v[194:197], v[54:57]
	v_mfma_f32_16x16x32_bf16 v[50:53], v[162:165], v[194:197], v[50:53]
	v_mfma_f32_16x16x32_bf16 v[30:33], v[150:153], v[202:205], v[30:33]
	v_mfma_f32_16x16x32_bf16 v[26:29], v[162:165], v[202:205], v[26:29]
	v_mfma_f32_16x16x32_bf16 v[22:25], v[150:153], v[210:213], v[22:25]
	v_mfma_f32_16x16x32_bf16 v[10:13], v[162:165], v[210:213], v[10:13]
	s_setprio 0
	s_setprio 1
	v_mfma_f32_16x16x32_bf16 v[46:49], v[166:169], v[182:185], v[46:49]
	v_mfma_f32_16x16x32_bf16 v[42:45], v[174:177], v[182:185], v[42:45]
	v_mfma_f32_16x16x32_bf16 v[38:41], v[166:169], v[190:193], v[38:41]
	v_mfma_f32_16x16x32_bf16 v[34:37], v[174:177], v[190:193], v[34:37]
	v_mfma_f32_16x16x32_bf16 v[18:21], v[166:169], v[198:201], v[18:21]
	v_mfma_f32_16x16x32_bf16 v[14:17], v[174:177], v[198:201], v[14:17]
	v_mfma_f32_16x16x32_bf16 v[6:9], v[166:169], v[206:209], v[6:9]
	v_mfma_f32_16x16x32_bf16 v[2:5], v[174:177], v[206:209], v[2:5]
	v_mfma_f32_16x16x32_bf16 v[46:49], v[170:173], v[186:189], v[46:49]
	v_mfma_f32_16x16x32_bf16 v[42:45], v[178:181], v[186:189], v[42:45]
	v_mfma_f32_16x16x32_bf16 v[38:41], v[170:173], v[194:197], v[38:41]
	v_mfma_f32_16x16x32_bf16 v[34:37], v[178:181], v[194:197], v[34:37]
	v_mfma_f32_16x16x32_bf16 v[18:21], v[170:173], v[202:205], v[18:21]
	v_mfma_f32_16x16x32_bf16 v[14:17], v[178:181], v[202:205], v[14:17]
	v_mfma_f32_16x16x32_bf16 v[6:9], v[170:173], v[210:213], v[6:9]
	v_mfma_f32_16x16x32_bf16 v[2:5], v[178:181], v[210:213], v[2:5]
	s_setprio 0
	s_barrier
; #define PG8_STAGE(bufoff, gbase, voff) do { _Pragma("unroll") for (int _i = 0; _i < 2; ++_i) \
;         __builtin_amdgcn_global_load_lds((const unsigned*)((const char*)(gbase) + (voff)[_i]), (PG8_LAS unsigned*)(lds + (bufoff) + ldsw + _i * 8192), 16, 0, 0); } while (0)
; #define PG8_LDA(dst, b, h) do { _Pragma("unroll") for (int m = 0; m < 4; ++m) _Pragma("unroll") for (int k = 0; k < 2; ++k) dst[m][k] = *(const PG8_LAS bf16x8*)(lds + PG8_SA(b, h) + aoff + m * 2048 + k * 1024); } while (0)
; #define PG8_LDB(dst, b, h) do { _Pragma("unroll") for (int n = 0; n < 2; ++n) _Pragma("unroll") for (int k = 0; k < 2; ++k) dst[n][k] = *(const PG8_LAS bf16x8*)(lds + PG8_SB(b, h) + boff + n * 2048 + k * 1024); } while (0)
; #define PG8_MMA(ai, bj, At, Bt) do { __builtin_amdgcn_s_setprio(1); _Pragma("unroll") for (int m = 0; m < 4; ++m) _Pragma("unroll") for (int n = 0; n < 2; ++n) _Pragma("unroll") for (int k = 0; k < 2; ++k) \
;         acc[ai][bj][m][n] = mma_<I8>(Bt[n][k], At[m][k], acc[ai][bj][m][n]); __builtin_amdgcn_s_setprio(0); } while (0)
; #define PG8_WAIT_V(n) asm volatile("s_waitcnt vmcnt(" #n ")" ::: "memory")
; #define PG8_WAIT_L(n) asm volatile("s_waitcnt lgkmcnt(" #n ")" ::: "memory")
; #define PG8_BAR __builtin_amdgcn_s_barrier()
; #define PG8_SCHED __builtin_amdgcn_sched_barrier(0)
; template <class Epi, class Sched, bool ALIGN_EPI = false, bool SP2 = false, bool I8 = false>
; __device__ __forceinline__ void gemm_phase(PG8_LAS unsigned char* lds, const Gemm g, const Sched& S, const Epi& E) {
;     ...
;         for (int t = 0; t < nt; t += 2) {
;             const bool last = (t == nt - 2);
;             const char* a1 = cA + (size_t)(t + 1) * kstep;
;             const char* a2 = last ? nA : cA + (size_t)(t + 2) * kstep; const char* b2 = last ? nB : cB + (size_t)(t + 2) * kstep;
;             const char* a3 = a2 + kstep; const char* b3 = b2 + kstep;
;     ...
;             PG8_LDB(B0, 1, 0); PG8_LDB(B1, 1, 1); PG8_SCHED; PG8_LDA(At, 1, 0); PG8_STAGE(PG8_SA(0, 1), a2 + hstepA, voffA);
;             PG8_WAIT_V(8); PG8_WAIT_L(0); PG8_BAR; PG8_MMA(0, 0, At, B0); PG8_MMA(0, 1, At, B1); PG8_BAR; PG8_SCHED;
;             PG8_LDA(At, 1, 1); PG8_STAGE(PG8_SB(1, 0), b3, voffB); PG8_STAGE(PG8_SB(1, 1), b3 + hstepB, voffB); PG8_STAGE(PG8_SA(1, 0), a3, voffA);
;             PG8_WAIT_V(8); PG8_WAIT_L(0); PG8_BAR; PG8_MMA(1, 0, At, B0); PG8_MMA(1, 1, At, B1); PG8_BAR; PG8_SCHED;
	s_add_i32 s50, 0, 0x18000
	v_add_u32_e32 v157, s50, v1
	s_add_i32 s51, 0, 0x1c000
	ds_read_b128 v[146:149], v157
	ds_read_b128 v[150:153], v157 offset:1024
	ds_read_b128 v[158:161], v157 offset:2048
	ds_read_b128 v[162:165], v157 offset:3072
	v_add_u32_e32 v157, s51, v1
	ds_read_b128 v[166:169], v157
	ds_read_b128 v[170:173], v157 offset:1024
	ds_read_b128 v[174:177], v157 offset:2048
	ds_read_b128 v[178:181], v157 offset:3072
	s_add_u32 s26, s26, 0x20000
	s_addc_u32 s27, s27, 0
	s_mov_b32 m0, s36
	ds_read_b128 v[182:185], v156 offset:32768
	ds_read_b128 v[186:189], v156 offset:33792
	ds_read_b128 v[190:193], v156 offset:34816
	ds_read_b128 v[194:197], v156 offset:35840
	ds_read_b128 v[198:201], v156 offset:36864
	ds_read_b128 v[202:205], v156 offset:37888
	ds_read_b128 v[206:209], v156 offset:38912
	ds_read_b128 v[210:213], v156 offset:39936
	global_load_lds_dwordx4 v130, s[26:27]
	s_mov_b32 m0, s37
	s_nop 0
	global_load_lds_dwordx4 v134, s[26:27]
	s_waitcnt vmcnt(8) lgkmcnt(0)
	s_barrier
	s_setprio 1
	s_waitcnt lgkmcnt(0)
	v_mfma_f32_16x16x32_bf16 v[126:129], v[146:149], v[182:185], v[126:129]
	v_mfma_f32_16x16x32_bf16 v[122:125], v[158:161], v[182:185], v[122:125]
	v_mfma_f32_16x16x32_bf16 v[114:117], v[146:149], v[190:193], v[114:117]
	v_mfma_f32_16x16x32_bf16 v[106:109], v[158:161], v[190:193], v[106:109]
	v_mfma_f32_16x16x32_bf16 v[94:97], v[146:149], v[198:201], v[94:97]
	v_mfma_f32_16x16x32_bf16 v[90:93], v[158:161], v[198:201], v[90:93]
	v_mfma_f32_16x16x32_bf16 v[86:89], v[146:149], v[206:209], v[86:89]
	v_mfma_f32_16x16x32_bf16 v[82:85], v[158:161], v[206:209], v[82:85]
	v_mfma_f32_16x16x32_bf16 v[126:129], v[150:153], v[186:189], v[126:129]
	v_mfma_f32_16x16x32_bf16 v[122:125], v[162:165], v[186:189], v[122:125]
	v_mfma_f32_16x16x32_bf16 v[114:117], v[150:153], v[194:197], v[114:117]
	v_mfma_f32_16x16x32_bf16 v[106:109], v[162:165], v[194:197], v[106:109]
	v_mfma_f32_16x16x32_bf16 v[94:97], v[150:153], v[202:205], v[94:97]
	v_mfma_f32_16x16x32_bf16 v[90:93], v[162:165], v[202:205], v[90:93]
	v_mfma_f32_16x16x32_bf16 v[86:89], v[150:153], v[210:213], v[86:89]
	v_mfma_f32_16x16x32_bf16 v[82:85], v[162:165], v[210:213], v[82:85]
	s_setprio 0
	s_setprio 1
	v_mfma_f32_16x16x32_bf16 v[118:121], v[166:169], v[182:185], v[118:121]
	v_mfma_f32_16x16x32_bf16 v[110:113], v[174:177], v[182:185], v[110:113]
	v_mfma_f32_16x16x32_bf16 v[102:105], v[166:169], v[190:193], v[102:105]
	v_mfma_f32_16x16x32_bf16 v[98:101], v[174:177], v[190:193], v[98:101]
	v_mfma_f32_16x16x32_bf16 v[78:81], v[166:169], v[198:201], v[78:81]
	v_mfma_f32_16x16x32_bf16 v[74:77], v[174:177], v[198:201], v[74:77]
	v_mfma_f32_16x16x32_bf16 v[70:73], v[166:169], v[206:209], v[70:73]
	v_mfma_f32_16x16x32_bf16 v[66:69], v[174:177], v[206:209], v[66:69]
	v_mfma_f32_16x16x32_bf16 v[118:121], v[170:173], v[186:189], v[118:121]
	v_mfma_f32_16x16x32_bf16 v[110:113], v[178:181], v[186:189], v[110:113]
	v_mfma_f32_16x16x32_bf16 v[102:105], v[170:173], v[194:197], v[102:105]
	v_mfma_f32_16x16x32_bf16 v[98:101], v[178:181], v[194:197], v[98:101]
	v_mfma_f32_16x16x32_bf16 v[78:81], v[170:173], v[202:205], v[78:81]
	v_mfma_f32_16x16x32_bf16 v[74:77], v[178:181], v[202:205], v[74:77]
	v_mfma_f32_16x16x32_bf16 v[70:73], v[170:173], v[210:213], v[70:73]
	v_mfma_f32_16x16x32_bf16 v[66:69], v[178:181], v[210:213], v[66:69]
	s_setprio 0
	s_barrier
	s_add_i32 s26, s50, s34
	s_add_i32 m0, s26, 0xffffff80
	ds_read_b128 v[182:185], v156 offset:49152
	ds_read_b128 v[186:189], v156 offset:50176
	ds_read_b128 v[190:193], v156 offset:51200
	ds_read_b128 v[194:197], v156 offset:52224
	ds_read_b128 v[198:201], v156 offset:53248
	ds_read_b128 v[202:205], v156 offset:54272
	ds_read_b128 v[206:209], v156 offset:55296
	ds_read_b128 v[210:213], v156 offset:56320
	global_load_lds_dwordx4 v132, s[98:99] offset:128
	s_add_i32 m0, s26, 0x1f80
	s_add_u32 s24, s24, 0x20080
	s_addc_u32 s25, s25, 0
	s_add_i32 s26, s51, s34
	global_load_lds_dwordx4 v136, s[98:99] offset:128
	s_mov_b32 m0, s26
	s_nop 0
	global_load_lds_dwordx4 v132, s[24:25]
	s_add_i32 m0, s26, 0x2000
	s_nop 0
	global_load_lds_dwordx4 v136, s[24:25]
	s_add_i32 m0, s39, 0xffffff80
	s_nop 0
	global_load_lds_dwordx4 v130, s[100:101] offset:128
	s_add_i32 m0, s40, 0xffffff80
	s_nop 0
	global_load_lds_dwordx4 v134, s[100:101] offset:128
	s_waitcnt vmcnt(8) lgkmcnt(0)
	s_barrier
	s_setprio 1
	s_waitcnt lgkmcnt(0)
	v_mfma_f32_16x16x32_bf16 v[62:65], v[146:149], v[182:185], v[62:65]
	v_mfma_f32_16x16x32_bf16 v[58:61], v[158:161], v[182:185], v[58:61]
	v_mfma_f32_16x16x32_bf16 v[54:57], v[146:149], v[190:193], v[54:57]
	v_mfma_f32_16x16x32_bf16 v[50:53], v[158:161], v[190:193], v[50:53]
	v_mfma_f32_16x16x32_bf16 v[30:33], v[146:149], v[198:201], v[30:33]
	v_mfma_f32_16x16x32_bf16 v[26:29], v[158:161], v[198:201], v[26:29]
	v_mfma_f32_16x16x32_bf16 v[22:25], v[146:149], v[206:209], v[22:25]
	v_mfma_f32_16x16x32_bf16 v[10:13], v[158:161], v[206:209], v[10:13]
	v_mfma_f32_16x16x32_bf16 v[62:65], v[150:153], v[186:189], v[62:65]
	v_mfma_f32_16x16x32_bf16 v[58:61], v[162:165], v[186:189], v[58:61]
	v_mfma_f32_16x16x32_bf16 v[54:57], v[150:153], v[194:197], v[54:57]
	v_mfma_f32_16x16x32_bf16 v[50:53], v[162:165], v[194:197], v[50:53]
	v_mfma_f32_16x16x32_bf16 v[30:33], v[150:153], v[202:205], v[30:33]
	v_mfma_f32_16x16x32_bf16 v[26:29], v[162:165], v[202:205], v[26:29]
	v_mfma_f32_16x16x32_bf16 v[22:25], v[150:153], v[210:213], v[22:25]
	v_mfma_f32_16x16x32_bf16 v[10:13], v[162:165], v[210:213], v[10:13]
	s_setprio 0
	s_setprio 1
	v_mfma_f32_16x16x32_bf16 v[46:49], v[166:169], v[182:185], v[46:49]
	v_mfma_f32_16x16x32_bf16 v[42:45], v[174:177], v[182:185], v[42:45]
	v_mfma_f32_16x16x32_bf16 v[38:41], v[166:169], v[190:193], v[38:41]
	v_mfma_f32_16x16x32_bf16 v[34:37], v[174:177], v[190:193], v[34:37]
	v_mfma_f32_16x16x32_bf16 v[18:21], v[166:169], v[198:201], v[18:21]
	v_mfma_f32_16x16x32_bf16 v[14:17], v[174:177], v[198:201], v[14:17]
	v_mfma_f32_16x16x32_bf16 v[6:9], v[166:169], v[206:209], v[6:9]
	v_mfma_f32_16x16x32_bf16 v[2:5], v[174:177], v[206:209], v[2:5]
	v_mfma_f32_16x16x32_bf16 v[46:49], v[170:173], v[186:189], v[46:49]
	v_mfma_f32_16x16x32_bf16 v[42:45], v[178:181], v[186:189], v[42:45]
	v_mfma_f32_16x16x32_bf16 v[38:41], v[170:173], v[194:197], v[38:41]
	v_mfma_f32_16x16x32_bf16 v[34:37], v[178:181], v[194:197], v[34:37]
	v_mfma_f32_16x16x32_bf16 v[18:21], v[170:173], v[202:205], v[18:21]
	v_mfma_f32_16x16x32_bf16 v[14:17], v[178:181], v[202:205], v[14:17]
	v_mfma_f32_16x16x32_bf16 v[6:9], v[170:173], v[210:213], v[6:9]
	v_mfma_f32_16x16x32_bf16 v[2:5], v[178:181], v[210:213], v[2:5]
	s_setprio 0
	s_barrier
	s_add_i32 s49, s49, 2
	s_add_u32 s22, s22, 0x100
	s_addc_u32 s23, s23, 0
	s_add_u32 s47, s47, 0x100
	s_addc_u32 s48, s48, 0
	s_cmp_gt_u32 s49, 5
	s_cbranch_scc0 .LBB0_1538
	s_and_b64 vcc, exec, s[10:11]
	s_cbranch_vccz .LBB0_1541
	s_barrier

; #define PG8_STAGE(bufoff, gbase, voff) do { _Pragma("unroll") for (int _i = 0; _i < 2; ++_i) \
;         __builtin_amdgcn_global_load_lds((const unsigned*)((const char*)(gbase) + (voff)[_i]), (PG8_LAS unsigned*)(lds + (bufoff) + ldsw + _i * 8192), 16, 0, 0); } while (0)
; #define PG8_LDA(dst, b, h) do { _Pragma("unroll") for (int m = 0; m < 4; ++m) _Pragma("unroll") for (int k = 0; k < 2; ++k) dst[m][k] = *(const PG8_LAS bf16x8*)(lds + PG8_SA(b, h) + aoff + m * 2048 + k * 1024); } while (0)
; #define PG8_LDB(dst, b, h) do { _Pragma("unroll") for (int n = 0; n < 2; ++n) _Pragma("unroll") for (int k = 0; k < 2; ++k) dst[n][k] = *(const PG8_LAS bf16x8*)(lds + PG8_SB(b, h) + boff + n * 2048 + k * 1024); } while (0)
; #define PG8_MMA(ai, bj, At, Bt) do { __builtin_amdgcn_s_setprio(1); _Pragma("unroll") for (int m = 0; m < 4; ++m) _Pragma("unroll") for (int n = 0; n < 2; ++n) _Pragma("unroll") for (int k = 0; k < 2; ++k) \
;         acc[ai][bj][m][n] = mma_<I8>(Bt[n][k], At[m][k], acc[ai][bj][m][n]); __builtin_amdgcn_s_setprio(0); } while (0)
; #define PG8_WAIT_V(n) asm volatile("s_waitcnt vmcnt(" #n ")" ::: "memory")
; #define PG8_WAIT_L(n) asm volatile("s_waitcnt lgkmcnt(" #n ")" ::: "memory")
; #define PG8_BAR __builtin_amdgcn_s_barrier()
; #define PG8_SCHED __builtin_amdgcn_sched_barrier(0)
; template <class Epi, class Sched, bool ALIGN_EPI = false, bool SP2 = false, bool I8 = false>
; __device__ __forceinline__ void gemm_phase(PG8_LAS unsigned char* lds, const Gemm g, const Sched& S, const Epi& E) {
;     ...
;             PG8_LDB(B0, 0, 0); PG8_LDB(B1, 0, 1); PG8_SCHED; PG8_LDA(At, 0, 0); PG8_STAGE(PG8_SA(1, 1), a1 + hstepA, voffA);
;             PG8_WAIT_V(8); PG8_WAIT_L(0); PG8_BAR; PG8_MMA(0, 0, At, B0); PG8_MMA(0, 1, At, B1); PG8_BAR; PG8_SCHED;
;             PG8_LDA(At, 0, 1); PG8_STAGE(PG8_SB(0, 0), b2, voffB); PG8_STAGE(PG8_SB(0, 1), b2 + hstepB, voffB); PG8_STAGE(PG8_SA(0, 0), a2, voffA);
;             PG8_WAIT_V(8); PG8_WAIT_L(0); PG8_BAR; PG8_MMA(1, 0, At, B0); PG8_MMA(1, 1, At, B1); PG8_BAR; PG8_SCHED;
.LBB0_1565:
	ds_read_b128 v[130:133], v176
	ds_read_b128 v[134:137], v176 offset:1024
	ds_read_b128 v[138:141], v176 offset:2048
	ds_read_b128 v[142:145], v176 offset:3072
	ds_read_b128 v[162:165], v177
	ds_read_b128 v[166:169], v177 offset:1024
	ds_read_b128 v[170:173], v177 offset:2048
	ds_read_b128 v[180:183], v177 offset:3072
	s_add_u32 s30, s28, 0xfff80080
	s_addc_u32 s31, s29, -1
	s_cmp_eq_u32 s54, 28
	s_cselect_b32 s35, s7, s31
	s_cselect_b32 s34, s21, s30
	s_cselect_b32 s31, s19, s53
	s_cselect_b32 s30, s27, s52
	s_add_i32 m0, s40, 0xc000
	ds_read_b128 v[184:187], v178
	ds_read_b128 v[188:191], v178 offset:1024
	ds_read_b128 v[192:195], v178 offset:2048
	ds_read_b128 v[196:199], v178 offset:3072
	ds_read_b128 v[200:203], v178 offset:4096
	ds_read_b128 v[204:207], v178 offset:5120
	ds_read_b128 v[208:211], v178 offset:6144
	ds_read_b128 v[212:215], v178 offset:7168
	global_load_lds_dwordx4 v154, s[28:29]
	s_add_i32 m0, s40, 0xe000
	s_nop 0
	global_load_lds_dwordx4 v156, s[28:29]
	s_waitcnt vmcnt(8) lgkmcnt(0)
	s_barrier
	s_setprio 1
	s_waitcnt lgkmcnt(0)
	v_mfma_f32_16x16x32_bf16 v[126:129], v[130:133], v[184:187], v[126:129]
	v_mfma_f32_16x16x32_bf16 v[122:125], v[138:141], v[184:187], v[122:125]
	v_mfma_f32_16x16x32_bf16 v[110:113], v[130:133], v[192:195], v[110:113]
	v_mfma_f32_16x16x32_bf16 v[106:109], v[138:141], v[192:195], v[106:109]
	v_mfma_f32_16x16x32_bf16 v[94:97], v[130:133], v[200:203], v[94:97]
	v_mfma_f32_16x16x32_bf16 v[90:93], v[138:141], v[200:203], v[90:93]
	v_mfma_f32_16x16x32_bf16 v[78:81], v[130:133], v[208:211], v[78:81]
	v_mfma_f32_16x16x32_bf16 v[74:77], v[138:141], v[208:211], v[74:77]
	v_mfma_f32_16x16x32_bf16 v[126:129], v[134:137], v[188:191], v[126:129]
	v_mfma_f32_16x16x32_bf16 v[122:125], v[142:145], v[188:191], v[122:125]
	v_mfma_f32_16x16x32_bf16 v[110:113], v[134:137], v[196:199], v[110:113]
	v_mfma_f32_16x16x32_bf16 v[106:109], v[142:145], v[196:199], v[106:109]
	v_mfma_f32_16x16x32_bf16 v[94:97], v[134:137], v[204:207], v[94:97]
	v_mfma_f32_16x16x32_bf16 v[90:93], v[142:145], v[204:207], v[90:93]
	v_mfma_f32_16x16x32_bf16 v[78:81], v[134:137], v[212:215], v[78:81]
	v_mfma_f32_16x16x32_bf16 v[74:77], v[142:145], v[212:215], v[74:77]
	s_setprio 0
	s_setprio 1
	v_mfma_f32_16x16x32_bf16 v[118:121], v[162:165], v[184:187], v[118:121]
	v_mfma_f32_16x16x32_bf16 v[114:117], v[170:173], v[184:187], v[114:117]
	v_mfma_f32_16x16x32_bf16 v[102:105], v[162:165], v[192:195], v[102:105]
	v_mfma_f32_16x16x32_bf16 v[98:101], v[170:173], v[192:195], v[98:101]
	v_mfma_f32_16x16x32_bf16 v[86:89], v[162:165], v[200:203], v[86:89]
	v_mfma_f32_16x16x32_bf16 v[82:85], v[170:173], v[200:203], v[82:85]
	v_mfma_f32_16x16x32_bf16 v[70:73], v[162:165], v[208:211], v[70:73]
	v_mfma_f32_16x16x32_bf16 v[66:69], v[170:173], v[208:211], v[66:69]
	v_mfma_f32_16x16x32_bf16 v[118:121], v[166:169], v[188:191], v[118:121]
	v_mfma_f32_16x16x32_bf16 v[114:117], v[180:183], v[188:191], v[114:117]
	v_mfma_f32_16x16x32_bf16 v[102:105], v[166:169], v[196:199], v[102:105]
	v_mfma_f32_16x16x32_bf16 v[98:101], v[180:183], v[196:199], v[98:101]
	v_mfma_f32_16x16x32_bf16 v[86:89], v[166:169], v[204:207], v[86:89]
	v_mfma_f32_16x16x32_bf16 v[82:85], v[180:183], v[204:207], v[82:85]
	v_mfma_f32_16x16x32_bf16 v[70:73], v[166:169], v[212:215], v[70:73]
	v_mfma_f32_16x16x32_bf16 v[66:69], v[180:183], v[212:215], v[66:69]
	s_setprio 0
	s_barrier
	s_add_i32 s55, s50, s39
	s_mov_b64 s[98:99], s[30:31]
	s_mov_b32 m0, s55
	ds_read_b128 v[184:187], v178 offset:16384
	ds_read_b128 v[188:191], v178 offset:17408
	ds_read_b128 v[192:195], v178 offset:18432
	ds_read_b128 v[196:199], v178 offset:19456
	ds_read_b128 v[200:203], v178 offset:20480
	ds_read_b128 v[204:207], v178 offset:21504
	ds_read_b128 v[208:211], v178 offset:22528
	ds_read_b128 v[212:215], v178 offset:23552
	global_load_lds_dwordx4 v148, s[30:31]
	s_add_i32 m0, s55, 0x2000
	s_add_u32 s56, s30, 0x80000
	s_mov_b64 s[98:99], s[30:31]
	s_addc_u32 s57, s31, 0
	s_add_i32 s55, s51, s39
	global_load_lds_dwordx4 v152, s[30:31]
	s_mov_b32 m0, s55
	s_mov_b64 s[100:101], s[34:35]
	global_load_lds_dwordx4 v148, s[56:57]
	s_add_i32 m0, s55, 0x2000
	s_nop 0
	global_load_lds_dwordx4 v152, s[56:57]
	s_mov_b64 s[100:101], s[34:35]
	s_mov_b32 m0, s40
	s_nop 0
	global_load_lds_dwordx4 v146, s[34:35]
	s_mov_b32 m0, s41
	s_nop 0
	global_load_lds_dwordx4 v150, s[34:35]
	s_waitcnt vmcnt(8) lgkmcnt(0)
	s_barrier
	s_setprio 1
	s_waitcnt lgkmcnt(0)
	v_mfma_f32_16x16x32_bf16 v[62:65], v[130:133], v[184:187], v[62:65]
	v_mfma_f32_16x16x32_bf16 v[58:61], v[138:141], v[184:187], v[58:61]
	v_mfma_f32_16x16x32_bf16 v[46:49], v[130:133], v[192:195], v[46:49]
	v_mfma_f32_16x16x32_bf16 v[42:45], v[138:141], v[192:195], v[42:45]
	v_mfma_f32_16x16x32_bf16 v[30:33], v[130:133], v[200:203], v[30:33]
	v_mfma_f32_16x16x32_bf16 v[26:29], v[138:141], v[200:203], v[26:29]
	v_mfma_f32_16x16x32_bf16 v[14:17], v[130:133], v[208:211], v[14:17]
	v_mfma_f32_16x16x32_bf16 v[10:13], v[138:141], v[208:211], v[10:13]
	v_mfma_f32_16x16x32_bf16 v[62:65], v[134:137], v[188:191], v[62:65]
	v_mfma_f32_16x16x32_bf16 v[58:61], v[142:145], v[188:191], v[58:61]
	v_mfma_f32_16x16x32_bf16 v[46:49], v[134:137], v[196:199], v[46:49]
	v_mfma_f32_16x16x32_bf16 v[42:45], v[142:145], v[196:199], v[42:45]
	v_mfma_f32_16x16x32_bf16 v[30:33], v[134:137], v[204:207], v[30:33]
	v_mfma_f32_16x16x32_bf16 v[26:29], v[142:145], v[204:207], v[26:29]
	v_mfma_f32_16x16x32_bf16 v[14:17], v[134:137], v[212:215], v[14:17]
	v_mfma_f32_16x16x32_bf16 v[10:13], v[142:145], v[212:215], v[10:13]
	s_setprio 0
	s_setprio 1
	v_mfma_f32_16x16x32_bf16 v[54:57], v[162:165], v[184:187], v[54:57]
	v_mfma_f32_16x16x32_bf16 v[50:53], v[170:173], v[184:187], v[50:53]
	v_mfma_f32_16x16x32_bf16 v[38:41], v[162:165], v[192:195], v[38:41]
	v_mfma_f32_16x16x32_bf16 v[34:37], v[170:173], v[192:195], v[34:37]
	v_mfma_f32_16x16x32_bf16 v[22:25], v[162:165], v[200:203], v[22:25]
	v_mfma_f32_16x16x32_bf16 v[18:21], v[170:173], v[200:203], v[18:21]
	v_mfma_f32_16x16x32_bf16 v[6:9], v[162:165], v[208:211], v[6:9]
	v_mfma_f32_16x16x32_bf16 v[2:5], v[170:173], v[208:211], v[2:5]
	v_mfma_f32_16x16x32_bf16 v[54:57], v[166:169], v[188:191], v[54:57]
	v_mfma_f32_16x16x32_bf16 v[50:53], v[180:183], v[188:191], v[50:53]
	v_mfma_f32_16x16x32_bf16 v[38:41], v[166:169], v[196:199], v[38:41]
	v_mfma_f32_16x16x32_bf16 v[34:37], v[180:183], v[196:199], v[34:37]
	v_mfma_f32_16x16x32_bf16 v[22:25], v[166:169], v[204:207], v[22:25]
	v_mfma_f32_16x16x32_bf16 v[18:21], v[180:183], v[204:207], v[18:21]
	v_mfma_f32_16x16x32_bf16 v[6:9], v[166:169], v[212:215], v[6:9]
	v_mfma_f32_16x16x32_bf16 v[2:5], v[180:183], v[212:215], v[2:5]
	s_setprio 0
	s_barrier
; #define PG8_STAGE(bufoff, gbase, voff) do { _Pragma("unroll") for (int _i = 0; _i < 2; ++_i) \
;         __builtin_amdgcn_global_load_lds((const unsigned*)((const char*)(gbase) + (voff)[_i]), (PG8_LAS unsigned*)(lds + (bufoff) + ldsw + _i * 8192), 16, 0, 0); } while (0)
; #define PG8_LDA(dst, b, h) do { _Pragma("unroll") for (int m = 0; m < 4; ++m) _Pragma("unroll") for (int k = 0; k < 2; ++k) dst[m][k] = *(const PG8_LAS bf16x8*)(lds + PG8_SA(b, h) + aoff + m * 2048 + k * 1024); } while (0)
; #define PG8_LDB(dst, b, h) do { _Pragma("unroll") for (int n = 0; n < 2; ++n) _Pragma("unroll") for (int k = 0; k < 2; ++k) dst[n][k] = *(const PG8_LAS bf16x8*)(lds + PG8_SB(b, h) + boff + n * 2048 + k * 1024); } while (0)
; #define PG8_MMA(ai, bj, At, Bt) do { __builtin_amdgcn_s_setprio(1); _Pragma("unroll") for (int m = 0; m < 4; ++m) _Pragma("unroll") for (int n = 0; n < 2; ++n) _Pragma("unroll") for (int k = 0; k < 2; ++k) \
;         acc[ai][bj][m][n] = mma_<I8>(Bt[n][k], At[m][k], acc[ai][bj][m][n]); __builtin_amdgcn_s_setprio(0); } while (0)
; #define PG8_WAIT_V(n) asm volatile("s_waitcnt vmcnt(" #n ")" ::: "memory")
; #define PG8_WAIT_L(n) asm volatile("s_waitcnt lgkmcnt(" #n ")" ::: "memory")
; #define PG8_BAR __builtin_amdgcn_s_barrier()
; #define PG8_SCHED __builtin_amdgcn_sched_barrier(0)
; template <class Epi, class Sched, bool ALIGN_EPI = false, bool SP2 = false, bool I8 = false>
; __device__ __forceinline__ void gemm_phase(PG8_LAS unsigned char* lds, const Gemm g, const Sched& S, const Epi& E) {
;     ...
;         for (int t = 0; t < nt; t += 2) {
;             const bool last = (t == nt - 2);
;             const char* a1 = cA + (size_t)(t + 1) * kstep;
;             const char* a2 = last ? nA : cA + (size_t)(t + 2) * kstep; const char* b2 = last ? nB : cB + (size_t)(t + 2) * kstep;
;             const char* a3 = a2 + kstep; const char* b3 = b2 + kstep;
;     ...
;             PG8_LDB(B0, 1, 0); PG8_LDB(B1, 1, 1); PG8_SCHED; PG8_LDA(At, 1, 0); PG8_STAGE(PG8_SA(0, 1), a2 + hstepA, voffA);
;             PG8_WAIT_V(8); PG8_WAIT_L(0); PG8_BAR; PG8_MMA(0, 0, At, B0); PG8_MMA(0, 1, At, B1); PG8_BAR; PG8_SCHED;
;             PG8_LDA(At, 1, 1); PG8_STAGE(PG8_SB(1, 0), b3, voffB); PG8_STAGE(PG8_SB(1, 1), b3 + hstepB, voffB); PG8_STAGE(PG8_SA(1, 0), a3, voffA);
;             PG8_WAIT_V(8); PG8_WAIT_L(0); PG8_BAR; PG8_MMA(1, 0, At, B0); PG8_MMA(1, 1, At, B1); PG8_BAR; PG8_SCHED;
	s_add_i32 s55, 0, 0x18000
	s_add_i32 s56, 0, 0x1c000
	v_add_u32_e32 v142, s55, v1
	v_add_u32_e32 v180, s56, v1
	ds_read_b128 v[130:133], v142
	ds_read_b128 v[134:137], v142 offset:1024
	ds_read_b128 v[138:141], v142 offset:2048
	ds_read_b128 v[142:145], v142 offset:3072
	ds_read_b128 v[162:165], v180
	ds_read_b128 v[166:169], v180 offset:1024
	ds_read_b128 v[170:173], v180 offset:2048
	ds_read_b128 v[180:183], v180 offset:3072
	s_add_u32 s34, s34, 0x80000
	s_addc_u32 s35, s35, 0
	s_mov_b32 m0, s42
	ds_read_b128 v[184:187], v178 offset:32768
	ds_read_b128 v[188:191], v178 offset:33792
	ds_read_b128 v[192:195], v178 offset:34816
	ds_read_b128 v[196:199], v178 offset:35840
	ds_read_b128 v[200:203], v178 offset:36864
	ds_read_b128 v[204:207], v178 offset:37888
	ds_read_b128 v[208:211], v178 offset:38912
	ds_read_b128 v[212:215], v178 offset:39936
	global_load_lds_dwordx4 v146, s[34:35]
	s_mov_b32 m0, s43
	s_nop 0
	global_load_lds_dwordx4 v150, s[34:35]
	s_waitcnt vmcnt(8) lgkmcnt(0)
	s_barrier
	s_setprio 1
	s_waitcnt lgkmcnt(0)
	v_mfma_f32_16x16x32_bf16 v[126:129], v[130:133], v[184:187], v[126:129]
	v_mfma_f32_16x16x32_bf16 v[122:125], v[138:141], v[184:187], v[122:125]
	v_mfma_f32_16x16x32_bf16 v[110:113], v[130:133], v[192:195], v[110:113]
	v_mfma_f32_16x16x32_bf16 v[106:109], v[138:141], v[192:195], v[106:109]
	v_mfma_f32_16x16x32_bf16 v[94:97], v[130:133], v[200:203], v[94:97]
	v_mfma_f32_16x16x32_bf16 v[90:93], v[138:141], v[200:203], v[90:93]
	v_mfma_f32_16x16x32_bf16 v[78:81], v[130:133], v[208:211], v[78:81]
	v_mfma_f32_16x16x32_bf16 v[74:77], v[138:141], v[208:211], v[74:77]
	v_mfma_f32_16x16x32_bf16 v[126:129], v[134:137], v[188:191], v[126:129]
	v_mfma_f32_16x16x32_bf16 v[122:125], v[142:145], v[188:191], v[122:125]
	v_mfma_f32_16x16x32_bf16 v[110:113], v[134:137], v[196:199], v[110:113]
	v_mfma_f32_16x16x32_bf16 v[106:109], v[142:145], v[196:199], v[106:109]
	v_mfma_f32_16x16x32_bf16 v[94:97], v[134:137], v[204:207], v[94:97]
	v_mfma_f32_16x16x32_bf16 v[90:93], v[142:145], v[204:207], v[90:93]
	v_mfma_f32_16x16x32_bf16 v[78:81], v[134:137], v[212:215], v[78:81]
	v_mfma_f32_16x16x32_bf16 v[74:77], v[142:145], v[212:215], v[74:77]
	s_setprio 0
	s_setprio 1
	v_mfma_f32_16x16x32_bf16 v[118:121], v[162:165], v[184:187], v[118:121]
	v_mfma_f32_16x16x32_bf16 v[114:117], v[170:173], v[184:187], v[114:117]
	v_mfma_f32_16x16x32_bf16 v[102:105], v[162:165], v[192:195], v[102:105]
	v_mfma_f32_16x16x32_bf16 v[98:101], v[170:173], v[192:195], v[98:101]
	v_mfma_f32_16x16x32_bf16 v[86:89], v[162:165], v[200:203], v[86:89]
	v_mfma_f32_16x16x32_bf16 v[82:85], v[170:173], v[200:203], v[82:85]
	v_mfma_f32_16x16x32_bf16 v[70:73], v[162:165], v[208:211], v[70:73]
	v_mfma_f32_16x16x32_bf16 v[66:69], v[170:173], v[208:211], v[66:69]
	v_mfma_f32_16x16x32_bf16 v[118:121], v[166:169], v[188:191], v[118:121]
	v_mfma_f32_16x16x32_bf16 v[114:117], v[180:183], v[188:191], v[114:117]
	v_mfma_f32_16x16x32_bf16 v[102:105], v[166:169], v[196:199], v[102:105]
	v_mfma_f32_16x16x32_bf16 v[98:101], v[180:183], v[196:199], v[98:101]
	v_mfma_f32_16x16x32_bf16 v[86:89], v[166:169], v[204:207], v[86:89]
	v_mfma_f32_16x16x32_bf16 v[82:85], v[180:183], v[204:207], v[82:85]
	v_mfma_f32_16x16x32_bf16 v[70:73], v[166:169], v[212:215], v[70:73]
	v_mfma_f32_16x16x32_bf16 v[66:69], v[180:183], v[212:215], v[66:69]
	s_setprio 0
	s_barrier
	s_add_i32 s34, s55, s39
	s_add_i32 m0, s34, 0xffffff80
	ds_read_b128 v[184:187], v178 offset:49152
	ds_read_b128 v[188:191], v178 offset:50176
	ds_read_b128 v[192:195], v178 offset:51200
	ds_read_b128 v[196:199], v178 offset:52224
	ds_read_b128 v[200:203], v178 offset:53248
	ds_read_b128 v[204:207], v178 offset:54272
	ds_read_b128 v[208:211], v178 offset:55296
	ds_read_b128 v[212:215], v178 offset:56320
	global_load_lds_dwordx4 v148, s[98:99] offset:128
	s_add_i32 m0, s34, 0x1f80
	s_add_u32 s30, s30, 0x80080
	s_addc_u32 s31, s31, 0
	s_add_i32 s34, s56, s39
	global_load_lds_dwordx4 v152, s[98:99] offset:128
	s_mov_b32 m0, s34
	s_nop 0
	global_load_lds_dwordx4 v148, s[30:31]
	s_add_i32 m0, s34, 0x2000
	s_nop 0
	global_load_lds_dwordx4 v152, s[30:31]
	s_add_i32 m0, s46, 0xffffff80
	s_nop 0
	global_load_lds_dwordx4 v146, s[100:101] offset:128
	s_add_i32 m0, s47, 0xffffff80
	s_nop 0
	global_load_lds_dwordx4 v150, s[100:101] offset:128
	s_waitcnt vmcnt(8) lgkmcnt(0)
	s_barrier
	s_setprio 1
	s_waitcnt lgkmcnt(0)
	v_mfma_f32_16x16x32_bf16 v[62:65], v[130:133], v[184:187], v[62:65]
	v_mfma_f32_16x16x32_bf16 v[58:61], v[138:141], v[184:187], v[58:61]
	v_mfma_f32_16x16x32_bf16 v[46:49], v[130:133], v[192:195], v[46:49]
	v_mfma_f32_16x16x32_bf16 v[42:45], v[138:141], v[192:195], v[42:45]
	v_mfma_f32_16x16x32_bf16 v[30:33], v[130:133], v[200:203], v[30:33]
	v_mfma_f32_16x16x32_bf16 v[26:29], v[138:141], v[200:203], v[26:29]
	v_mfma_f32_16x16x32_bf16 v[14:17], v[130:133], v[208:211], v[14:17]
	v_mfma_f32_16x16x32_bf16 v[10:13], v[138:141], v[208:211], v[10:13]
	v_mfma_f32_16x16x32_bf16 v[62:65], v[134:137], v[188:191], v[62:65]
	v_mfma_f32_16x16x32_bf16 v[58:61], v[142:145], v[188:191], v[58:61]
	v_mfma_f32_16x16x32_bf16 v[46:49], v[134:137], v[196:199], v[46:49]
	v_mfma_f32_16x16x32_bf16 v[42:45], v[142:145], v[196:199], v[42:45]
	v_mfma_f32_16x16x32_bf16 v[30:33], v[134:137], v[204:207], v[30:33]
	v_mfma_f32_16x16x32_bf16 v[26:29], v[142:145], v[204:207], v[26:29]
	v_mfma_f32_16x16x32_bf16 v[14:17], v[134:137], v[212:215], v[14:17]
	v_mfma_f32_16x16x32_bf16 v[10:13], v[142:145], v[212:215], v[10:13]
	s_setprio 0
	s_setprio 1
	v_mfma_f32_16x16x32_bf16 v[54:57], v[162:165], v[184:187], v[54:57]
	v_mfma_f32_16x16x32_bf16 v[50:53], v[170:173], v[184:187], v[50:53]
	v_mfma_f32_16x16x32_bf16 v[38:41], v[162:165], v[192:195], v[38:41]
	v_mfma_f32_16x16x32_bf16 v[34:37], v[170:173], v[192:195], v[34:37]
	v_mfma_f32_16x16x32_bf16 v[22:25], v[162:165], v[200:203], v[22:25]
	v_mfma_f32_16x16x32_bf16 v[18:21], v[170:173], v[200:203], v[18:21]
	v_mfma_f32_16x16x32_bf16 v[6:9], v[162:165], v[208:211], v[6:9]
	v_mfma_f32_16x16x32_bf16 v[2:5], v[170:173], v[208:211], v[2:5]
	v_mfma_f32_16x16x32_bf16 v[54:57], v[166:169], v[188:191], v[54:57]
	v_mfma_f32_16x16x32_bf16 v[50:53], v[180:183], v[188:191], v[50:53]
	v_mfma_f32_16x16x32_bf16 v[38:41], v[166:169], v[196:199], v[38:41]
	v_mfma_f32_16x16x32_bf16 v[34:37], v[180:183], v[196:199], v[34:37]
	v_mfma_f32_16x16x32_bf16 v[22:25], v[166:169], v[204:207], v[22:25]
	v_mfma_f32_16x16x32_bf16 v[18:21], v[180:183], v[204:207], v[18:21]
	v_mfma_f32_16x16x32_bf16 v[6:9], v[166:169], v[212:215], v[6:9]
	v_mfma_f32_16x16x32_bf16 v[2:5], v[180:183], v[212:215], v[2:5]
	s_setprio 0
	s_barrier
	s_add_i32 s54, s54, 2
	s_add_u32 s28, s28, 0x100
	s_addc_u32 s29, s29, 0
	s_add_u32 s52, s52, 0x100
	s_addc_u32 s53, s53, 0
	s_cmp_gt_u32 s54, 29
	s_cbranch_scc0 .LBB0_1565
	s_and_b64 vcc, exec, s[16:17]
	s_cbranch_vccz .LBB0_1568
	s_barrier

; #define PG8_STAGE(bufoff, gbase, voff) do { _Pragma("unroll") for (int _i = 0; _i < 2; ++_i) \
;         __builtin_amdgcn_global_load_lds((const unsigned*)((const char*)(gbase) + (voff)[_i]), (PG8_LAS unsigned*)(lds + (bufoff) + ldsw + _i * 8192), 16, 0, 0); } while (0)
; #define PG8_LDA(dst, b, h) do { _Pragma("unroll") for (int m = 0; m < 4; ++m) _Pragma("unroll") for (int k = 0; k < 2; ++k) dst[m][k] = *(const PG8_LAS bf16x8*)(lds + PG8_SA(b, h) + aoff + m * 2048 + k * 1024); } while (0)
; #define PG8_LDB(dst, b, h) do { _Pragma("unroll") for (int n = 0; n < 2; ++n) _Pragma("unroll") for (int k = 0; k < 2; ++k) dst[n][k] = *(const PG8_LAS bf16x8*)(lds + PG8_SB(b, h) + boff + n * 2048 + k * 1024); } while (0)
; #define PG8_MMA(ai, bj, At, Bt) do { __builtin_amdgcn_s_setprio(1); _Pragma("unroll") for (int m = 0; m < 4; ++m) _Pragma("unroll") for (int n = 0; n < 2; ++n) _Pragma("unroll") for (int k = 0; k < 2; ++k) \
;         acc[ai][bj][m][n] = mma_<I8>(Bt[n][k], At[m][k], acc[ai][bj][m][n]); __builtin_amdgcn_s_setprio(0); } while (0)
; #define PG8_WAIT_V(n) asm volatile("s_waitcnt vmcnt(" #n ")" ::: "memory")
; #define PG8_WAIT_L(n) asm volatile("s_waitcnt lgkmcnt(" #n ")" ::: "memory")
; #define PG8_BAR __builtin_amdgcn_s_barrier()
; #define PG8_SCHED __builtin_amdgcn_sched_barrier(0)
; template <class Epi, class Sched, bool ALIGN_EPI = false, bool SP2 = false, bool I8 = false>
; __device__ __forceinline__ void gemm_phase(PG8_LAS unsigned char* lds, const Gemm g, const Sched& S, const Epi& E) {
;     ...
;             PG8_LDB(B0, 0, 0); PG8_LDB(B1, 0, 1); PG8_SCHED; PG8_LDA(At, 0, 0); PG8_STAGE(PG8_SA(1, 1), a1 + hstepA, voffA);
;             PG8_WAIT_V(8); PG8_WAIT_L(0); PG8_BAR; PG8_MMA(0, 0, At, B0); PG8_MMA(0, 1, At, B1); PG8_BAR; PG8_SCHED;
;             PG8_LDA(At, 0, 1); PG8_STAGE(PG8_SB(0, 0), b2, voffB); PG8_STAGE(PG8_SB(0, 1), b2 + hstepB, voffB); PG8_STAGE(PG8_SA(0, 0), a2, voffA);
;             PG8_WAIT_V(8); PG8_WAIT_L(0); PG8_BAR; PG8_MMA(1, 0, At, B0); PG8_MMA(1, 1, At, B1); PG8_BAR; PG8_SCHED;
.LBB0_1721:
	ds_read_b128 v[34:37], v233
	ds_read_b128 v[38:41], v233 offset:1024
	ds_read_b128 v[42:45], v233 offset:2048
	ds_read_b128 v[62:65], v233 offset:3072
	ds_read_b128 v[146:149], v234
	ds_read_b128 v[150:153], v234 offset:1024
	ds_read_b128 v[154:157], v234 offset:2048
	ds_read_b128 v[158:161], v234 offset:3072
	s_add_u32 s34, s8, 0xfff80080
	s_addc_u32 s35, s9, -1
	s_cmp_eq_u32 s55, 28
	s_cselect_b32 s37, s3, s35
	s_cselect_b32 s36, s7, s34
	s_cselect_b32 s35, s25, s54
	s_cselect_b32 s34, s27, s33
	s_add_i32 m0, s43, 0xc000
	ds_read_b128 v[162:165], v235
	ds_read_b128 v[166:169], v235 offset:1024
	ds_read_b128 v[170:173], v235 offset:2048
	ds_read_b128 v[186:189], v235 offset:3072
	ds_read_b128 v[190:193], v235 offset:4096
	ds_read_b128 v[194:197], v235 offset:5120
	ds_read_b128 v[198:201], v235 offset:6144
	ds_read_b128 v[202:205], v235 offset:7168
	global_load_lds_dwordx4 v178, s[8:9]
	s_add_i32 m0, s43, 0xe000
	s_nop 0
	global_load_lds_dwordx4 v180, s[8:9]
	s_waitcnt vmcnt(8) lgkmcnt(0)
	s_barrier
	s_setprio 1
	s_waitcnt lgkmcnt(0)
	v_mfma_i32_16x16x64_i8 v[142:145], v[34:37], v[162:165], v[142:145]
	v_mfma_i32_16x16x64_i8 v[138:141], v[42:45], v[162:165], v[138:141]
	v_mfma_i32_16x16x64_i8 v[126:129], v[34:37], v[170:173], v[126:129]
	v_mfma_i32_16x16x64_i8 v[122:125], v[42:45], v[170:173], v[122:125]
	v_mfma_i32_16x16x64_i8 v[110:113], v[34:37], v[190:193], v[110:113]
	v_mfma_i32_16x16x64_i8 v[106:109], v[42:45], v[190:193], v[106:109]
	v_mfma_i32_16x16x64_i8 v[94:97], v[34:37], v[198:201], v[94:97]
	v_mfma_i32_16x16x64_i8 v[90:93], v[42:45], v[198:201], v[90:93]
	v_mfma_i32_16x16x64_i8 v[142:145], v[38:41], v[166:169], v[142:145]
	v_mfma_i32_16x16x64_i8 v[138:141], v[62:65], v[166:169], v[138:141]
	v_mfma_i32_16x16x64_i8 v[126:129], v[38:41], v[186:189], v[126:129]
	v_mfma_i32_16x16x64_i8 v[122:125], v[62:65], v[186:189], v[122:125]
	v_mfma_i32_16x16x64_i8 v[110:113], v[38:41], v[194:197], v[110:113]
	v_mfma_i32_16x16x64_i8 v[106:109], v[62:65], v[194:197], v[106:109]
	v_mfma_i32_16x16x64_i8 v[94:97], v[38:41], v[202:205], v[94:97]
	v_mfma_i32_16x16x64_i8 v[90:93], v[62:65], v[202:205], v[90:93]
	s_setprio 0
	s_setprio 1
	v_mfma_i32_16x16x64_i8 v[134:137], v[146:149], v[162:165], v[134:137]
	v_mfma_i32_16x16x64_i8 v[130:133], v[154:157], v[162:165], v[130:133]
	v_mfma_i32_16x16x64_i8 v[118:121], v[146:149], v[170:173], v[118:121]
	v_mfma_i32_16x16x64_i8 v[114:117], v[154:157], v[170:173], v[114:117]
	v_mfma_i32_16x16x64_i8 v[102:105], v[146:149], v[190:193], v[102:105]
	v_mfma_i32_16x16x64_i8 v[98:101], v[154:157], v[190:193], v[98:101]
	v_mfma_i32_16x16x64_i8 v[86:89], v[146:149], v[198:201], v[86:89]
	v_mfma_i32_16x16x64_i8 v[82:85], v[154:157], v[198:201], v[82:85]
	v_mfma_i32_16x16x64_i8 v[134:137], v[150:153], v[166:169], v[134:137]
	v_mfma_i32_16x16x64_i8 v[130:133], v[158:161], v[166:169], v[130:133]
	v_mfma_i32_16x16x64_i8 v[118:121], v[150:153], v[186:189], v[118:121]
	v_mfma_i32_16x16x64_i8 v[114:117], v[158:161], v[186:189], v[114:117]
	v_mfma_i32_16x16x64_i8 v[102:105], v[150:153], v[194:197], v[102:105]
	v_mfma_i32_16x16x64_i8 v[98:101], v[158:161], v[194:197], v[98:101]
	v_mfma_i32_16x16x64_i8 v[86:89], v[150:153], v[202:205], v[86:89]
	v_mfma_i32_16x16x64_i8 v[82:85], v[158:161], v[202:205], v[82:85]
	s_setprio 0
	s_barrier
	s_add_i32 s56, s52, s40
	s_mov_b64 s[98:99], s[34:35]
	s_mov_b32 m0, s56
	ds_read_b128 v[162:165], v235 offset:16384
	ds_read_b128 v[166:169], v235 offset:17408
	ds_read_b128 v[170:173], v235 offset:18432
	ds_read_b128 v[186:189], v235 offset:19456
	ds_read_b128 v[190:193], v235 offset:20480
	ds_read_b128 v[194:197], v235 offset:21504
	ds_read_b128 v[198:201], v235 offset:22528
	ds_read_b128 v[202:205], v235 offset:23552
	global_load_lds_dwordx4 v174, s[34:35]
	s_add_i32 m0, s56, 0x2000
	s_add_u32 s56, s34, 0x80000
	s_mov_b64 s[98:99], s[34:35]
	s_addc_u32 s57, s35, 0
	s_add_i32 s58, s53, s40
	global_load_lds_dwordx4 v176, s[34:35]
	s_mov_b32 m0, s58
	s_mov_b64 s[100:101], s[36:37]
	global_load_lds_dwordx4 v174, s[56:57]
	s_add_i32 m0, s58, 0x2000
	s_nop 0
	global_load_lds_dwordx4 v176, s[56:57]
	s_mov_b64 s[100:101], s[36:37]
	s_mov_b32 m0, s43
	s_nop 0
	global_load_lds_dwordx4 v174, s[36:37]
	s_mov_b32 m0, s44
	s_nop 0
	global_load_lds_dwordx4 v176, s[36:37]
	s_waitcnt vmcnt(8) lgkmcnt(0)
	s_barrier
	s_setprio 1
	s_waitcnt lgkmcnt(0)
	v_mfma_i32_16x16x64_i8 v[78:81], v[34:37], v[162:165], v[78:81]
	v_mfma_i32_16x16x64_i8 v[74:77], v[42:45], v[162:165], v[74:77]
	v_mfma_i32_16x16x64_i8 v[58:61], v[34:37], v[170:173], v[58:61]
	v_mfma_i32_16x16x64_i8 v[54:57], v[42:45], v[170:173], v[54:57]
	v_mfma_i32_16x16x64_i8 v[30:33], v[34:37], v[190:193], v[30:33]
	v_mfma_i32_16x16x64_i8 v[26:29], v[42:45], v[190:193], v[26:29]
	v_mfma_i32_16x16x64_i8 v[14:17], v[34:37], v[198:201], v[14:17]
	v_mfma_i32_16x16x64_i8 v[10:13], v[42:45], v[198:201], v[10:13]
	v_mfma_i32_16x16x64_i8 v[78:81], v[38:41], v[166:169], v[78:81]
	v_mfma_i32_16x16x64_i8 v[74:77], v[62:65], v[166:169], v[74:77]
	v_mfma_i32_16x16x64_i8 v[58:61], v[38:41], v[186:189], v[58:61]
	v_mfma_i32_16x16x64_i8 v[54:57], v[62:65], v[186:189], v[54:57]
	v_mfma_i32_16x16x64_i8 v[30:33], v[38:41], v[194:197], v[30:33]
	v_mfma_i32_16x16x64_i8 v[26:29], v[62:65], v[194:197], v[26:29]
	v_mfma_i32_16x16x64_i8 v[14:17], v[38:41], v[202:205], v[14:17]
	v_mfma_i32_16x16x64_i8 v[10:13], v[62:65], v[202:205], v[10:13]
	s_setprio 0
	s_setprio 1
	v_mfma_i32_16x16x64_i8 v[46:49], v[154:157], v[170:173], v[46:49]
	v_mfma_i32_16x16x64_i8 v[22:25], v[146:149], v[190:193], v[22:25]
	v_mfma_i32_16x16x64_i8 v[18:21], v[154:157], v[190:193], v[18:21]
	v_mfma_i32_16x16x64_i8 v[6:9], v[146:149], v[198:201], v[6:9]
	v_mfma_i32_16x16x64_i8 v[2:5], v[154:157], v[198:201], v[2:5]
	v_mfma_i32_16x16x64_i8 v[34:37], v[146:149], v[162:165], v[70:73]
	v_mfma_i32_16x16x64_i8 v[38:41], v[154:157], v[162:165], v[66:69]
	v_mfma_i32_16x16x64_i8 v[42:45], v[146:149], v[170:173], v[50:53]
	v_mfma_i32_16x16x64_i8 v[46:49], v[158:161], v[186:189], v[46:49]
	v_mfma_i32_16x16x64_i8 v[22:25], v[150:153], v[194:197], v[22:25]
	v_mfma_i32_16x16x64_i8 v[18:21], v[158:161], v[194:197], v[18:21]
	v_mfma_i32_16x16x64_i8 v[6:9], v[150:153], v[202:205], v[6:9]
	v_mfma_i32_16x16x64_i8 v[2:5], v[158:161], v[202:205], v[2:5]
	v_mfma_i32_16x16x64_i8 v[34:37], v[150:153], v[166:169], v[34:37]
	v_mfma_i32_16x16x64_i8 v[38:41], v[158:161], v[166:169], v[38:41]
	v_mfma_i32_16x16x64_i8 v[42:45], v[150:153], v[186:189], v[42:45]
	s_setprio 0
	s_barrier
; #define PG8_STAGE(bufoff, gbase, voff) do { _Pragma("unroll") for (int _i = 0; _i < 2; ++_i) \
;         __builtin_amdgcn_global_load_lds((const unsigned*)((const char*)(gbase) + (voff)[_i]), (PG8_LAS unsigned*)(lds + (bufoff) + ldsw + _i * 8192), 16, 0, 0); } while (0)
; #define PG8_LDA(dst, b, h) do { _Pragma("unroll") for (int m = 0; m < 4; ++m) _Pragma("unroll") for (int k = 0; k < 2; ++k) dst[m][k] = *(const PG8_LAS bf16x8*)(lds + PG8_SA(b, h) + aoff + m * 2048 + k * 1024); } while (0)
; #define PG8_LDB(dst, b, h) do { _Pragma("unroll") for (int n = 0; n < 2; ++n) _Pragma("unroll") for (int k = 0; k < 2; ++k) dst[n][k] = *(const PG8_LAS bf16x8*)(lds + PG8_SB(b, h) + boff + n * 2048 + k * 1024); } while (0)
; #define PG8_MMA(ai, bj, At, Bt) do { __builtin_amdgcn_s_setprio(1); _Pragma("unroll") for (int m = 0; m < 4; ++m) _Pragma("unroll") for (int n = 0; n < 2; ++n) _Pragma("unroll") for (int k = 0; k < 2; ++k) \
;         acc[ai][bj][m][n] = mma_<I8>(Bt[n][k], At[m][k], acc[ai][bj][m][n]); __builtin_amdgcn_s_setprio(0); } while (0)
; #define PG8_WAIT_V(n) asm volatile("s_waitcnt vmcnt(" #n ")" ::: "memory")
; #define PG8_WAIT_L(n) asm volatile("s_waitcnt lgkmcnt(" #n ")" ::: "memory")
; #define PG8_BAR __builtin_amdgcn_s_barrier()
; #define PG8_SCHED __builtin_amdgcn_sched_barrier(0)
; template <class Epi, class Sched, bool ALIGN_EPI = false, bool SP2 = false, bool I8 = false>
; __device__ __forceinline__ void gemm_phase(PG8_LAS unsigned char* lds, const Gemm g, const Sched& S, const Epi& E) {
;     ...
;         for (int t = 0; t < nt; t += 2) {
;             const bool last = (t == nt - 2);
;             const char* a1 = cA + (size_t)(t + 1) * kstep;
;             const char* a2 = last ? nA : cA + (size_t)(t + 2) * kstep; const char* b2 = last ? nB : cB + (size_t)(t + 2) * kstep;
;             const char* a3 = a2 + kstep; const char* b3 = b2 + kstep;
;     ...
;             PG8_LDB(B0, 1, 0); PG8_LDB(B1, 1, 1); PG8_SCHED; PG8_LDA(At, 1, 0); PG8_STAGE(PG8_SA(0, 1), a2 + hstepA, voffA);
;             PG8_WAIT_V(8); PG8_WAIT_L(0); PG8_BAR; PG8_MMA(0, 0, At, B0); PG8_MMA(0, 1, At, B1); PG8_BAR; PG8_SCHED;
;             PG8_LDA(At, 1, 1); PG8_STAGE(PG8_SB(1, 0), b3, voffB); PG8_STAGE(PG8_SB(1, 1), b3 + hstepB, voffB); PG8_STAGE(PG8_SA(1, 0), a3, voffA);
;             PG8_WAIT_V(8); PG8_WAIT_L(0); PG8_BAR; PG8_MMA(1, 0, At, B0); PG8_MMA(1, 1, At, B1); PG8_BAR; PG8_SCHED;
	s_add_i32 s56, 0, 0x18000
	s_add_i32 s57, 0, 0x1c000
	v_add_u32_e32 v70, s56, v1
	v_add_u32_e32 v158, s57, v1
	ds_read_b128 v[50:53], v70
	ds_read_b128 v[62:65], v70 offset:1024
	ds_read_b128 v[66:69], v70 offset:2048
	ds_read_b128 v[70:73], v70 offset:3072
	ds_read_b128 v[146:149], v158
	ds_read_b128 v[150:153], v158 offset:1024
	ds_read_b128 v[154:157], v158 offset:2048
	ds_read_b128 v[158:161], v158 offset:3072
	s_add_u32 s36, s36, 0x80000
	s_addc_u32 s37, s37, 0
	s_mov_b32 m0, s45
	ds_read_b128 v[162:165], v235 offset:32768
	ds_read_b128 v[166:169], v235 offset:33792
	ds_read_b128 v[170:173], v235 offset:34816
	ds_read_b128 v[186:189], v235 offset:35840
	ds_read_b128 v[190:193], v235 offset:36864
	ds_read_b128 v[194:197], v235 offset:37888
	ds_read_b128 v[198:201], v235 offset:38912
	ds_read_b128 v[202:205], v235 offset:39936
	global_load_lds_dwordx4 v174, s[36:37]
	s_mov_b32 m0, s46
	s_nop 0
	global_load_lds_dwordx4 v176, s[36:37]
	s_waitcnt vmcnt(8) lgkmcnt(0)
	s_barrier
	s_setprio 1
	s_waitcnt lgkmcnt(0)
	v_mfma_i32_16x16x64_i8 v[142:145], v[50:53], v[162:165], v[142:145]
	v_mfma_i32_16x16x64_i8 v[138:141], v[66:69], v[162:165], v[138:141]
	v_mfma_i32_16x16x64_i8 v[126:129], v[50:53], v[170:173], v[126:129]
	v_mfma_i32_16x16x64_i8 v[122:125], v[66:69], v[170:173], v[122:125]
	v_mfma_i32_16x16x64_i8 v[110:113], v[50:53], v[190:193], v[110:113]
	v_mfma_i32_16x16x64_i8 v[106:109], v[66:69], v[190:193], v[106:109]
	v_mfma_i32_16x16x64_i8 v[94:97], v[50:53], v[198:201], v[94:97]
	v_mfma_i32_16x16x64_i8 v[90:93], v[66:69], v[198:201], v[90:93]
	v_mfma_i32_16x16x64_i8 v[142:145], v[62:65], v[166:169], v[142:145]
	v_mfma_i32_16x16x64_i8 v[138:141], v[70:73], v[166:169], v[138:141]
	v_mfma_i32_16x16x64_i8 v[126:129], v[62:65], v[186:189], v[126:129]
	v_mfma_i32_16x16x64_i8 v[122:125], v[70:73], v[186:189], v[122:125]
	v_mfma_i32_16x16x64_i8 v[110:113], v[62:65], v[194:197], v[110:113]
	v_mfma_i32_16x16x64_i8 v[106:109], v[70:73], v[194:197], v[106:109]
	v_mfma_i32_16x16x64_i8 v[94:97], v[62:65], v[202:205], v[94:97]
	v_mfma_i32_16x16x64_i8 v[90:93], v[70:73], v[202:205], v[90:93]
	s_setprio 0
	s_setprio 1
	v_mfma_i32_16x16x64_i8 v[134:137], v[146:149], v[162:165], v[134:137]
	v_mfma_i32_16x16x64_i8 v[130:133], v[154:157], v[162:165], v[130:133]
	v_mfma_i32_16x16x64_i8 v[118:121], v[146:149], v[170:173], v[118:121]
	v_mfma_i32_16x16x64_i8 v[114:117], v[154:157], v[170:173], v[114:117]
	v_mfma_i32_16x16x64_i8 v[102:105], v[146:149], v[190:193], v[102:105]
	v_mfma_i32_16x16x64_i8 v[98:101], v[154:157], v[190:193], v[98:101]
	v_mfma_i32_16x16x64_i8 v[86:89], v[146:149], v[198:201], v[86:89]
	v_mfma_i32_16x16x64_i8 v[82:85], v[154:157], v[198:201], v[82:85]
	v_mfma_i32_16x16x64_i8 v[134:137], v[150:153], v[166:169], v[134:137]
	v_mfma_i32_16x16x64_i8 v[130:133], v[158:161], v[166:169], v[130:133]
	v_mfma_i32_16x16x64_i8 v[118:121], v[150:153], v[186:189], v[118:121]
	v_mfma_i32_16x16x64_i8 v[114:117], v[158:161], v[186:189], v[114:117]
	v_mfma_i32_16x16x64_i8 v[102:105], v[150:153], v[194:197], v[102:105]
	v_mfma_i32_16x16x64_i8 v[98:101], v[158:161], v[194:197], v[98:101]
	v_mfma_i32_16x16x64_i8 v[86:89], v[150:153], v[202:205], v[86:89]
	v_mfma_i32_16x16x64_i8 v[82:85], v[158:161], v[202:205], v[82:85]
	s_setprio 0
	s_barrier
	s_add_i32 s36, s56, s40
	s_add_i32 m0, s36, 0xffffff80
	ds_read_b128 v[162:165], v235 offset:49152
	ds_read_b128 v[166:169], v235 offset:50176
	ds_read_b128 v[170:173], v235 offset:51200
	ds_read_b128 v[186:189], v235 offset:52224
	ds_read_b128 v[190:193], v235 offset:53248
	ds_read_b128 v[194:197], v235 offset:54272
	ds_read_b128 v[198:201], v235 offset:55296
	ds_read_b128 v[202:205], v235 offset:56320
	global_load_lds_dwordx4 v174, s[98:99] offset:128
	s_add_i32 m0, s36, 0x1f80
	s_add_u32 s34, s34, 0x80080
	s_addc_u32 s35, s35, 0
	s_add_i32 s36, s57, s40
	global_load_lds_dwordx4 v176, s[98:99] offset:128
	s_mov_b32 m0, s36
	s_nop 0
	global_load_lds_dwordx4 v174, s[34:35]
	s_add_i32 m0, s36, 0x2000
	s_nop 0
	global_load_lds_dwordx4 v176, s[34:35]
	s_add_i32 m0, s48, 0xffffff80
	s_nop 0
	global_load_lds_dwordx4 v174, s[100:101] offset:128
	s_add_i32 m0, s49, 0xffffff80
	s_nop 0
	global_load_lds_dwordx4 v176, s[100:101] offset:128
	s_waitcnt vmcnt(8) lgkmcnt(0)
	s_barrier
	s_setprio 1
	s_waitcnt lgkmcnt(0)
	v_mfma_i32_16x16x64_i8 v[78:81], v[50:53], v[162:165], v[78:81]
	v_mfma_i32_16x16x64_i8 v[74:77], v[66:69], v[162:165], v[74:77]
	v_mfma_i32_16x16x64_i8 v[58:61], v[50:53], v[170:173], v[58:61]
	v_mfma_i32_16x16x64_i8 v[54:57], v[66:69], v[170:173], v[54:57]
	v_mfma_i32_16x16x64_i8 v[30:33], v[50:53], v[190:193], v[30:33]
	v_mfma_i32_16x16x64_i8 v[26:29], v[66:69], v[190:193], v[26:29]
	v_mfma_i32_16x16x64_i8 v[14:17], v[50:53], v[198:201], v[14:17]
	v_mfma_i32_16x16x64_i8 v[10:13], v[66:69], v[198:201], v[10:13]
	v_mfma_i32_16x16x64_i8 v[78:81], v[62:65], v[166:169], v[78:81]
	v_mfma_i32_16x16x64_i8 v[74:77], v[70:73], v[166:169], v[74:77]
	v_mfma_i32_16x16x64_i8 v[58:61], v[62:65], v[186:189], v[58:61]
	v_mfma_i32_16x16x64_i8 v[54:57], v[70:73], v[186:189], v[54:57]
	v_mfma_i32_16x16x64_i8 v[30:33], v[62:65], v[194:197], v[30:33]
	v_mfma_i32_16x16x64_i8 v[26:29], v[70:73], v[194:197], v[26:29]
	v_mfma_i32_16x16x64_i8 v[14:17], v[62:65], v[202:205], v[14:17]
	v_mfma_i32_16x16x64_i8 v[10:13], v[70:73], v[202:205], v[10:13]
	s_setprio 0
	s_setprio 1
	v_mfma_i32_16x16x64_i8 v[34:37], v[146:149], v[162:165], v[34:37]
	v_mfma_i32_16x16x64_i8 v[70:73], v[150:153], v[166:169], v[34:37]
	v_mfma_i32_16x16x64_i8 v[34:37], v[154:157], v[162:165], v[38:41]
	v_mfma_i32_16x16x64_i8 v[66:69], v[158:161], v[166:169], v[34:37]
	v_mfma_i32_16x16x64_i8 v[34:37], v[146:149], v[170:173], v[42:45]
	v_mfma_i32_16x16x64_i8 v[50:53], v[150:153], v[186:189], v[34:37]
	v_mfma_i32_16x16x64_i8 v[34:37], v[154:157], v[170:173], v[46:49]
	v_mfma_i32_16x16x64_i8 v[22:25], v[146:149], v[190:193], v[22:25]
	v_mfma_i32_16x16x64_i8 v[18:21], v[154:157], v[190:193], v[18:21]
	v_mfma_i32_16x16x64_i8 v[6:9], v[146:149], v[198:201], v[6:9]
	v_mfma_i32_16x16x64_i8 v[2:5], v[154:157], v[198:201], v[2:5]
	v_mfma_i32_16x16x64_i8 v[46:49], v[158:161], v[186:189], v[34:37]
	v_mfma_i32_16x16x64_i8 v[22:25], v[150:153], v[194:197], v[22:25]
	v_mfma_i32_16x16x64_i8 v[18:21], v[158:161], v[194:197], v[18:21]
	v_mfma_i32_16x16x64_i8 v[6:9], v[150:153], v[202:205], v[6:9]
	v_mfma_i32_16x16x64_i8 v[2:5], v[158:161], v[202:205], v[2:5]
	s_setprio 0
	s_barrier
	s_add_i32 s55, s55, 2
	s_add_u32 s8, s8, 0x100
	s_addc_u32 s9, s9, 0
	s_add_u32 s33, s33, 0x100
	s_addc_u32 s54, s54, 0
	s_cmp_gt_u32 s55, 29
	s_cbranch_scc0 .LBB0_1721
	s_and_b64 vcc, exec, s[20:21]
	s_cbranch_vccz .LBB0_1724
	s_barrier

; #define PG8_STAGE(bufoff, gbase, voff) do { _Pragma("unroll") for (int _i = 0; _i < 2; ++_i) \
;         __builtin_amdgcn_global_load_lds((const unsigned*)((const char*)(gbase) + (voff)[_i]), (PG8_LAS unsigned*)(lds + (bufoff) + ldsw + _i * 8192), 16, 0, 0); } while (0)
; #define PG8_LDA(dst, b, h) do { _Pragma("unroll") for (int m = 0; m < 4; ++m) _Pragma("unroll") for (int k = 0; k < 2; ++k) dst[m][k] = *(const PG8_LAS bf16x8*)(lds + PG8_SA(b, h) + aoff + m * 2048 + k * 1024); } while (0)
; #define PG8_LDB(dst, b, h) do { _Pragma("unroll") for (int n = 0; n < 2; ++n) _Pragma("unroll") for (int k = 0; k < 2; ++k) dst[n][k] = *(const PG8_LAS bf16x8*)(lds + PG8_SB(b, h) + boff + n * 2048 + k * 1024); } while (0)
; #define PG8_MMA(ai, bj, At, Bt) do { __builtin_amdgcn_s_setprio(1); _Pragma("unroll") for (int m = 0; m < 4; ++m) _Pragma("unroll") for (int n = 0; n < 2; ++n) _Pragma("unroll") for (int k = 0; k < 2; ++k) \
;         acc[ai][bj][m][n] = mma_<I8>(Bt[n][k], At[m][k], acc[ai][bj][m][n]); __builtin_amdgcn_s_setprio(0); } while (0)
; #define PG8_WAIT_V(n) asm volatile("s_waitcnt vmcnt(" #n ")" ::: "memory")
; #define PG8_WAIT_L(n) asm volatile("s_waitcnt lgkmcnt(" #n ")" ::: "memory")
; #define PG8_BAR __builtin_amdgcn_s_barrier()
; #define PG8_SCHED __builtin_amdgcn_sched_barrier(0)
; template <class Epi, class Sched, bool ALIGN_EPI = false, bool SP2 = false, bool I8 = false>
; __device__ __forceinline__ void gemm_phase(PG8_LAS unsigned char* lds, const Gemm g, const Sched& S, const Epi& E) {
;     ...
;             PG8_LDB(B0, 0, 0); PG8_LDB(B1, 0, 1); PG8_SCHED; PG8_LDA(At, 0, 0); PG8_STAGE(PG8_SA(1, 1), a1 + hstepA, voffA);
;             PG8_WAIT_V(8); PG8_WAIT_L(0); PG8_BAR; PG8_MMA(0, 0, At, B0); PG8_MMA(0, 1, At, B1); PG8_BAR; PG8_SCHED;
;             PG8_LDA(At, 0, 1); PG8_STAGE(PG8_SB(0, 0), b2, voffB); PG8_STAGE(PG8_SB(0, 1), b2 + hstepB, voffB); PG8_STAGE(PG8_SA(0, 0), a2, voffA);
;             PG8_WAIT_V(8); PG8_WAIT_L(0); PG8_BAR; PG8_MMA(1, 0, At, B0); PG8_MMA(1, 1, At, B1); PG8_BAR; PG8_SCHED;
.LBB0_2014:
	ds_read_b128 v[118:121], v163
	ds_read_b128 v[126:129], v163 offset:1024
	ds_read_b128 v[130:133], v163 offset:2048
	ds_read_b128 v[134:137], v163 offset:3072
	ds_read_b128 v[168:171], v167
	ds_read_b128 v[176:179], v167 offset:1024
	ds_read_b128 v[180:183], v167 offset:2048
	ds_read_b128 v[184:187], v167 offset:3072
	s_add_u32 s38, s36, 0xfff80080
	s_addc_u32 s39, s37, -1
	s_cmp_eq_u32 s65, 28
	s_cselect_b32 s41, s27, s39
	s_cselect_b32 s40, s61, s38
	s_cselect_b32 s39, s25, s64
	s_cselect_b32 s38, s62, s63
	s_add_i32 m0, s35, 0xc000
	ds_read_b128 v[188:191], v173
	ds_read_b128 v[192:195], v173 offset:1024
	ds_read_b128 v[196:199], v173 offset:2048
	ds_read_b128 v[200:203], v173 offset:3072
	ds_read_b128 v[204:207], v173 offset:4096
	ds_read_b128 v[208:211], v173 offset:5120
	ds_read_b128 v[212:215], v173 offset:6144
	ds_read_b128 v[216:219], v173 offset:7168
	global_load_lds_dwordx4 v154, s[36:37]
	s_add_i32 m0, s35, 0xe000
	s_nop 0
	global_load_lds_dwordx4 v156, s[36:37]
	s_waitcnt vmcnt(8) lgkmcnt(0)
	s_barrier
	s_setprio 1
	s_waitcnt lgkmcnt(0)
	v_mfma_i32_16x16x64_i8 v[142:145], v[118:121], v[188:191], v[142:145]
	v_mfma_i32_16x16x64_i8 v[138:141], v[130:133], v[188:191], v[138:141]
	v_mfma_i32_16x16x64_i8 v[110:113], v[118:121], v[196:199], v[110:113]
	v_mfma_i32_16x16x64_i8 v[106:109], v[130:133], v[196:199], v[106:109]
	v_mfma_i32_16x16x64_i8 v[94:97], v[118:121], v[204:207], v[94:97]
	v_mfma_i32_16x16x64_i8 v[90:93], v[130:133], v[204:207], v[90:93]
	v_mfma_i32_16x16x64_i8 v[78:81], v[118:121], v[212:215], v[78:81]
	v_mfma_i32_16x16x64_i8 v[74:77], v[130:133], v[212:215], v[74:77]
	v_mfma_i32_16x16x64_i8 v[142:145], v[126:129], v[192:195], v[142:145]
	v_mfma_i32_16x16x64_i8 v[138:141], v[134:137], v[192:195], v[138:141]
	v_mfma_i32_16x16x64_i8 v[110:113], v[126:129], v[200:203], v[110:113]
	v_mfma_i32_16x16x64_i8 v[106:109], v[134:137], v[200:203], v[106:109]
	v_mfma_i32_16x16x64_i8 v[94:97], v[126:129], v[208:211], v[94:97]
	v_mfma_i32_16x16x64_i8 v[90:93], v[134:137], v[208:211], v[90:93]
	v_mfma_i32_16x16x64_i8 v[78:81], v[126:129], v[216:219], v[78:81]
	v_mfma_i32_16x16x64_i8 v[74:77], v[134:137], v[216:219], v[74:77]
	s_setprio 0
	s_setprio 1
	v_mfma_i32_16x16x64_i8 v[122:125], v[168:171], v[188:191], v[122:125]
	v_mfma_i32_16x16x64_i8 v[114:117], v[180:183], v[188:191], v[114:117]
	v_mfma_i32_16x16x64_i8 v[102:105], v[168:171], v[196:199], v[102:105]
	v_mfma_i32_16x16x64_i8 v[98:101], v[180:183], v[196:199], v[98:101]
	v_mfma_i32_16x16x64_i8 v[86:89], v[168:171], v[204:207], v[86:89]
	v_mfma_i32_16x16x64_i8 v[82:85], v[180:183], v[204:207], v[82:85]
	v_mfma_i32_16x16x64_i8 v[70:73], v[168:171], v[212:215], v[70:73]
	v_mfma_i32_16x16x64_i8 v[66:69], v[180:183], v[212:215], v[66:69]
	v_mfma_i32_16x16x64_i8 v[122:125], v[176:179], v[192:195], v[122:125]
	v_mfma_i32_16x16x64_i8 v[114:117], v[184:187], v[192:195], v[114:117]
	v_mfma_i32_16x16x64_i8 v[102:105], v[176:179], v[200:203], v[102:105]
	v_mfma_i32_16x16x64_i8 v[98:101], v[184:187], v[200:203], v[98:101]
	v_mfma_i32_16x16x64_i8 v[86:89], v[176:179], v[208:211], v[86:89]
	v_mfma_i32_16x16x64_i8 v[82:85], v[184:187], v[208:211], v[82:85]
	v_mfma_i32_16x16x64_i8 v[70:73], v[176:179], v[216:219], v[70:73]
	v_mfma_i32_16x16x64_i8 v[66:69], v[184:187], v[216:219], v[66:69]
	s_setprio 0
	s_barrier
	s_add_i32 s66, s54, s46
	s_mov_b64 s[98:99], s[38:39]
	s_mov_b32 m0, s66
	ds_read_b128 v[188:191], v173 offset:16384
	ds_read_b128 v[192:195], v173 offset:17408
	ds_read_b128 v[196:199], v173 offset:18432
	ds_read_b128 v[200:203], v173 offset:19456
	ds_read_b128 v[204:207], v173 offset:20480
	ds_read_b128 v[208:211], v173 offset:21504
	ds_read_b128 v[212:215], v173 offset:22528
	ds_read_b128 v[216:219], v173 offset:23552
	global_load_lds_dwordx4 v148, s[38:39]
	s_add_i32 m0, s66, 0x2000
	s_add_u32 s66, s38, 0x80000
	s_mov_b64 s[98:99], s[38:39]
	s_addc_u32 s67, s39, 0
	s_add_i32 s68, s55, s46
	global_load_lds_dwordx4 v152, s[38:39]
	s_mov_b32 m0, s68
	s_mov_b64 s[100:101], s[40:41]
	global_load_lds_dwordx4 v148, s[66:67]
	s_add_i32 m0, s68, 0x2000
	s_nop 0
	global_load_lds_dwordx4 v152, s[66:67]
	s_mov_b64 s[100:101], s[40:41]
	s_mov_b32 m0, s35
	s_nop 0
	global_load_lds_dwordx4 v146, s[40:41]
	s_mov_b32 m0, s47
	s_nop 0
	global_load_lds_dwordx4 v150, s[40:41]
	s_waitcnt vmcnt(8) lgkmcnt(0)
	s_barrier
	s_setprio 1
	s_waitcnt lgkmcnt(0)
	v_mfma_i32_16x16x64_i8 v[62:65], v[118:121], v[188:191], v[62:65]
	v_mfma_i32_16x16x64_i8 v[58:61], v[130:133], v[188:191], v[58:61]
	v_mfma_i32_16x16x64_i8 v[46:49], v[118:121], v[196:199], v[46:49]
	v_mfma_i32_16x16x64_i8 v[42:45], v[130:133], v[196:199], v[42:45]
	v_mfma_i32_16x16x64_i8 v[30:33], v[118:121], v[204:207], v[30:33]
	v_mfma_i32_16x16x64_i8 v[26:29], v[130:133], v[204:207], v[26:29]
	v_mfma_i32_16x16x64_i8 v[14:17], v[118:121], v[212:215], v[14:17]
	v_mfma_i32_16x16x64_i8 v[10:13], v[130:133], v[212:215], v[10:13]
	v_mfma_i32_16x16x64_i8 v[62:65], v[126:129], v[192:195], v[62:65]
	v_mfma_i32_16x16x64_i8 v[58:61], v[134:137], v[192:195], v[58:61]
	v_mfma_i32_16x16x64_i8 v[46:49], v[126:129], v[200:203], v[46:49]
	v_mfma_i32_16x16x64_i8 v[42:45], v[134:137], v[200:203], v[42:45]
	v_mfma_i32_16x16x64_i8 v[30:33], v[126:129], v[208:211], v[30:33]
	v_mfma_i32_16x16x64_i8 v[26:29], v[134:137], v[208:211], v[26:29]
	v_mfma_i32_16x16x64_i8 v[14:17], v[126:129], v[216:219], v[14:17]
	v_mfma_i32_16x16x64_i8 v[10:13], v[134:137], v[216:219], v[10:13]
	s_setprio 0
	s_setprio 1
	v_mfma_i32_16x16x64_i8 v[54:57], v[168:171], v[188:191], v[54:57]
	v_mfma_i32_16x16x64_i8 v[50:53], v[180:183], v[188:191], v[50:53]
	v_mfma_i32_16x16x64_i8 v[38:41], v[168:171], v[196:199], v[38:41]
	v_mfma_i32_16x16x64_i8 v[34:37], v[180:183], v[196:199], v[34:37]
	v_mfma_i32_16x16x64_i8 v[22:25], v[168:171], v[204:207], v[22:25]
	v_mfma_i32_16x16x64_i8 v[18:21], v[180:183], v[204:207], v[18:21]
	v_mfma_i32_16x16x64_i8 v[6:9], v[168:171], v[212:215], v[6:9]
	v_mfma_i32_16x16x64_i8 v[2:5], v[180:183], v[212:215], v[2:5]
	v_mfma_i32_16x16x64_i8 v[54:57], v[176:179], v[192:195], v[54:57]
	v_mfma_i32_16x16x64_i8 v[50:53], v[184:187], v[192:195], v[50:53]
	v_mfma_i32_16x16x64_i8 v[38:41], v[176:179], v[200:203], v[38:41]
	v_mfma_i32_16x16x64_i8 v[34:37], v[184:187], v[200:203], v[34:37]
	v_mfma_i32_16x16x64_i8 v[22:25], v[176:179], v[208:211], v[22:25]
	v_mfma_i32_16x16x64_i8 v[18:21], v[184:187], v[208:211], v[18:21]
	v_mfma_i32_16x16x64_i8 v[6:9], v[176:179], v[216:219], v[6:9]
	v_mfma_i32_16x16x64_i8 v[2:5], v[184:187], v[216:219], v[2:5]
	s_setprio 0
	s_barrier
; #define PG8_STAGE(bufoff, gbase, voff) do { _Pragma("unroll") for (int _i = 0; _i < 2; ++_i) \
;         __builtin_amdgcn_global_load_lds((const unsigned*)((const char*)(gbase) + (voff)[_i]), (PG8_LAS unsigned*)(lds + (bufoff) + ldsw + _i * 8192), 16, 0, 0); } while (0)
; #define PG8_LDA(dst, b, h) do { _Pragma("unroll") for (int m = 0; m < 4; ++m) _Pragma("unroll") for (int k = 0; k < 2; ++k) dst[m][k] = *(const PG8_LAS bf16x8*)(lds + PG8_SA(b, h) + aoff + m * 2048 + k * 1024); } while (0)
; #define PG8_LDB(dst, b, h) do { _Pragma("unroll") for (int n = 0; n < 2; ++n) _Pragma("unroll") for (int k = 0; k < 2; ++k) dst[n][k] = *(const PG8_LAS bf16x8*)(lds + PG8_SB(b, h) + boff + n * 2048 + k * 1024); } while (0)
; #define PG8_MMA(ai, bj, At, Bt) do { __builtin_amdgcn_s_setprio(1); _Pragma("unroll") for (int m = 0; m < 4; ++m) _Pragma("unroll") for (int n = 0; n < 2; ++n) _Pragma("unroll") for (int k = 0; k < 2; ++k) \
;         acc[ai][bj][m][n] = mma_<I8>(Bt[n][k], At[m][k], acc[ai][bj][m][n]); __builtin_amdgcn_s_setprio(0); } while (0)
; #define PG8_WAIT_V(n) asm volatile("s_waitcnt vmcnt(" #n ")" ::: "memory")
; #define PG8_WAIT_L(n) asm volatile("s_waitcnt lgkmcnt(" #n ")" ::: "memory")
; #define PG8_BAR __builtin_amdgcn_s_barrier()
; #define PG8_SCHED __builtin_amdgcn_sched_barrier(0)
; template <class Epi, class Sched, bool ALIGN_EPI = false, bool SP2 = false, bool I8 = false>
; __device__ __forceinline__ void gemm_phase(PG8_LAS unsigned char* lds, const Gemm g, const Sched& S, const Epi& E) {
;     ...
;         for (int t = 0; t < nt; t += 2) {
;             const bool last = (t == nt - 2);
;             const char* a1 = cA + (size_t)(t + 1) * kstep;
;             const char* a2 = last ? nA : cA + (size_t)(t + 2) * kstep; const char* b2 = last ? nB : cB + (size_t)(t + 2) * kstep;
;             const char* a3 = a2 + kstep; const char* b3 = b2 + kstep;
;     ...
;             PG8_LDB(B0, 1, 0); PG8_LDB(B1, 1, 1); PG8_SCHED; PG8_LDA(At, 1, 0); PG8_STAGE(PG8_SA(0, 1), a2 + hstepA, voffA);
;             PG8_WAIT_V(8); PG8_WAIT_L(0); PG8_BAR; PG8_MMA(0, 0, At, B0); PG8_MMA(0, 1, At, B1); PG8_BAR; PG8_SCHED;
;             PG8_LDA(At, 1, 1); PG8_STAGE(PG8_SB(1, 0), b3, voffB); PG8_STAGE(PG8_SB(1, 1), b3 + hstepB, voffB); PG8_STAGE(PG8_SA(1, 0), a3, voffA);
;             PG8_WAIT_V(8); PG8_WAIT_L(0); PG8_BAR; PG8_MMA(1, 0, At, B0); PG8_MMA(1, 1, At, B1); PG8_BAR; PG8_SCHED;
	s_add_i32 s66, 0, 0x18000
	s_add_i32 s67, 0, 0x1c000
	v_add_u32_e32 v134, s66, v1
	v_add_u32_e32 v162, s67, v1
	ds_read_b128 v[118:121], v134
	ds_read_b128 v[126:129], v134 offset:1024
	ds_read_b128 v[130:133], v134 offset:2048
	ds_read_b128 v[134:137], v134 offset:3072
	ds_read_b128 v[168:171], v162
	ds_read_b128 v[176:179], v162 offset:1024
	ds_read_b128 v[180:183], v162 offset:2048
	ds_read_b128 v[184:187], v162 offset:3072
	s_add_u32 s40, s40, 0x80000
	s_addc_u32 s41, s41, 0
	s_mov_b32 m0, s48
	ds_read_b128 v[188:191], v173 offset:32768
	ds_read_b128 v[192:195], v173 offset:33792
	ds_read_b128 v[196:199], v173 offset:34816
	ds_read_b128 v[200:203], v173 offset:35840
	ds_read_b128 v[204:207], v173 offset:36864
	ds_read_b128 v[208:211], v173 offset:37888
	ds_read_b128 v[212:215], v173 offset:38912
	ds_read_b128 v[216:219], v173 offset:39936
	global_load_lds_dwordx4 v146, s[40:41]
	s_mov_b32 m0, s49
	s_nop 0
	global_load_lds_dwordx4 v150, s[40:41]
	s_waitcnt vmcnt(8) lgkmcnt(0)
	s_barrier
	s_setprio 1
	s_waitcnt lgkmcnt(0)
	v_mfma_i32_16x16x64_i8 v[142:145], v[118:121], v[188:191], v[142:145]
	v_mfma_i32_16x16x64_i8 v[138:141], v[130:133], v[188:191], v[138:141]
	v_mfma_i32_16x16x64_i8 v[110:113], v[118:121], v[196:199], v[110:113]
	v_mfma_i32_16x16x64_i8 v[106:109], v[130:133], v[196:199], v[106:109]
	v_mfma_i32_16x16x64_i8 v[94:97], v[118:121], v[204:207], v[94:97]
	v_mfma_i32_16x16x64_i8 v[90:93], v[130:133], v[204:207], v[90:93]
	v_mfma_i32_16x16x64_i8 v[78:81], v[118:121], v[212:215], v[78:81]
	v_mfma_i32_16x16x64_i8 v[74:77], v[130:133], v[212:215], v[74:77]
	v_mfma_i32_16x16x64_i8 v[142:145], v[126:129], v[192:195], v[142:145]
	v_mfma_i32_16x16x64_i8 v[138:141], v[134:137], v[192:195], v[138:141]
	v_mfma_i32_16x16x64_i8 v[110:113], v[126:129], v[200:203], v[110:113]
	v_mfma_i32_16x16x64_i8 v[106:109], v[134:137], v[200:203], v[106:109]
	v_mfma_i32_16x16x64_i8 v[94:97], v[126:129], v[208:211], v[94:97]
	v_mfma_i32_16x16x64_i8 v[90:93], v[134:137], v[208:211], v[90:93]
	v_mfma_i32_16x16x64_i8 v[78:81], v[126:129], v[216:219], v[78:81]
	v_mfma_i32_16x16x64_i8 v[74:77], v[134:137], v[216:219], v[74:77]
	s_setprio 0
	s_setprio 1
	v_mfma_i32_16x16x64_i8 v[122:125], v[168:171], v[188:191], v[122:125]
	v_mfma_i32_16x16x64_i8 v[114:117], v[180:183], v[188:191], v[114:117]
	v_mfma_i32_16x16x64_i8 v[102:105], v[168:171], v[196:199], v[102:105]
	v_mfma_i32_16x16x64_i8 v[98:101], v[180:183], v[196:199], v[98:101]
	v_mfma_i32_16x16x64_i8 v[86:89], v[168:171], v[204:207], v[86:89]
	v_mfma_i32_16x16x64_i8 v[82:85], v[180:183], v[204:207], v[82:85]
	v_mfma_i32_16x16x64_i8 v[70:73], v[168:171], v[212:215], v[70:73]
	v_mfma_i32_16x16x64_i8 v[66:69], v[180:183], v[212:215], v[66:69]
	v_mfma_i32_16x16x64_i8 v[122:125], v[176:179], v[192:195], v[122:125]
	v_mfma_i32_16x16x64_i8 v[114:117], v[184:187], v[192:195], v[114:117]
	v_mfma_i32_16x16x64_i8 v[102:105], v[176:179], v[200:203], v[102:105]
	v_mfma_i32_16x16x64_i8 v[98:101], v[184:187], v[200:203], v[98:101]
	v_mfma_i32_16x16x64_i8 v[86:89], v[176:179], v[208:211], v[86:89]
	v_mfma_i32_16x16x64_i8 v[82:85], v[184:187], v[208:211], v[82:85]
	v_mfma_i32_16x16x64_i8 v[70:73], v[176:179], v[216:219], v[70:73]
	v_mfma_i32_16x16x64_i8 v[66:69], v[184:187], v[216:219], v[66:69]
	s_setprio 0
	s_barrier
	s_add_i32 s40, s66, s46
	s_add_i32 m0, s40, 0xffffff80
	ds_read_b128 v[188:191], v173 offset:49152
	ds_read_b128 v[192:195], v173 offset:50176
	ds_read_b128 v[196:199], v173 offset:51200
	ds_read_b128 v[200:203], v173 offset:52224
	ds_read_b128 v[204:207], v173 offset:53248
	ds_read_b128 v[208:211], v173 offset:54272
	ds_read_b128 v[212:215], v173 offset:55296
	ds_read_b128 v[216:219], v173 offset:56320
	global_load_lds_dwordx4 v148, s[98:99] offset:128
	s_add_i32 m0, s40, 0x1f80
	s_add_u32 s38, s38, 0x80080
	s_addc_u32 s39, s39, 0
	s_add_i32 s40, s67, s46
	global_load_lds_dwordx4 v152, s[98:99] offset:128
	s_mov_b32 m0, s40
	s_nop 0
	global_load_lds_dwordx4 v148, s[38:39]
	s_add_i32 m0, s40, 0x2000
	s_nop 0
	global_load_lds_dwordx4 v152, s[38:39]
	s_add_i32 m0, s51, 0xffffff80
	s_nop 0
	global_load_lds_dwordx4 v146, s[100:101] offset:128
	s_add_i32 m0, s52, 0xffffff80
	s_nop 0
	global_load_lds_dwordx4 v150, s[100:101] offset:128
	s_waitcnt vmcnt(8) lgkmcnt(0)
	s_barrier
	s_setprio 1
	s_waitcnt lgkmcnt(0)
	v_mfma_i32_16x16x64_i8 v[62:65], v[118:121], v[188:191], v[62:65]
	v_mfma_i32_16x16x64_i8 v[58:61], v[130:133], v[188:191], v[58:61]
	v_mfma_i32_16x16x64_i8 v[46:49], v[118:121], v[196:199], v[46:49]
	v_mfma_i32_16x16x64_i8 v[42:45], v[130:133], v[196:199], v[42:45]
	v_mfma_i32_16x16x64_i8 v[30:33], v[118:121], v[204:207], v[30:33]
	v_mfma_i32_16x16x64_i8 v[26:29], v[130:133], v[204:207], v[26:29]
	v_mfma_i32_16x16x64_i8 v[14:17], v[118:121], v[212:215], v[14:17]
	v_mfma_i32_16x16x64_i8 v[10:13], v[130:133], v[212:215], v[10:13]
	v_mfma_i32_16x16x64_i8 v[62:65], v[126:129], v[192:195], v[62:65]
	v_mfma_i32_16x16x64_i8 v[58:61], v[134:137], v[192:195], v[58:61]
	v_mfma_i32_16x16x64_i8 v[46:49], v[126:129], v[200:203], v[46:49]
	v_mfma_i32_16x16x64_i8 v[42:45], v[134:137], v[200:203], v[42:45]
	v_mfma_i32_16x16x64_i8 v[30:33], v[126:129], v[208:211], v[30:33]
	v_mfma_i32_16x16x64_i8 v[26:29], v[134:137], v[208:211], v[26:29]
	v_mfma_i32_16x16x64_i8 v[14:17], v[126:129], v[216:219], v[14:17]
	v_mfma_i32_16x16x64_i8 v[10:13], v[134:137], v[216:219], v[10:13]
	s_setprio 0
	s_setprio 1
	v_mfma_i32_16x16x64_i8 v[54:57], v[168:171], v[188:191], v[54:57]
	v_mfma_i32_16x16x64_i8 v[50:53], v[180:183], v[188:191], v[50:53]
	v_mfma_i32_16x16x64_i8 v[38:41], v[168:171], v[196:199], v[38:41]
	v_mfma_i32_16x16x64_i8 v[34:37], v[180:183], v[196:199], v[34:37]
	v_mfma_i32_16x16x64_i8 v[22:25], v[168:171], v[204:207], v[22:25]
	v_mfma_i32_16x16x64_i8 v[18:21], v[180:183], v[204:207], v[18:21]
	v_mfma_i32_16x16x64_i8 v[6:9], v[168:171], v[212:215], v[6:9]
	v_mfma_i32_16x16x64_i8 v[2:5], v[180:183], v[212:215], v[2:5]
	v_mfma_i32_16x16x64_i8 v[54:57], v[176:179], v[192:195], v[54:57]
	v_mfma_i32_16x16x64_i8 v[50:53], v[184:187], v[192:195], v[50:53]
	v_mfma_i32_16x16x64_i8 v[38:41], v[176:179], v[200:203], v[38:41]
	v_mfma_i32_16x16x64_i8 v[34:37], v[184:187], v[200:203], v[34:37]
	v_mfma_i32_16x16x64_i8 v[22:25], v[176:179], v[208:211], v[22:25]
	v_mfma_i32_16x16x64_i8 v[18:21], v[184:187], v[208:211], v[18:21]
	v_mfma_i32_16x16x64_i8 v[6:9], v[176:179], v[216:219], v[6:9]
	v_mfma_i32_16x16x64_i8 v[2:5], v[184:187], v[216:219], v[2:5]
	s_setprio 0
	s_barrier
	s_add_i32 s65, s65, 2
	s_add_u32 s36, s36, 0x100
	s_addc_u32 s37, s37, 0
	s_add_u32 s63, s63, 0x100
	s_addc_u32 s64, s64, 0
	s_cmp_gt_u32 s65, 29
	s_cbranch_scc0 .LBB0_2014
	s_and_b64 vcc, exec, s[14:15]
	s_cbranch_vccz .LBB0_2017
	s_barrier

; #define PG8_STAGE(bufoff, gbase, voff) do { _Pragma("unroll") for (int _i = 0; _i < 2; ++_i) \
;         __builtin_amdgcn_global_load_lds((const unsigned*)((const char*)(gbase) + (voff)[_i]), (PG8_LAS unsigned*)(lds + (bufoff) + ldsw + _i * 8192), 16, 0, 0); } while (0)
; #define PG8_LDA(dst, b, h) do { _Pragma("unroll") for (int m = 0; m < 4; ++m) _Pragma("unroll") for (int k = 0; k < 2; ++k) dst[m][k] = *(const PG8_LAS bf16x8*)(lds + PG8_SA(b, h) + aoff + m * 2048 + k * 1024); } while (0)
; #define PG8_LDB(dst, b, h) do { _Pragma("unroll") for (int n = 0; n < 2; ++n) _Pragma("unroll") for (int k = 0; k < 2; ++k) dst[n][k] = *(const PG8_LAS bf16x8*)(lds + PG8_SB(b, h) + boff + n * 2048 + k * 1024); } while (0)
; #define PG8_MMA(ai, bj, At, Bt) do { __builtin_amdgcn_s_setprio(1); _Pragma("unroll") for (int m = 0; m < 4; ++m) _Pragma("unroll") for (int n = 0; n < 2; ++n) _Pragma("unroll") for (int k = 0; k < 2; ++k) \
;         acc[ai][bj][m][n] = mma_<I8>(Bt[n][k], At[m][k], acc[ai][bj][m][n]); __builtin_amdgcn_s_setprio(0); } while (0)
; #define PG8_WAIT_V(n) asm volatile("s_waitcnt vmcnt(" #n ")" ::: "memory")
; #define PG8_WAIT_L(n) asm volatile("s_waitcnt lgkmcnt(" #n ")" ::: "memory")
; #define PG8_BAR __builtin_amdgcn_s_barrier()
; #define PG8_SCHED __builtin_amdgcn_sched_barrier(0)
; template <class Epi, class Sched, bool ALIGN_EPI = false, bool SP2 = false, bool I8 = false>
; __device__ __forceinline__ void gemm_phase(PG8_LAS unsigned char* lds, const Gemm g, const Sched& S, const Epi& E) {
;     ...
;             PG8_LDB(B0, 0, 0); PG8_LDB(B1, 0, 1); PG8_SCHED; PG8_LDA(At, 0, 0); PG8_STAGE(PG8_SA(1, 1), a1 + hstepA, voffA);
;             PG8_WAIT_V(8); PG8_WAIT_L(0); PG8_BAR; PG8_MMA(0, 0, At, B0); PG8_MMA(0, 1, At, B1); PG8_BAR; PG8_SCHED;
;             PG8_LDA(At, 0, 1); PG8_STAGE(PG8_SB(0, 0), b2, voffB); PG8_STAGE(PG8_SB(0, 1), b2 + hstepB, voffB); PG8_STAGE(PG8_SA(0, 0), a2, voffA);
;             PG8_WAIT_V(8); PG8_WAIT_L(0); PG8_BAR; PG8_MMA(1, 0, At, B0); PG8_MMA(1, 1, At, B1); PG8_BAR; PG8_SCHED;
.LBB0_2092:
	ds_read_b128 v[130:133], v192
	ds_read_b128 v[134:137], v192 offset:1024
	ds_read_b128 v[138:141], v192 offset:2048
	ds_read_b128 v[142:145], v192 offset:3072
	ds_read_b128 v[146:149], v193
	ds_read_b128 v[150:153], v193 offset:1024
	ds_read_b128 v[154:157], v193 offset:2048
	ds_read_b128 v[158:161], v193 offset:3072
	s_add_u32 s28, s8, 0xffc00080
	s_addc_u32 s29, s9, -1
	s_cmpk_eq_i32 s51, 0xfc
	s_cselect_b32 s31, s3, s29
	s_cselect_b32 s30, s7, s28
	s_cselect_b32 s29, s21, s50
	s_cselect_b32 s28, s23, s49
	s_add_i32 m0, s38, 0xc000
	ds_read_b128 v[162:165], v194
	ds_read_b128 v[166:169], v194 offset:1024
	ds_read_b128 v[182:185], v194 offset:2048
	ds_read_b128 v[186:189], v194 offset:3072
	ds_read_b128 v[196:199], v194 offset:4096
	ds_read_b128 v[200:203], v194 offset:5120
	ds_read_b128 v[204:207], v194 offset:6144
	ds_read_b128 v[208:211], v194 offset:7168
	global_load_lds_dwordx4 v174, s[8:9]
	s_add_i32 m0, s38, 0xe000
	s_nop 0
	global_load_lds_dwordx4 v176, s[8:9]
	s_waitcnt vmcnt(8) lgkmcnt(0)
	s_barrier
	s_setprio 1
	s_waitcnt lgkmcnt(0)
	v_mfma_f32_16x16x32_bf16 v[126:129], v[130:133], v[162:165], v[126:129]
	v_mfma_f32_16x16x32_bf16 v[122:125], v[138:141], v[162:165], v[122:125]
	v_mfma_f32_16x16x32_bf16 v[110:113], v[130:133], v[182:185], v[110:113]
	v_mfma_f32_16x16x32_bf16 v[106:109], v[138:141], v[182:185], v[106:109]
	v_mfma_f32_16x16x32_bf16 v[94:97], v[130:133], v[196:199], v[94:97]
	v_mfma_f32_16x16x32_bf16 v[90:93], v[138:141], v[196:199], v[90:93]
	v_mfma_f32_16x16x32_bf16 v[78:81], v[130:133], v[204:207], v[78:81]
	v_mfma_f32_16x16x32_bf16 v[74:77], v[138:141], v[204:207], v[74:77]
	v_mfma_f32_16x16x32_bf16 v[126:129], v[134:137], v[166:169], v[126:129]
	v_mfma_f32_16x16x32_bf16 v[122:125], v[142:145], v[166:169], v[122:125]
	v_mfma_f32_16x16x32_bf16 v[110:113], v[134:137], v[186:189], v[110:113]
	v_mfma_f32_16x16x32_bf16 v[106:109], v[142:145], v[186:189], v[106:109]
	v_mfma_f32_16x16x32_bf16 v[94:97], v[134:137], v[200:203], v[94:97]
	v_mfma_f32_16x16x32_bf16 v[90:93], v[142:145], v[200:203], v[90:93]
	v_mfma_f32_16x16x32_bf16 v[78:81], v[134:137], v[208:211], v[78:81]
	v_mfma_f32_16x16x32_bf16 v[74:77], v[142:145], v[208:211], v[74:77]
	s_setprio 0
	s_setprio 1
	v_mfma_f32_16x16x32_bf16 v[118:121], v[146:149], v[162:165], v[118:121]
	v_mfma_f32_16x16x32_bf16 v[114:117], v[154:157], v[162:165], v[114:117]
	v_mfma_f32_16x16x32_bf16 v[102:105], v[146:149], v[182:185], v[102:105]
	v_mfma_f32_16x16x32_bf16 v[98:101], v[154:157], v[182:185], v[98:101]
	v_mfma_f32_16x16x32_bf16 v[86:89], v[146:149], v[196:199], v[86:89]
	v_mfma_f32_16x16x32_bf16 v[82:85], v[154:157], v[196:199], v[82:85]
	v_mfma_f32_16x16x32_bf16 v[70:73], v[146:149], v[204:207], v[70:73]
	v_mfma_f32_16x16x32_bf16 v[66:69], v[154:157], v[204:207], v[66:69]
	v_mfma_f32_16x16x32_bf16 v[118:121], v[150:153], v[166:169], v[118:121]
	v_mfma_f32_16x16x32_bf16 v[114:117], v[158:161], v[166:169], v[114:117]
	v_mfma_f32_16x16x32_bf16 v[102:105], v[150:153], v[186:189], v[102:105]
	v_mfma_f32_16x16x32_bf16 v[98:101], v[158:161], v[186:189], v[98:101]
	v_mfma_f32_16x16x32_bf16 v[86:89], v[150:153], v[200:203], v[86:89]
	v_mfma_f32_16x16x32_bf16 v[82:85], v[158:161], v[200:203], v[82:85]
	v_mfma_f32_16x16x32_bf16 v[70:73], v[150:153], v[208:211], v[70:73]
	v_mfma_f32_16x16x32_bf16 v[66:69], v[158:161], v[208:211], v[66:69]
	s_setprio 0
	s_barrier
	s_add_i32 s52, s47, s33
	s_mov_b64 s[98:99], s[28:29]
	s_mov_b32 m0, s52
	ds_read_b128 v[162:165], v194 offset:16384
	ds_read_b128 v[166:169], v194 offset:17408
	ds_read_b128 v[182:185], v194 offset:18432
	ds_read_b128 v[186:189], v194 offset:19456
	ds_read_b128 v[196:199], v194 offset:20480
	ds_read_b128 v[200:203], v194 offset:21504
	ds_read_b128 v[204:207], v194 offset:22528
	ds_read_b128 v[208:211], v194 offset:23552
	global_load_lds_dwordx4 v170, s[28:29]
	s_add_i32 m0, s52, 0x2000
	s_add_u32 s52, s28, 0x400000
	s_mov_b64 s[98:99], s[28:29]
	s_addc_u32 s53, s29, 0
	s_add_i32 s54, s48, s33
	global_load_lds_dwordx4 v172, s[28:29]
	s_mov_b32 m0, s54
	s_mov_b64 s[100:101], s[30:31]
	global_load_lds_dwordx4 v170, s[52:53]
	s_add_i32 m0, s54, 0x2000
	s_nop 0
	global_load_lds_dwordx4 v172, s[52:53]
	s_mov_b64 s[100:101], s[30:31]
	s_mov_b32 m0, s38
	s_nop 0
	global_load_lds_dwordx4 v170, s[30:31]
	s_mov_b32 m0, s39
	s_nop 0
	global_load_lds_dwordx4 v172, s[30:31]
	s_waitcnt vmcnt(8) lgkmcnt(0)
	s_barrier
	s_setprio 1
	s_waitcnt lgkmcnt(0)
	v_mfma_f32_16x16x32_bf16 v[62:65], v[130:133], v[162:165], v[62:65]
	v_mfma_f32_16x16x32_bf16 v[58:61], v[138:141], v[162:165], v[58:61]
	v_mfma_f32_16x16x32_bf16 v[46:49], v[130:133], v[182:185], v[46:49]
	v_mfma_f32_16x16x32_bf16 v[42:45], v[138:141], v[182:185], v[42:45]
	v_mfma_f32_16x16x32_bf16 v[30:33], v[130:133], v[196:199], v[30:33]
	v_mfma_f32_16x16x32_bf16 v[26:29], v[138:141], v[196:199], v[26:29]
	v_mfma_f32_16x16x32_bf16 v[22:25], v[130:133], v[204:207], v[22:25]
	v_mfma_f32_16x16x32_bf16 v[10:13], v[138:141], v[204:207], v[10:13]
	v_mfma_f32_16x16x32_bf16 v[62:65], v[134:137], v[166:169], v[62:65]
	v_mfma_f32_16x16x32_bf16 v[58:61], v[142:145], v[166:169], v[58:61]
	v_mfma_f32_16x16x32_bf16 v[46:49], v[134:137], v[186:189], v[46:49]
	v_mfma_f32_16x16x32_bf16 v[42:45], v[142:145], v[186:189], v[42:45]
	v_mfma_f32_16x16x32_bf16 v[30:33], v[134:137], v[200:203], v[30:33]
	v_mfma_f32_16x16x32_bf16 v[26:29], v[142:145], v[200:203], v[26:29]
	v_mfma_f32_16x16x32_bf16 v[22:25], v[134:137], v[208:211], v[22:25]
	v_mfma_f32_16x16x32_bf16 v[10:13], v[142:145], v[208:211], v[10:13]
	s_setprio 0
	s_setprio 1
	v_mfma_f32_16x16x32_bf16 v[54:57], v[146:149], v[162:165], v[54:57]
	v_mfma_f32_16x16x32_bf16 v[50:53], v[154:157], v[162:165], v[50:53]
	v_mfma_f32_16x16x32_bf16 v[38:41], v[146:149], v[182:185], v[38:41]
	v_mfma_f32_16x16x32_bf16 v[34:37], v[154:157], v[182:185], v[34:37]
	v_mfma_f32_16x16x32_bf16 v[18:21], v[146:149], v[196:199], v[18:21]
	v_mfma_f32_16x16x32_bf16 v[14:17], v[154:157], v[196:199], v[14:17]
	v_mfma_f32_16x16x32_bf16 v[6:9], v[146:149], v[204:207], v[6:9]
	v_mfma_f32_16x16x32_bf16 v[2:5], v[154:157], v[204:207], v[2:5]
	v_mfma_f32_16x16x32_bf16 v[54:57], v[150:153], v[166:169], v[54:57]
	v_mfma_f32_16x16x32_bf16 v[50:53], v[158:161], v[166:169], v[50:53]
	v_mfma_f32_16x16x32_bf16 v[38:41], v[150:153], v[186:189], v[38:41]
	v_mfma_f32_16x16x32_bf16 v[34:37], v[158:161], v[186:189], v[34:37]
	v_mfma_f32_16x16x32_bf16 v[18:21], v[150:153], v[200:203], v[18:21]
	v_mfma_f32_16x16x32_bf16 v[14:17], v[158:161], v[200:203], v[14:17]
	v_mfma_f32_16x16x32_bf16 v[6:9], v[150:153], v[208:211], v[6:9]
	v_mfma_f32_16x16x32_bf16 v[2:5], v[158:161], v[208:211], v[2:5]
	s_setprio 0
	s_barrier
; #define PG8_STAGE(bufoff, gbase, voff) do { _Pragma("unroll") for (int _i = 0; _i < 2; ++_i) \
;         __builtin_amdgcn_global_load_lds((const unsigned*)((const char*)(gbase) + (voff)[_i]), (PG8_LAS unsigned*)(lds + (bufoff) + ldsw + _i * 8192), 16, 0, 0); } while (0)
; #define PG8_LDA(dst, b, h) do { _Pragma("unroll") for (int m = 0; m < 4; ++m) _Pragma("unroll") for (int k = 0; k < 2; ++k) dst[m][k] = *(const PG8_LAS bf16x8*)(lds + PG8_SA(b, h) + aoff + m * 2048 + k * 1024); } while (0)
; #define PG8_LDB(dst, b, h) do { _Pragma("unroll") for (int n = 0; n < 2; ++n) _Pragma("unroll") for (int k = 0; k < 2; ++k) dst[n][k] = *(const PG8_LAS bf16x8*)(lds + PG8_SB(b, h) + boff + n * 2048 + k * 1024); } while (0)
; #define PG8_MMA(ai, bj, At, Bt) do { __builtin_amdgcn_s_setprio(1); _Pragma("unroll") for (int m = 0; m < 4; ++m) _Pragma("unroll") for (int n = 0; n < 2; ++n) _Pragma("unroll") for (int k = 0; k < 2; ++k) \
;         acc[ai][bj][m][n] = mma_<I8>(Bt[n][k], At[m][k], acc[ai][bj][m][n]); __builtin_amdgcn_s_setprio(0); } while (0)
; #define PG8_WAIT_V(n) asm volatile("s_waitcnt vmcnt(" #n ")" ::: "memory")
; #define PG8_WAIT_L(n) asm volatile("s_waitcnt lgkmcnt(" #n ")" ::: "memory")
; #define PG8_BAR __builtin_amdgcn_s_barrier()
; #define PG8_SCHED __builtin_amdgcn_sched_barrier(0)
; template <class Epi, class Sched, bool ALIGN_EPI = false, bool SP2 = false, bool I8 = false>
; __device__ __forceinline__ void gemm_phase(PG8_LAS unsigned char* lds, const Gemm g, const Sched& S, const Epi& E) {
;     ...
;         for (int t = 0; t < nt; t += 2) {
;             const bool last = (t == nt - 2);
;             const char* a1 = cA + (size_t)(t + 1) * kstep;
;             const char* a2 = last ? nA : cA + (size_t)(t + 2) * kstep; const char* b2 = last ? nB : cB + (size_t)(t + 2) * kstep;
;             const char* a3 = a2 + kstep; const char* b3 = b2 + kstep;
;     ...
;             PG8_LDB(B0, 1, 0); PG8_LDB(B1, 1, 1); PG8_SCHED; PG8_LDA(At, 1, 0); PG8_STAGE(PG8_SA(0, 1), a2 + hstepA, voffA);
;             PG8_WAIT_V(8); PG8_WAIT_L(0); PG8_BAR; PG8_MMA(0, 0, At, B0); PG8_MMA(0, 1, At, B1); PG8_BAR; PG8_SCHED;
;             PG8_LDA(At, 1, 1); PG8_STAGE(PG8_SB(1, 0), b3, voffB); PG8_STAGE(PG8_SB(1, 1), b3 + hstepB, voffB); PG8_STAGE(PG8_SA(1, 0), a3, voffA);
;             PG8_WAIT_V(8); PG8_WAIT_L(0); PG8_BAR; PG8_MMA(1, 0, At, B0); PG8_MMA(1, 1, At, B1); PG8_BAR; PG8_SCHED;
	s_add_i32 s52, 0, 0x18000
	s_add_i32 s53, 0, 0x1c000
	v_add_u32_e32 v142, s52, v1
	v_add_u32_e32 v158, s53, v1
	ds_read_b128 v[130:133], v142
	ds_read_b128 v[134:137], v142 offset:1024
	ds_read_b128 v[138:141], v142 offset:2048
	ds_read_b128 v[142:145], v142 offset:3072
	ds_read_b128 v[146:149], v158
	ds_read_b128 v[150:153], v158 offset:1024
	ds_read_b128 v[154:157], v158 offset:2048
	ds_read_b128 v[158:161], v158 offset:3072
	s_add_u32 s30, s30, 0x400000
	s_addc_u32 s31, s31, 0
	s_mov_b32 m0, s40
	ds_read_b128 v[162:165], v194 offset:32768
	ds_read_b128 v[166:169], v194 offset:33792
	ds_read_b128 v[182:185], v194 offset:34816
	ds_read_b128 v[186:189], v194 offset:35840
	ds_read_b128 v[196:199], v194 offset:36864
	ds_read_b128 v[200:203], v194 offset:37888
	ds_read_b128 v[204:207], v194 offset:38912
	ds_read_b128 v[208:211], v194 offset:39936
	global_load_lds_dwordx4 v170, s[30:31]
	s_mov_b32 m0, s41
	s_nop 0
	global_load_lds_dwordx4 v172, s[30:31]
	s_waitcnt vmcnt(8) lgkmcnt(0)
	s_barrier
	s_setprio 1
	s_waitcnt lgkmcnt(0)
	v_mfma_f32_16x16x32_bf16 v[126:129], v[130:133], v[162:165], v[126:129]
	v_mfma_f32_16x16x32_bf16 v[122:125], v[138:141], v[162:165], v[122:125]
	v_mfma_f32_16x16x32_bf16 v[110:113], v[130:133], v[182:185], v[110:113]
	v_mfma_f32_16x16x32_bf16 v[106:109], v[138:141], v[182:185], v[106:109]
	v_mfma_f32_16x16x32_bf16 v[94:97], v[130:133], v[196:199], v[94:97]
	v_mfma_f32_16x16x32_bf16 v[90:93], v[138:141], v[196:199], v[90:93]
	v_mfma_f32_16x16x32_bf16 v[78:81], v[130:133], v[204:207], v[78:81]
	v_mfma_f32_16x16x32_bf16 v[74:77], v[138:141], v[204:207], v[74:77]
	v_mfma_f32_16x16x32_bf16 v[126:129], v[134:137], v[166:169], v[126:129]
	v_mfma_f32_16x16x32_bf16 v[122:125], v[142:145], v[166:169], v[122:125]
	v_mfma_f32_16x16x32_bf16 v[110:113], v[134:137], v[186:189], v[110:113]
	v_mfma_f32_16x16x32_bf16 v[106:109], v[142:145], v[186:189], v[106:109]
	v_mfma_f32_16x16x32_bf16 v[94:97], v[134:137], v[200:203], v[94:97]
	v_mfma_f32_16x16x32_bf16 v[90:93], v[142:145], v[200:203], v[90:93]
	v_mfma_f32_16x16x32_bf16 v[78:81], v[134:137], v[208:211], v[78:81]
	v_mfma_f32_16x16x32_bf16 v[74:77], v[142:145], v[208:211], v[74:77]
	s_setprio 0
	s_setprio 1
	v_mfma_f32_16x16x32_bf16 v[118:121], v[146:149], v[162:165], v[118:121]
	v_mfma_f32_16x16x32_bf16 v[114:117], v[154:157], v[162:165], v[114:117]
	v_mfma_f32_16x16x32_bf16 v[102:105], v[146:149], v[182:185], v[102:105]
	v_mfma_f32_16x16x32_bf16 v[98:101], v[154:157], v[182:185], v[98:101]
	v_mfma_f32_16x16x32_bf16 v[86:89], v[146:149], v[196:199], v[86:89]
	v_mfma_f32_16x16x32_bf16 v[82:85], v[154:157], v[196:199], v[82:85]
	v_mfma_f32_16x16x32_bf16 v[70:73], v[146:149], v[204:207], v[70:73]
	v_mfma_f32_16x16x32_bf16 v[66:69], v[154:157], v[204:207], v[66:69]
	v_mfma_f32_16x16x32_bf16 v[118:121], v[150:153], v[166:169], v[118:121]
	v_mfma_f32_16x16x32_bf16 v[114:117], v[158:161], v[166:169], v[114:117]
	v_mfma_f32_16x16x32_bf16 v[102:105], v[150:153], v[186:189], v[102:105]
	v_mfma_f32_16x16x32_bf16 v[98:101], v[158:161], v[186:189], v[98:101]
	v_mfma_f32_16x16x32_bf16 v[86:89], v[150:153], v[200:203], v[86:89]
	v_mfma_f32_16x16x32_bf16 v[82:85], v[158:161], v[200:203], v[82:85]
	v_mfma_f32_16x16x32_bf16 v[70:73], v[150:153], v[208:211], v[70:73]
	v_mfma_f32_16x16x32_bf16 v[66:69], v[158:161], v[208:211], v[66:69]
	s_setprio 0
	s_barrier
	s_add_i32 s30, s52, s33
	s_add_i32 m0, s30, 0xffffff80
	ds_read_b128 v[162:165], v194 offset:49152
	ds_read_b128 v[166:169], v194 offset:50176
	ds_read_b128 v[182:185], v194 offset:51200
	ds_read_b128 v[186:189], v194 offset:52224
	ds_read_b128 v[196:199], v194 offset:53248
	ds_read_b128 v[200:203], v194 offset:54272
	ds_read_b128 v[204:207], v194 offset:55296
	ds_read_b128 v[208:211], v194 offset:56320
	global_load_lds_dwordx4 v170, s[98:99] offset:128
	s_add_i32 m0, s30, 0x1f80
	s_add_u32 s28, s28, 0x400080
	s_addc_u32 s29, s29, 0
	s_add_i32 s30, s53, s33
	global_load_lds_dwordx4 v172, s[98:99] offset:128
	s_mov_b32 m0, s30
	s_nop 0
	global_load_lds_dwordx4 v170, s[28:29]
	s_add_i32 m0, s30, 0x2000
	s_nop 0
	global_load_lds_dwordx4 v172, s[28:29]
	s_add_i32 m0, s43, 0xffffff80
	s_nop 0
	global_load_lds_dwordx4 v170, s[100:101] offset:128
	s_add_i32 m0, s44, 0xffffff80
	s_nop 0
	global_load_lds_dwordx4 v172, s[100:101] offset:128
	s_waitcnt vmcnt(8) lgkmcnt(0)
	s_barrier
	s_setprio 1
	s_waitcnt lgkmcnt(0)
	v_mfma_f32_16x16x32_bf16 v[62:65], v[130:133], v[162:165], v[62:65]
	v_mfma_f32_16x16x32_bf16 v[58:61], v[138:141], v[162:165], v[58:61]
	v_mfma_f32_16x16x32_bf16 v[46:49], v[130:133], v[182:185], v[46:49]
	v_mfma_f32_16x16x32_bf16 v[42:45], v[138:141], v[182:185], v[42:45]
	v_mfma_f32_16x16x32_bf16 v[30:33], v[130:133], v[196:199], v[30:33]
	v_mfma_f32_16x16x32_bf16 v[26:29], v[138:141], v[196:199], v[26:29]
	v_mfma_f32_16x16x32_bf16 v[22:25], v[130:133], v[204:207], v[22:25]
	v_mfma_f32_16x16x32_bf16 v[10:13], v[138:141], v[204:207], v[10:13]
	v_mfma_f32_16x16x32_bf16 v[62:65], v[134:137], v[166:169], v[62:65]
	v_mfma_f32_16x16x32_bf16 v[58:61], v[142:145], v[166:169], v[58:61]
	v_mfma_f32_16x16x32_bf16 v[46:49], v[134:137], v[186:189], v[46:49]
	v_mfma_f32_16x16x32_bf16 v[42:45], v[142:145], v[186:189], v[42:45]
	v_mfma_f32_16x16x32_bf16 v[30:33], v[134:137], v[200:203], v[30:33]
	v_mfma_f32_16x16x32_bf16 v[26:29], v[142:145], v[200:203], v[26:29]
	v_mfma_f32_16x16x32_bf16 v[22:25], v[134:137], v[208:211], v[22:25]
	v_mfma_f32_16x16x32_bf16 v[10:13], v[142:145], v[208:211], v[10:13]
	s_setprio 0
	s_setprio 1
	v_mfma_f32_16x16x32_bf16 v[54:57], v[146:149], v[162:165], v[54:57]
	v_mfma_f32_16x16x32_bf16 v[50:53], v[154:157], v[162:165], v[50:53]
	v_mfma_f32_16x16x32_bf16 v[38:41], v[146:149], v[182:185], v[38:41]
	v_mfma_f32_16x16x32_bf16 v[34:37], v[154:157], v[182:185], v[34:37]
	v_mfma_f32_16x16x32_bf16 v[18:21], v[146:149], v[196:199], v[18:21]
	v_mfma_f32_16x16x32_bf16 v[14:17], v[154:157], v[196:199], v[14:17]
	v_mfma_f32_16x16x32_bf16 v[6:9], v[146:149], v[204:207], v[6:9]
	v_mfma_f32_16x16x32_bf16 v[2:5], v[154:157], v[204:207], v[2:5]
	v_mfma_f32_16x16x32_bf16 v[54:57], v[150:153], v[166:169], v[54:57]
	v_mfma_f32_16x16x32_bf16 v[50:53], v[158:161], v[166:169], v[50:53]
	v_mfma_f32_16x16x32_bf16 v[38:41], v[150:153], v[186:189], v[38:41]
	v_mfma_f32_16x16x32_bf16 v[34:37], v[158:161], v[186:189], v[34:37]
	v_mfma_f32_16x16x32_bf16 v[18:21], v[150:153], v[200:203], v[18:21]
	v_mfma_f32_16x16x32_bf16 v[14:17], v[158:161], v[200:203], v[14:17]
	v_mfma_f32_16x16x32_bf16 v[6:9], v[150:153], v[208:211], v[6:9]
	v_mfma_f32_16x16x32_bf16 v[2:5], v[158:161], v[208:211], v[2:5]
	s_setprio 0
	s_barrier
	s_add_i32 s51, s51, 2
	s_add_u32 s8, s8, 0x100
	s_addc_u32 s9, s9, 0
	s_add_u32 s49, s49, 0x100
	s_addc_u32 s50, s50, 0
	s_cmpk_gt_u32 s51, 0xfd
	s_cbranch_scc0 .LBB0_2092
	s_and_b64 vcc, exec, s[16:17]
	s_cbranch_vccz .LBB0_2095
	s_barrier

; #define PG8_STAGE(bufoff, gbase, voff) do { _Pragma("unroll") for (int _i = 0; _i < 2; ++_i) \
;         __builtin_amdgcn_global_load_lds((const unsigned*)((const char*)(gbase) + (voff)[_i]), (PG8_LAS unsigned*)(lds + (bufoff) + ldsw + _i * 8192), 16, 0, 0); } while (0)
; #define PG8_LDA(dst, b, h) do { _Pragma("unroll") for (int m = 0; m < 4; ++m) _Pragma("unroll") for (int k = 0; k < 2; ++k) dst[m][k] = *(const PG8_LAS bf16x8*)(lds + PG8_SA(b, h) + aoff + m * 2048 + k * 1024); } while (0)
; #define PG8_LDB(dst, b, h) do { _Pragma("unroll") for (int n = 0; n < 2; ++n) _Pragma("unroll") for (int k = 0; k < 2; ++k) dst[n][k] = *(const PG8_LAS bf16x8*)(lds + PG8_SB(b, h) + boff + n * 2048 + k * 1024); } while (0)
; #define PG8_MMA(ai, bj, At, Bt) do { __builtin_amdgcn_s_setprio(1); _Pragma("unroll") for (int m = 0; m < 4; ++m) _Pragma("unroll") for (int n = 0; n < 2; ++n) _Pragma("unroll") for (int k = 0; k < 2; ++k) \
;         acc[ai][bj][m][n] = mma_<I8>(Bt[n][k], At[m][k], acc[ai][bj][m][n]); __builtin_amdgcn_s_setprio(0); } while (0)
; #define PG8_WAIT_V(n) asm volatile("s_waitcnt vmcnt(" #n ")" ::: "memory")
; #define PG8_WAIT_L(n) asm volatile("s_waitcnt lgkmcnt(" #n ")" ::: "memory")
; #define PG8_BAR __builtin_amdgcn_s_barrier()
; #define PG8_SCHED __builtin_amdgcn_sched_barrier(0)
; template <class Epi, class Sched, bool ALIGN_EPI = false, bool SP2 = false, bool I8 = false>
; __device__ __forceinline__ void gemm_phase(PG8_LAS unsigned char* lds, const Gemm g, const Sched& S, const Epi& E) {
;     ...
;             PG8_LDB(B0, 0, 0); PG8_LDB(B1, 0, 1); PG8_SCHED; PG8_LDA(At, 0, 0); PG8_STAGE(PG8_SA(1, 1), a1 + hstepA, voffA);
;             PG8_WAIT_V(8); PG8_WAIT_L(0); PG8_BAR; PG8_MMA(0, 0, At, B0); PG8_MMA(0, 1, At, B1); PG8_BAR; PG8_SCHED;
;             PG8_LDA(At, 0, 1); PG8_STAGE(PG8_SB(0, 0), b2, voffB); PG8_STAGE(PG8_SB(0, 1), b2 + hstepB, voffB); PG8_STAGE(PG8_SA(0, 0), a2, voffA);
;             PG8_WAIT_V(8); PG8_WAIT_L(0); PG8_BAR; PG8_MMA(1, 0, At, B0); PG8_MMA(1, 1, At, B1); PG8_BAR; PG8_SCHED;
.LBB0_2322:
	ds_read_b128 v[58:61], v183
	ds_read_b128 v[66:69], v183 offset:1024
	ds_read_b128 v[74:77], v183 offset:2048
	ds_read_b128 v[78:81], v183 offset:3072
	ds_read_b128 v[146:149], v189
	ds_read_b128 v[150:153], v189 offset:1024
	ds_read_b128 v[154:157], v189 offset:2048
	ds_read_b128 v[158:161], v189 offset:3072
	s_add_u32 s28, s26, 0xfff80080
	s_addc_u32 s29, s27, -1
	s_cmp_eq_u32 s53, 28
	s_cselect_b32 s31, s21, s29
	s_cselect_b32 s30, s49, s28
	s_cselect_b32 s29, s19, s52
	s_cselect_b32 s28, s50, s51
	s_add_i32 m0, s3, 0xc000
	ds_read_b128 v[162:165], v193
	ds_read_b128 v[178:181], v193 offset:1024
	ds_read_b128 v[184:187], v193 offset:2048
	ds_read_b128 v[198:201], v193 offset:3072
	ds_read_b128 v[202:205], v193 offset:4096
	ds_read_b128 v[206:209], v193 offset:5120
	ds_read_b128 v[210:213], v193 offset:6144
	ds_read_b128 v[214:217], v193 offset:7168
	global_load_lds_dwordx4 v170, s[26:27]
	s_add_i32 m0, s3, 0xe000
	s_nop 0
	global_load_lds_dwordx4 v172, s[26:27]
	s_waitcnt vmcnt(8) lgkmcnt(0)
	s_barrier
	s_setprio 1
	s_waitcnt lgkmcnt(0)
	v_mfma_i32_16x16x64_i8 v[142:145], v[58:61], v[162:165], v[142:145]
	v_mfma_i32_16x16x64_i8 v[138:141], v[74:77], v[162:165], v[138:141]
	v_mfma_i32_16x16x64_i8 v[126:129], v[58:61], v[184:187], v[126:129]
	v_mfma_i32_16x16x64_i8 v[122:125], v[74:77], v[184:187], v[122:125]
	v_mfma_i32_16x16x64_i8 v[110:113], v[58:61], v[202:205], v[110:113]
	v_mfma_i32_16x16x64_i8 v[106:109], v[74:77], v[202:205], v[106:109]
	v_mfma_i32_16x16x64_i8 v[94:97], v[58:61], v[210:213], v[94:97]
	v_mfma_i32_16x16x64_i8 v[90:93], v[74:77], v[210:213], v[90:93]
	v_mfma_i32_16x16x64_i8 v[142:145], v[66:69], v[178:181], v[142:145]
	v_mfma_i32_16x16x64_i8 v[138:141], v[78:81], v[178:181], v[138:141]
	v_mfma_i32_16x16x64_i8 v[126:129], v[66:69], v[198:201], v[126:129]
	v_mfma_i32_16x16x64_i8 v[122:125], v[78:81], v[198:201], v[122:125]
	v_mfma_i32_16x16x64_i8 v[110:113], v[66:69], v[206:209], v[110:113]
	v_mfma_i32_16x16x64_i8 v[106:109], v[78:81], v[206:209], v[106:109]
	v_mfma_i32_16x16x64_i8 v[94:97], v[66:69], v[214:217], v[94:97]
	v_mfma_i32_16x16x64_i8 v[90:93], v[78:81], v[214:217], v[90:93]
	s_setprio 0
	s_setprio 1
	v_mfma_i32_16x16x64_i8 v[134:137], v[146:149], v[162:165], v[134:137]
	v_mfma_i32_16x16x64_i8 v[130:133], v[154:157], v[162:165], v[130:133]
	v_mfma_i32_16x16x64_i8 v[118:121], v[146:149], v[184:187], v[118:121]
	v_mfma_i32_16x16x64_i8 v[114:117], v[154:157], v[184:187], v[114:117]
	v_mfma_i32_16x16x64_i8 v[102:105], v[146:149], v[202:205], v[102:105]
	v_mfma_i32_16x16x64_i8 v[98:101], v[154:157], v[202:205], v[98:101]
	v_mfma_i32_16x16x64_i8 v[86:89], v[146:149], v[210:213], v[86:89]
	v_mfma_i32_16x16x64_i8 v[82:85], v[154:157], v[210:213], v[82:85]
	v_mfma_i32_16x16x64_i8 v[134:137], v[150:153], v[178:181], v[134:137]
	v_mfma_i32_16x16x64_i8 v[130:133], v[158:161], v[178:181], v[130:133]
	v_mfma_i32_16x16x64_i8 v[118:121], v[150:153], v[198:201], v[118:121]
	v_mfma_i32_16x16x64_i8 v[114:117], v[158:161], v[198:201], v[114:117]
	v_mfma_i32_16x16x64_i8 v[102:105], v[150:153], v[206:209], v[102:105]
	v_mfma_i32_16x16x64_i8 v[98:101], v[158:161], v[206:209], v[98:101]
	v_mfma_i32_16x16x64_i8 v[86:89], v[150:153], v[214:217], v[86:89]
	v_mfma_i32_16x16x64_i8 v[82:85], v[158:161], v[214:217], v[82:85]
	s_setprio 0
	s_barrier
	s_add_i32 s54, s46, s38
	s_mov_b64 s[98:99], s[28:29]
	s_mov_b32 m0, s54
	ds_read_b128 v[162:165], v193 offset:16384
	ds_read_b128 v[178:181], v193 offset:17408
	ds_read_b128 v[184:187], v193 offset:18432
	ds_read_b128 v[198:201], v193 offset:19456
	ds_read_b128 v[202:205], v193 offset:20480
	ds_read_b128 v[206:209], v193 offset:21504
	ds_read_b128 v[210:213], v193 offset:22528
	ds_read_b128 v[214:217], v193 offset:23552
	global_load_lds_dwordx4 v166, s[28:29]
	s_add_i32 m0, s54, 0x2000
	s_add_u32 s54, s28, 0x80000
	s_mov_b64 s[98:99], s[28:29]
	s_addc_u32 s55, s29, 0
	s_add_i32 s56, s47, s38
	global_load_lds_dwordx4 v168, s[28:29]
	s_mov_b32 m0, s56
	s_mov_b64 s[100:101], s[30:31]
	global_load_lds_dwordx4 v166, s[54:55]
	s_add_i32 m0, s56, 0x2000
	s_nop 0
	global_load_lds_dwordx4 v168, s[54:55]
	s_mov_b64 s[100:101], s[30:31]
	s_mov_b32 m0, s3
	s_nop 0
	global_load_lds_dwordx4 v166, s[30:31]
	s_mov_b32 m0, s39
	s_nop 0
	global_load_lds_dwordx4 v168, s[30:31]
	s_waitcnt vmcnt(8) lgkmcnt(0)
	s_barrier
	s_setprio 1
	s_waitcnt lgkmcnt(0)
	v_mfma_i32_16x16x64_i8 v[70:73], v[58:61], v[162:165], v[70:73]
	v_mfma_i32_16x16x64_i8 v[62:65], v[74:77], v[162:165], v[62:65]
	v_mfma_i32_16x16x64_i8 v[46:49], v[58:61], v[184:187], v[46:49]
	v_mfma_i32_16x16x64_i8 v[42:45], v[74:77], v[184:187], v[42:45]
	v_mfma_i32_16x16x64_i8 v[30:33], v[58:61], v[202:205], v[30:33]
	v_mfma_i32_16x16x64_i8 v[26:29], v[74:77], v[202:205], v[26:29]
	v_mfma_i32_16x16x64_i8 v[14:17], v[58:61], v[210:213], v[14:17]
	v_mfma_i32_16x16x64_i8 v[10:13], v[74:77], v[210:213], v[10:13]
	v_mfma_i32_16x16x64_i8 v[70:73], v[66:69], v[178:181], v[70:73]
	v_mfma_i32_16x16x64_i8 v[62:65], v[78:81], v[178:181], v[62:65]
	v_mfma_i32_16x16x64_i8 v[46:49], v[66:69], v[198:201], v[46:49]
	v_mfma_i32_16x16x64_i8 v[42:45], v[78:81], v[198:201], v[42:45]
	v_mfma_i32_16x16x64_i8 v[30:33], v[66:69], v[206:209], v[30:33]
	v_mfma_i32_16x16x64_i8 v[26:29], v[78:81], v[206:209], v[26:29]
	v_mfma_i32_16x16x64_i8 v[14:17], v[66:69], v[214:217], v[14:17]
	v_mfma_i32_16x16x64_i8 v[10:13], v[78:81], v[214:217], v[10:13]
	s_setprio 0
	s_setprio 1
	v_mfma_i32_16x16x64_i8 v[54:57], v[146:149], v[162:165], v[54:57]
	v_mfma_i32_16x16x64_i8 v[50:53], v[154:157], v[162:165], v[50:53]
	v_mfma_i32_16x16x64_i8 v[38:41], v[146:149], v[184:187], v[38:41]
	v_mfma_i32_16x16x64_i8 v[34:37], v[154:157], v[184:187], v[34:37]
	v_mfma_i32_16x16x64_i8 v[22:25], v[146:149], v[202:205], v[22:25]
	v_mfma_i32_16x16x64_i8 v[18:21], v[154:157], v[202:205], v[18:21]
	v_mfma_i32_16x16x64_i8 v[6:9], v[146:149], v[210:213], v[6:9]
	v_mfma_i32_16x16x64_i8 v[2:5], v[154:157], v[210:213], v[2:5]
	v_mfma_i32_16x16x64_i8 v[54:57], v[150:153], v[178:181], v[54:57]
	v_mfma_i32_16x16x64_i8 v[50:53], v[158:161], v[178:181], v[50:53]
	v_mfma_i32_16x16x64_i8 v[38:41], v[150:153], v[198:201], v[38:41]
	v_mfma_i32_16x16x64_i8 v[34:37], v[158:161], v[198:201], v[34:37]
	v_mfma_i32_16x16x64_i8 v[22:25], v[150:153], v[206:209], v[22:25]
	v_mfma_i32_16x16x64_i8 v[18:21], v[158:161], v[206:209], v[18:21]
	v_mfma_i32_16x16x64_i8 v[6:9], v[150:153], v[214:217], v[6:9]
	v_mfma_i32_16x16x64_i8 v[2:5], v[158:161], v[214:217], v[2:5]
	s_setprio 0
	s_barrier
; #define PG8_STAGE(bufoff, gbase, voff) do { _Pragma("unroll") for (int _i = 0; _i < 2; ++_i) \
;         __builtin_amdgcn_global_load_lds((const unsigned*)((const char*)(gbase) + (voff)[_i]), (PG8_LAS unsigned*)(lds + (bufoff) + ldsw + _i * 8192), 16, 0, 0); } while (0)
; #define PG8_LDA(dst, b, h) do { _Pragma("unroll") for (int m = 0; m < 4; ++m) _Pragma("unroll") for (int k = 0; k < 2; ++k) dst[m][k] = *(const PG8_LAS bf16x8*)(lds + PG8_SA(b, h) + aoff + m * 2048 + k * 1024); } while (0)
; #define PG8_LDB(dst, b, h) do { _Pragma("unroll") for (int n = 0; n < 2; ++n) _Pragma("unroll") for (int k = 0; k < 2; ++k) dst[n][k] = *(const PG8_LAS bf16x8*)(lds + PG8_SB(b, h) + boff + n * 2048 + k * 1024); } while (0)
; #define PG8_MMA(ai, bj, At, Bt) do { __builtin_amdgcn_s_setprio(1); _Pragma("unroll") for (int m = 0; m < 4; ++m) _Pragma("unroll") for (int n = 0; n < 2; ++n) _Pragma("unroll") for (int k = 0; k < 2; ++k) \
;         acc[ai][bj][m][n] = mma_<I8>(Bt[n][k], At[m][k], acc[ai][bj][m][n]); __builtin_amdgcn_s_setprio(0); } while (0)
; #define PG8_WAIT_V(n) asm volatile("s_waitcnt vmcnt(" #n ")" ::: "memory")
; #define PG8_WAIT_L(n) asm volatile("s_waitcnt lgkmcnt(" #n ")" ::: "memory")
; #define PG8_BAR __builtin_amdgcn_s_barrier()
; #define PG8_SCHED __builtin_amdgcn_sched_barrier(0)
; template <class Epi, class Sched, bool ALIGN_EPI = false, bool SP2 = false, bool I8 = false>
; __device__ __forceinline__ void gemm_phase(PG8_LAS unsigned char* lds, const Gemm g, const Sched& S, const Epi& E) {
;     ...
;             PG8_LDB(B0, 1, 0); PG8_LDB(B1, 1, 1); PG8_SCHED; PG8_LDA(At, 1, 0); PG8_STAGE(PG8_SA(0, 1), a2 + hstepA, voffA);
;             PG8_WAIT_V(8); PG8_WAIT_L(0); PG8_BAR; PG8_MMA(0, 0, At, B0); PG8_MMA(0, 1, At, B1); PG8_BAR; PG8_SCHED;
;             PG8_LDA(At, 1, 1); PG8_STAGE(PG8_SB(1, 0), b3, voffB); PG8_STAGE(PG8_SB(1, 1), b3 + hstepB, voffB); PG8_STAGE(PG8_SA(1, 0), a3, voffA);
;             PG8_WAIT_V(8); PG8_WAIT_L(0); PG8_BAR; PG8_MMA(1, 0, At, B0); PG8_MMA(1, 1, At, B1); PG8_BAR; PG8_SCHED;
	s_add_i32 s54, 0, 0x18000
	s_add_i32 s55, 0, 0x1c000
	v_add_u32_e32 v78, s54, v1
	v_add_u32_e32 v158, s55, v1
	ds_read_b128 v[58:61], v78
	ds_read_b128 v[66:69], v78 offset:1024
	ds_read_b128 v[74:77], v78 offset:2048
	ds_read_b128 v[78:81], v78 offset:3072
	ds_read_b128 v[146:149], v158
	ds_read_b128 v[150:153], v158 offset:1024
	ds_read_b128 v[154:157], v158 offset:2048
	ds_read_b128 v[158:161], v158 offset:3072
	s_add_u32 s30, s30, 0x80000
	s_addc_u32 s31, s31, 0
	s_mov_b32 m0, s40
	ds_read_b128 v[162:165], v193 offset:32768
	ds_read_b128 v[178:181], v193 offset:33792
	ds_read_b128 v[184:187], v193 offset:34816
	ds_read_b128 v[198:201], v193 offset:35840
	ds_read_b128 v[202:205], v193 offset:36864
	ds_read_b128 v[206:209], v193 offset:37888
	ds_read_b128 v[210:213], v193 offset:38912
	ds_read_b128 v[214:217], v193 offset:39936
	global_load_lds_dwordx4 v166, s[30:31]
	s_mov_b32 m0, s41
	s_nop 0
	global_load_lds_dwordx4 v168, s[30:31]
	s_waitcnt vmcnt(8) lgkmcnt(0)
	s_barrier
	s_setprio 1
	s_waitcnt lgkmcnt(0)
	v_mfma_i32_16x16x64_i8 v[142:145], v[58:61], v[162:165], v[142:145]
	v_mfma_i32_16x16x64_i8 v[138:141], v[74:77], v[162:165], v[138:141]
	v_mfma_i32_16x16x64_i8 v[126:129], v[58:61], v[184:187], v[126:129]
	v_mfma_i32_16x16x64_i8 v[122:125], v[74:77], v[184:187], v[122:125]
	v_mfma_i32_16x16x64_i8 v[110:113], v[58:61], v[202:205], v[110:113]
	v_mfma_i32_16x16x64_i8 v[106:109], v[74:77], v[202:205], v[106:109]
	v_mfma_i32_16x16x64_i8 v[94:97], v[58:61], v[210:213], v[94:97]
	v_mfma_i32_16x16x64_i8 v[90:93], v[74:77], v[210:213], v[90:93]
	v_mfma_i32_16x16x64_i8 v[142:145], v[66:69], v[178:181], v[142:145]
	v_mfma_i32_16x16x64_i8 v[138:141], v[78:81], v[178:181], v[138:141]
	v_mfma_i32_16x16x64_i8 v[126:129], v[66:69], v[198:201], v[126:129]
	v_mfma_i32_16x16x64_i8 v[122:125], v[78:81], v[198:201], v[122:125]
	v_mfma_i32_16x16x64_i8 v[110:113], v[66:69], v[206:209], v[110:113]
	v_mfma_i32_16x16x64_i8 v[106:109], v[78:81], v[206:209], v[106:109]
	v_mfma_i32_16x16x64_i8 v[94:97], v[66:69], v[214:217], v[94:97]
	v_mfma_i32_16x16x64_i8 v[90:93], v[78:81], v[214:217], v[90:93]
	s_setprio 0
	s_setprio 1
	v_mfma_i32_16x16x64_i8 v[134:137], v[146:149], v[162:165], v[134:137]
	v_mfma_i32_16x16x64_i8 v[130:133], v[154:157], v[162:165], v[130:133]
	v_mfma_i32_16x16x64_i8 v[118:121], v[146:149], v[184:187], v[118:121]
	v_mfma_i32_16x16x64_i8 v[114:117], v[154:157], v[184:187], v[114:117]
	v_mfma_i32_16x16x64_i8 v[102:105], v[146:149], v[202:205], v[102:105]
	v_mfma_i32_16x16x64_i8 v[98:101], v[154:157], v[202:205], v[98:101]
	v_mfma_i32_16x16x64_i8 v[86:89], v[146:149], v[210:213], v[86:89]
	v_mfma_i32_16x16x64_i8 v[82:85], v[154:157], v[210:213], v[82:85]
	v_mfma_i32_16x16x64_i8 v[134:137], v[150:153], v[178:181], v[134:137]
	v_mfma_i32_16x16x64_i8 v[130:133], v[158:161], v[178:181], v[130:133]
	v_mfma_i32_16x16x64_i8 v[118:121], v[150:153], v[198:201], v[118:121]
	v_mfma_i32_16x16x64_i8 v[114:117], v[158:161], v[198:201], v[114:117]
	v_mfma_i32_16x16x64_i8 v[102:105], v[150:153], v[206:209], v[102:105]
	v_mfma_i32_16x16x64_i8 v[98:101], v[158:161], v[206:209], v[98:101]
	v_mfma_i32_16x16x64_i8 v[86:89], v[150:153], v[214:217], v[86:89]
	v_mfma_i32_16x16x64_i8 v[82:85], v[158:161], v[214:217], v[82:85]
	s_setprio 0
	s_barrier
	s_add_i32 s30, s54, s38
	s_add_i32 m0, s30, 0xffffff80
	ds_read_b128 v[162:165], v193 offset:49152
	ds_read_b128 v[178:181], v193 offset:50176
	ds_read_b128 v[184:187], v193 offset:51200
	ds_read_b128 v[198:201], v193 offset:52224
	ds_read_b128 v[202:205], v193 offset:53248
	ds_read_b128 v[206:209], v193 offset:54272
	ds_read_b128 v[210:213], v193 offset:55296
	ds_read_b128 v[214:217], v193 offset:56320
	global_load_lds_dwordx4 v166, s[98:99] offset:128
	s_add_i32 m0, s30, 0x1f80
	s_add_u32 s28, s28, 0x80080
	s_addc_u32 s29, s29, 0
	s_add_i32 s30, s55, s38
	global_load_lds_dwordx4 v168, s[98:99] offset:128
	s_mov_b32 m0, s30
	s_nop 0
	global_load_lds_dwordx4 v166, s[28:29]
	s_add_i32 m0, s30, 0x2000
	s_nop 0
	global_load_lds_dwordx4 v168, s[28:29]
	s_add_i32 m0, s43, 0xffffff80
	s_nop 0
	global_load_lds_dwordx4 v166, s[100:101] offset:128
	s_add_i32 m0, s44, 0xffffff80
	s_nop 0
	global_load_lds_dwordx4 v168, s[100:101] offset:128
	s_waitcnt vmcnt(8) lgkmcnt(0)
	s_barrier
	s_setprio 1
	s_waitcnt lgkmcnt(0)
	v_mfma_i32_16x16x64_i8 v[70:73], v[58:61], v[162:165], v[70:73]
	v_mfma_i32_16x16x64_i8 v[62:65], v[74:77], v[162:165], v[62:65]
	v_mfma_i32_16x16x64_i8 v[46:49], v[58:61], v[184:187], v[46:49]
	v_mfma_i32_16x16x64_i8 v[42:45], v[74:77], v[184:187], v[42:45]
	v_mfma_i32_16x16x64_i8 v[30:33], v[58:61], v[202:205], v[30:33]
	v_mfma_i32_16x16x64_i8 v[26:29], v[74:77], v[202:205], v[26:29]
	v_mfma_i32_16x16x64_i8 v[14:17], v[58:61], v[210:213], v[14:17]
	v_mfma_i32_16x16x64_i8 v[10:13], v[74:77], v[210:213], v[10:13]
	v_mfma_i32_16x16x64_i8 v[70:73], v[66:69], v[178:181], v[70:73]
	v_mfma_i32_16x16x64_i8 v[62:65], v[78:81], v[178:181], v[62:65]
	v_mfma_i32_16x16x64_i8 v[46:49], v[66:69], v[198:201], v[46:49]
	v_mfma_i32_16x16x64_i8 v[42:45], v[78:81], v[198:201], v[42:45]
	v_mfma_i32_16x16x64_i8 v[30:33], v[66:69], v[206:209], v[30:33]
	v_mfma_i32_16x16x64_i8 v[26:29], v[78:81], v[206:209], v[26:29]
	v_mfma_i32_16x16x64_i8 v[14:17], v[66:69], v[214:217], v[14:17]
	v_mfma_i32_16x16x64_i8 v[10:13], v[78:81], v[214:217], v[10:13]
	s_setprio 0
	s_setprio 1
	v_mfma_i32_16x16x64_i8 v[54:57], v[146:149], v[162:165], v[54:57]
	v_mfma_i32_16x16x64_i8 v[50:53], v[154:157], v[162:165], v[50:53]
	v_mfma_i32_16x16x64_i8 v[38:41], v[146:149], v[184:187], v[38:41]
	v_mfma_i32_16x16x64_i8 v[34:37], v[154:157], v[184:187], v[34:37]
	v_mfma_i32_16x16x64_i8 v[22:25], v[146:149], v[202:205], v[22:25]
	v_mfma_i32_16x16x64_i8 v[18:21], v[154:157], v[202:205], v[18:21]
	v_mfma_i32_16x16x64_i8 v[6:9], v[146:149], v[210:213], v[6:9]
	v_mfma_i32_16x16x64_i8 v[2:5], v[154:157], v[210:213], v[2:5]
	v_mfma_i32_16x16x64_i8 v[54:57], v[150:153], v[178:181], v[54:57]
	v_mfma_i32_16x16x64_i8 v[50:53], v[158:161], v[178:181], v[50:53]
	v_mfma_i32_16x16x64_i8 v[38:41], v[150:153], v[198:201], v[38:41]
	v_mfma_i32_16x16x64_i8 v[34:37], v[158:161], v[198:201], v[34:37]
	v_mfma_i32_16x16x64_i8 v[22:25], v[150:153], v[206:209], v[22:25]
	v_mfma_i32_16x16x64_i8 v[18:21], v[158:161], v[206:209], v[18:21]
	v_mfma_i32_16x16x64_i8 v[6:9], v[150:153], v[214:217], v[6:9]
	v_mfma_i32_16x16x64_i8 v[2:5], v[158:161], v[214:217], v[2:5]
	s_setprio 0
	s_barrier
	s_add_i32 s53, s53, 2
	s_add_u32 s26, s26, 0x100
	s_addc_u32 s27, s27, 0
	s_add_u32 s51, s51, 0x100
	s_addc_u32 s52, s52, 0
	s_cmp_gt_u32 s53, 29
	s_cbranch_scc0 .LBB0_2322
	s_and_b64 vcc, exec, s[16:17]
	s_cbranch_vccz .LBB0_2325
	s_barrier
